# hand-scheduled 192x128 GEMM mainloop (1 barrier/k-tile, pipelined LDS frag reads, saddr LDS-DMA) in 8 phases, k-rotation removed for L2 locality
# speedup vs baseline: 1.0304x; 1.0304x over previous
.LBB0_150:
	s_ashr_i32 s4, s35, 31
	s_lshr_b32 s4, s4, 26
	s_add_i32 s4, s35, s4
	s_ashr_i32 s6, s4, 6
	s_and_b32 s4, s4, 0x3ffffc0
	s_sub_i32 s4, s35, s4
	s_mulk_i32 s4, 0xc0
	v_add_u32_e32 v2, s4, v1
	s_lshr_b32 s7, s4, 6
	s_lshl_b32 s5, s6, 7
	v_ashrrev_i32_e32 v3, 31, v2
	s_add_i32 s7, s7, s6
	v_lshlrev_b64 v[2:3], 11, v[2:3]
	v_or_b32_e32 v4, s5, v1
	s_lshl_b32 s6, s7, 6
	s_lshl_b32 s7, s7, 7
	v_ashrrev_i32_e32 v5, 31, v4
	v_lshl_add_u64 v[104:105], v[100:101], 0, v[2:3]
	s_and_b32 s14, s7, 0x780
	v_readfirstlane_b32 s7, v112
	v_lshlrev_b64 v[4:5], 11, v[4:5]
	v_lshl_add_u64 v[2:3], v[104:105], 0, s[14:15]
	s_mov_b32 m0, s7
	v_readfirstlane_b32 s7, v124
	v_lshl_add_u64 v[106:107], v[102:103], 0, v[4:5]
	s_waitcnt vmcnt(0)
	s_barrier
	s_load_dwordx2 s[66:67], s[0:1], 0x90
	s_load_dwordx2 s[68:69], s[0:1], 0xc0
	v_and_b32_e32 v201, 0x3ff, v0
	v_readfirstlane_b32 s76, v0
	v_and_b32_e32 v200, 31, v201
	v_bfe_u32 v214, v201, 1, 3
	v_bfe_u32 v213, v201, 5, 1
	v_xor_b32_e32 v214, v214, v213
	v_lshlrev_b32_e32 v214, 4, v214
	s_and_b32 s76, s76, 0x3ff
	s_lshr_b32 s79, s76, 6
	s_lshl_b32 s76, s76, 4
	s_lshr_b32 s80, s79, 1
	s_and_b32 s79, s79, 1
	s_mul_i32 s80, s80, 0x3000
	s_lshl_b32 s79, s79, 13
	s_add_u32 s79, s79, 0xc000
	v_lshlrev_b32_e32 v200, 7, v200
	v_or_b32_e32 v200, v200, v214
	v_add_u32_e32 v215, s80, v200
	v_add_u32_e32 v211, s79, v200
	v_xor_b32_e32 v214, 0x20, v215
	v_xor_b32_e32 v210, 0x20, v211
	v_xor_b32_e32 v213, 0x40, v215
	v_xor_b32_e32 v209, 0x40, v211
	v_xor_b32_e32 v212, 0x60, v215
	v_xor_b32_e32 v208, 0x60, v211
	v_bfe_u32 v200, v201, 4, 3
	v_and_b32_e32 v206, 7, v201
	v_xor_b32_e32 v200, v200, v206
	v_lshlrev_b32_e32 v200, 4, v200
	v_lshrrev_b32_e32 v206, 3, v201
	v_lshl_or_b32 v207, v206, 11, v200
	v_add_u32_e32 v206, 0x10000, v207
	v_add_u32_e32 v205, 0x20000, v207
	v_add_u32_e32 v204, 0x30000, v207
	v_add_u32_e32 v203, 0x40000, v207
	v_add_u32_e32 v202, 0x50000, v207
	s_lshr_b32 s79, s35, 6
	s_and_b32 s80, s35, 63
	s_mov_b32 s75, 0
	s_mul_i32 s80, s80, 0x60000
	s_lshl_b32 s79, s79, 18
	s_waitcnt lgkmcnt(0)
	s_add_u32 s66, s66, s80
	s_addc_u32 s67, s67, 0
	s_add_u32 s68, s68, s79
	s_addc_u32 s69, s69, 0
	s_add_u32 s79, s75, 0
	s_and_b32 s79, s79, 15
	s_lshl_b32 s79, s79, 7
	s_add_u32 s70, s66, s79
	s_addc_u32 s71, s67, 0
	s_add_u32 s72, s68, s79
	s_addc_u32 s73, s69, 0
	s_add_u32 s77, s76, 0x0
	s_add_u32 s78, s76, 0xc000
	s_add_u32 m0, s77, 0x0
	s_nop 0
	global_load_lds_dwordx4 v207, s[70:71]
	s_add_u32 m0, s77, 0x1000
	s_nop 0
	global_load_lds_dwordx4 v206, s[70:71]
	s_add_u32 m0, s77, 0x2000
	s_nop 0
	global_load_lds_dwordx4 v205, s[70:71]
	s_add_u32 m0, s77, 0x3000
	s_nop 0
	global_load_lds_dwordx4 v204, s[70:71]
	s_add_u32 m0, s77, 0x4000
	s_nop 0
	global_load_lds_dwordx4 v203, s[70:71]
	s_add_u32 m0, s77, 0x5000
	s_nop 0
	global_load_lds_dwordx4 v202, s[70:71]
	s_add_u32 m0, s78, 0x0
	s_nop 0
	global_load_lds_dwordx4 v207, s[72:73]
	s_add_u32 m0, s78, 0x1000
	s_nop 0
	global_load_lds_dwordx4 v206, s[72:73]
	s_add_u32 m0, s78, 0x2000
	s_nop 0
	global_load_lds_dwordx4 v205, s[72:73]
	s_add_u32 m0, s78, 0x3000
	s_nop 0
	global_load_lds_dwordx4 v204, s[72:73]
	s_add_u32 s79, s75, 1
	s_and_b32 s79, s79, 15
	s_lshl_b32 s79, s79, 7
	s_add_u32 s70, s66, s79
	s_addc_u32 s71, s67, 0
	s_add_u32 s72, s68, s79
	s_addc_u32 s73, s69, 0
	s_add_u32 s77, s76, 0x6000
	s_add_u32 s78, s76, 0x10000
	s_add_u32 m0, s77, 0x0
	s_nop 0
	global_load_lds_dwordx4 v207, s[70:71]
	s_add_u32 m0, s77, 0x1000
	s_nop 0
	global_load_lds_dwordx4 v206, s[70:71]
	s_add_u32 m0, s77, 0x2000
	s_nop 0
	global_load_lds_dwordx4 v205, s[70:71]
	s_add_u32 m0, s77, 0x3000
	s_nop 0
	global_load_lds_dwordx4 v204, s[70:71]
	s_add_u32 m0, s77, 0x4000
	s_nop 0
	global_load_lds_dwordx4 v203, s[70:71]
	s_add_u32 m0, s77, 0x5000
	s_nop 0
	global_load_lds_dwordx4 v202, s[70:71]
	s_add_u32 m0, s78, 0x0
	s_nop 0
	global_load_lds_dwordx4 v207, s[72:73]
	s_add_u32 m0, s78, 0x1000
	s_nop 0
	global_load_lds_dwordx4 v206, s[72:73]
	s_add_u32 m0, s78, 0x2000
	s_nop 0
	global_load_lds_dwordx4 v205, s[72:73]
	s_add_u32 m0, s78, 0x3000
	s_nop 0
	global_load_lds_dwordx4 v204, s[72:73]
	v_mov_b32_e32 v2, 0
	v_mov_b32_e32 v3, 0
	v_mov_b32_e32 v4, 0
	v_mov_b32_e32 v5, 0
	v_mov_b32_e32 v6, 0
	v_mov_b32_e32 v7, 0
	v_mov_b32_e32 v8, 0
	v_mov_b32_e32 v9, 0
	v_mov_b32_e32 v10, 0
	v_mov_b32_e32 v11, 0
	v_mov_b32_e32 v12, 0
	v_mov_b32_e32 v13, 0
	v_mov_b32_e32 v14, 0
	v_mov_b32_e32 v15, 0
	v_mov_b32_e32 v16, 0
	v_mov_b32_e32 v17, 0
	v_mov_b32_e32 v18, 0
	v_mov_b32_e32 v19, 0
	v_mov_b32_e32 v20, 0
	v_mov_b32_e32 v21, 0
	v_mov_b32_e32 v22, 0
	v_mov_b32_e32 v23, 0
	v_mov_b32_e32 v24, 0
	v_mov_b32_e32 v25, 0
	v_mov_b32_e32 v26, 0
	v_mov_b32_e32 v27, 0
	v_mov_b32_e32 v28, 0
	v_mov_b32_e32 v29, 0
	v_mov_b32_e32 v30, 0
	v_mov_b32_e32 v31, 0
	v_mov_b32_e32 v32, 0
	v_mov_b32_e32 v33, 0
	v_mov_b32_e32 v34, 0
	v_mov_b32_e32 v35, 0
	v_mov_b32_e32 v36, 0
	v_mov_b32_e32 v37, 0
	v_mov_b32_e32 v38, 0
	v_mov_b32_e32 v39, 0
	v_mov_b32_e32 v40, 0
	v_mov_b32_e32 v41, 0
	v_mov_b32_e32 v42, 0
	v_mov_b32_e32 v43, 0
	v_mov_b32_e32 v44, 0
	v_mov_b32_e32 v45, 0
	v_mov_b32_e32 v46, 0
	v_mov_b32_e32 v47, 0
	v_mov_b32_e32 v48, 0
	v_mov_b32_e32 v49, 0
	v_mov_b32_e32 v50, 0
	v_mov_b32_e32 v51, 0
	v_mov_b32_e32 v52, 0
	v_mov_b32_e32 v53, 0
	v_mov_b32_e32 v54, 0
	v_mov_b32_e32 v55, 0
	v_mov_b32_e32 v56, 0
	v_mov_b32_e32 v57, 0
	v_mov_b32_e32 v58, 0
	v_mov_b32_e32 v59, 0
	v_mov_b32_e32 v60, 0
	v_mov_b32_e32 v61, 0
	v_mov_b32_e32 v62, 0
	v_mov_b32_e32 v63, 0
	v_mov_b32_e32 v64, 0
	v_mov_b32_e32 v65, 0
	v_mov_b32_e32 v66, 0
	v_mov_b32_e32 v67, 0
	v_mov_b32_e32 v68, 0
	v_mov_b32_e32 v69, 0
	v_mov_b32_e32 v70, 0
	v_mov_b32_e32 v71, 0
	v_mov_b32_e32 v72, 0
	v_mov_b32_e32 v73, 0
	v_mov_b32_e32 v74, 0
	v_mov_b32_e32 v75, 0
	v_mov_b32_e32 v76, 0
	v_mov_b32_e32 v77, 0
	v_mov_b32_e32 v78, 0
	v_mov_b32_e32 v79, 0
	v_mov_b32_e32 v80, 0
	v_mov_b32_e32 v81, 0
	v_mov_b32_e32 v82, 0
	v_mov_b32_e32 v83, 0
	v_mov_b32_e32 v84, 0
	v_mov_b32_e32 v85, 0
	v_mov_b32_e32 v86, 0
	v_mov_b32_e32 v87, 0
	v_mov_b32_e32 v88, 0
	v_mov_b32_e32 v89, 0
	v_mov_b32_e32 v90, 0
	v_mov_b32_e32 v91, 0
	v_mov_b32_e32 v92, 0
	v_mov_b32_e32 v93, 0
	v_mov_b32_e32 v94, 0
	v_mov_b32_e32 v95, 0
	v_mov_b32_e32 v96, 0
	v_mov_b32_e32 v97, 0
	s_waitcnt vmcnt(10)
	s_barrier
	ds_read_b128 v[240:243], v211 offset:0
	ds_read_b128 v[252:255], v215 offset:0
	ds_read_b128 v[236:239], v211 offset:4096
	ds_read_b128 v[248:251], v215 offset:4096
	ds_read_b128 v[244:247], v215 offset:8192
	s_mov_b32 s74, 0
.Lgm_ph2_loop:
	s_waitcnt lgkmcnt(1)
	v_mfma_f32_32x32x16_bf16 v[82:97], v[240:243], v[252:255], v[82:97]
	ds_read_b128 v[220:223], v210 offset:0
	v_mfma_f32_32x32x16_bf16 v[66:81], v[236:239], v[252:255], v[66:81]
	ds_read_b128 v[232:235], v214 offset:0
	v_mfma_f32_32x32x16_bf16 v[50:65], v[240:243], v[248:251], v[50:65]
	ds_read_b128 v[216:219], v210 offset:4096
	v_mfma_f32_32x32x16_bf16 v[34:49], v[236:239], v[248:251], v[34:49]
	ds_read_b128 v[228:231], v214 offset:4096
	s_waitcnt lgkmcnt(4)
	v_mfma_f32_32x32x16_bf16 v[18:33], v[240:243], v[244:247], v[18:33]
	ds_read_b128 v[224:227], v214 offset:8192
	v_mfma_f32_32x32x16_bf16 v[2:17], v[236:239], v[244:247], v[2:17]
	s_waitcnt lgkmcnt(1)
	v_mfma_f32_32x32x16_bf16 v[82:97], v[220:223], v[232:235], v[82:97]
	ds_read_b128 v[240:243], v209 offset:0
	v_mfma_f32_32x32x16_bf16 v[66:81], v[216:219], v[232:235], v[66:81]
	ds_read_b128 v[252:255], v213 offset:0
	v_mfma_f32_32x32x16_bf16 v[50:65], v[220:223], v[228:231], v[50:65]
	ds_read_b128 v[236:239], v209 offset:4096
	v_mfma_f32_32x32x16_bf16 v[34:49], v[216:219], v[228:231], v[34:49]
	ds_read_b128 v[248:251], v213 offset:4096
	s_waitcnt lgkmcnt(4)
	v_mfma_f32_32x32x16_bf16 v[18:33], v[220:223], v[224:227], v[18:33]
	ds_read_b128 v[244:247], v213 offset:8192
	v_mfma_f32_32x32x16_bf16 v[2:17], v[216:219], v[224:227], v[2:17]
	s_waitcnt lgkmcnt(1)
	v_mfma_f32_32x32x16_bf16 v[82:97], v[240:243], v[252:255], v[82:97]
	ds_read_b128 v[220:223], v208 offset:0
	s_add_u32 s79, s75, s74
	s_add_u32 s79, s79, 2
	s_and_b32 s79, s79, 15
	v_mfma_f32_32x32x16_bf16 v[66:81], v[236:239], v[252:255], v[66:81]
	ds_read_b128 v[232:235], v212 offset:0
	s_lshl_b32 s79, s79, 7
	s_add_u32 s70, s66, s79
	v_mfma_f32_32x32x16_bf16 v[50:65], v[240:243], v[248:251], v[50:65]
	ds_read_b128 v[216:219], v208 offset:4096
	s_addc_u32 s71, s67, 0
	s_add_u32 s72, s68, s79
	v_mfma_f32_32x32x16_bf16 v[34:49], v[236:239], v[248:251], v[34:49]
	ds_read_b128 v[228:231], v212 offset:4096
	s_addc_u32 s73, s69, 0
	s_add_u32 s77, s76, 0x0
	s_add_u32 s78, s76, 0xc000
	s_waitcnt lgkmcnt(4)
	v_mfma_f32_32x32x16_bf16 v[18:33], v[240:243], v[244:247], v[18:33]
	ds_read_b128 v[224:227], v212 offset:8192
	v_mfma_f32_32x32x16_bf16 v[2:17], v[236:239], v[244:247], v[2:17]
	s_waitcnt vmcnt(0) lgkmcnt(0)
	s_barrier
	v_mfma_f32_32x32x16_bf16 v[82:97], v[220:223], v[232:235], v[82:97]
	s_add_u32 m0, s77, 0x0
	ds_read_b128 v[240:243], v211 offset:16384
	global_load_lds_dwordx4 v207, s[70:71]
	s_add_u32 m0, s77, 0x1000
	s_nop 0
	global_load_lds_dwordx4 v206, s[70:71]
	v_mfma_f32_32x32x16_bf16 v[66:81], v[216:219], v[232:235], v[66:81]
	s_add_u32 m0, s77, 0x2000
	ds_read_b128 v[252:255], v215 offset:24576
	global_load_lds_dwordx4 v205, s[70:71]
	s_add_u32 m0, s77, 0x3000
	s_nop 0
	global_load_lds_dwordx4 v204, s[70:71]
	v_mfma_f32_32x32x16_bf16 v[50:65], v[220:223], v[228:231], v[50:65]
	s_add_u32 m0, s77, 0x4000
	ds_read_b128 v[236:239], v211 offset:20480
	global_load_lds_dwordx4 v203, s[70:71]
	s_add_u32 m0, s77, 0x5000
	s_nop 0
	global_load_lds_dwordx4 v202, s[70:71]
	v_mfma_f32_32x32x16_bf16 v[34:49], v[216:219], v[228:231], v[34:49]
	s_add_u32 m0, s78, 0x0
	ds_read_b128 v[248:251], v215 offset:28672
	global_load_lds_dwordx4 v207, s[72:73]
	s_add_u32 m0, s78, 0x1000
	s_nop 0
	global_load_lds_dwordx4 v206, s[72:73]
	v_mfma_f32_32x32x16_bf16 v[18:33], v[220:223], v[224:227], v[18:33]
	s_add_u32 m0, s78, 0x2000
	ds_read_b128 v[244:247], v215 offset:32768
	global_load_lds_dwordx4 v205, s[72:73]
	s_add_u32 m0, s78, 0x3000
	s_nop 0
	global_load_lds_dwordx4 v204, s[72:73]
	v_mfma_f32_32x32x16_bf16 v[2:17], v[216:219], v[224:227], v[2:17]
	s_waitcnt lgkmcnt(1)
	v_mfma_f32_32x32x16_bf16 v[82:97], v[240:243], v[252:255], v[82:97]
	ds_read_b128 v[220:223], v210 offset:16384
	v_mfma_f32_32x32x16_bf16 v[66:81], v[236:239], v[252:255], v[66:81]
	ds_read_b128 v[232:235], v214 offset:24576
	v_mfma_f32_32x32x16_bf16 v[50:65], v[240:243], v[248:251], v[50:65]
	ds_read_b128 v[216:219], v210 offset:20480
	v_mfma_f32_32x32x16_bf16 v[34:49], v[236:239], v[248:251], v[34:49]
	ds_read_b128 v[228:231], v214 offset:28672
	s_waitcnt lgkmcnt(4)
	v_mfma_f32_32x32x16_bf16 v[18:33], v[240:243], v[244:247], v[18:33]
	ds_read_b128 v[224:227], v214 offset:32768
	v_mfma_f32_32x32x16_bf16 v[2:17], v[236:239], v[244:247], v[2:17]
	s_waitcnt lgkmcnt(1)
	v_mfma_f32_32x32x16_bf16 v[82:97], v[220:223], v[232:235], v[82:97]
	ds_read_b128 v[240:243], v209 offset:16384
	v_mfma_f32_32x32x16_bf16 v[66:81], v[216:219], v[232:235], v[66:81]
	ds_read_b128 v[252:255], v213 offset:24576
	v_mfma_f32_32x32x16_bf16 v[50:65], v[220:223], v[228:231], v[50:65]
	ds_read_b128 v[236:239], v209 offset:20480
	v_mfma_f32_32x32x16_bf16 v[34:49], v[216:219], v[228:231], v[34:49]
	ds_read_b128 v[248:251], v213 offset:28672
	s_waitcnt lgkmcnt(4)
	v_mfma_f32_32x32x16_bf16 v[18:33], v[220:223], v[224:227], v[18:33]
	ds_read_b128 v[244:247], v213 offset:32768
	v_mfma_f32_32x32x16_bf16 v[2:17], v[216:219], v[224:227], v[2:17]
	s_waitcnt lgkmcnt(1)
	v_mfma_f32_32x32x16_bf16 v[82:97], v[240:243], v[252:255], v[82:97]
	ds_read_b128 v[220:223], v208 offset:16384
	s_add_u32 s79, s75, s74
	s_add_u32 s79, s79, 3
	s_and_b32 s79, s79, 15
	v_mfma_f32_32x32x16_bf16 v[66:81], v[236:239], v[252:255], v[66:81]
	ds_read_b128 v[232:235], v212 offset:24576
	s_lshl_b32 s79, s79, 7
	s_add_u32 s70, s66, s79
	v_mfma_f32_32x32x16_bf16 v[50:65], v[240:243], v[248:251], v[50:65]
	ds_read_b128 v[216:219], v208 offset:20480
	s_addc_u32 s71, s67, 0
	s_add_u32 s72, s68, s79
	v_mfma_f32_32x32x16_bf16 v[34:49], v[236:239], v[248:251], v[34:49]
	ds_read_b128 v[228:231], v212 offset:28672
	s_addc_u32 s73, s69, 0
	s_add_u32 s77, s76, 0x6000
	s_add_u32 s78, s76, 0x10000
	s_waitcnt lgkmcnt(4)
	v_mfma_f32_32x32x16_bf16 v[18:33], v[240:243], v[244:247], v[18:33]
	ds_read_b128 v[224:227], v212 offset:32768
	v_mfma_f32_32x32x16_bf16 v[2:17], v[236:239], v[244:247], v[2:17]
	s_waitcnt vmcnt(0) lgkmcnt(0)
	s_barrier
	v_mfma_f32_32x32x16_bf16 v[82:97], v[220:223], v[232:235], v[82:97]
	s_add_u32 m0, s77, 0x0
	ds_read_b128 v[240:243], v211 offset:0
	global_load_lds_dwordx4 v207, s[70:71]
	s_add_u32 m0, s77, 0x1000
	s_nop 0
	global_load_lds_dwordx4 v206, s[70:71]
	v_mfma_f32_32x32x16_bf16 v[66:81], v[216:219], v[232:235], v[66:81]
	s_add_u32 m0, s77, 0x2000
	ds_read_b128 v[252:255], v215 offset:0
	global_load_lds_dwordx4 v205, s[70:71]
	s_add_u32 m0, s77, 0x3000
	s_nop 0
	global_load_lds_dwordx4 v204, s[70:71]
	v_mfma_f32_32x32x16_bf16 v[50:65], v[220:223], v[228:231], v[50:65]
	s_add_u32 m0, s77, 0x4000
	ds_read_b128 v[236:239], v211 offset:4096
	global_load_lds_dwordx4 v203, s[70:71]
	s_add_u32 m0, s77, 0x5000
	s_nop 0
	global_load_lds_dwordx4 v202, s[70:71]
	v_mfma_f32_32x32x16_bf16 v[34:49], v[216:219], v[228:231], v[34:49]
	s_add_u32 m0, s78, 0x0
	ds_read_b128 v[248:251], v215 offset:4096
	global_load_lds_dwordx4 v207, s[72:73]
	s_add_u32 m0, s78, 0x1000
	s_nop 0
	global_load_lds_dwordx4 v206, s[72:73]
	v_mfma_f32_32x32x16_bf16 v[18:33], v[220:223], v[224:227], v[18:33]
	s_add_u32 m0, s78, 0x2000
	ds_read_b128 v[244:247], v215 offset:8192
	global_load_lds_dwordx4 v205, s[72:73]
	s_add_u32 m0, s78, 0x3000
	s_nop 0
	global_load_lds_dwordx4 v204, s[72:73]
	v_mfma_f32_32x32x16_bf16 v[2:17], v[216:219], v[224:227], v[2:17]
	s_add_u32 s74, s74, 2
	s_cmp_lt_u32 s74, 14
	s_cbranch_scc1 .Lgm_ph2_loop
	s_waitcnt lgkmcnt(1)
	v_mfma_f32_32x32x16_bf16 v[82:97], v[240:243], v[252:255], v[82:97]
	ds_read_b128 v[220:223], v210 offset:0
	v_mfma_f32_32x32x16_bf16 v[66:81], v[236:239], v[252:255], v[66:81]
	ds_read_b128 v[232:235], v214 offset:0
	v_mfma_f32_32x32x16_bf16 v[50:65], v[240:243], v[248:251], v[50:65]
	ds_read_b128 v[216:219], v210 offset:4096
	v_mfma_f32_32x32x16_bf16 v[34:49], v[236:239], v[248:251], v[34:49]
	ds_read_b128 v[228:231], v214 offset:4096
	s_waitcnt lgkmcnt(4)
	v_mfma_f32_32x32x16_bf16 v[18:33], v[240:243], v[244:247], v[18:33]
	ds_read_b128 v[224:227], v214 offset:8192
	v_mfma_f32_32x32x16_bf16 v[2:17], v[236:239], v[244:247], v[2:17]
	s_waitcnt lgkmcnt(1)
	v_mfma_f32_32x32x16_bf16 v[82:97], v[220:223], v[232:235], v[82:97]
	ds_read_b128 v[240:243], v209 offset:0
	v_mfma_f32_32x32x16_bf16 v[66:81], v[216:219], v[232:235], v[66:81]
	ds_read_b128 v[252:255], v213 offset:0
	v_mfma_f32_32x32x16_bf16 v[50:65], v[220:223], v[228:231], v[50:65]
	ds_read_b128 v[236:239], v209 offset:4096
	v_mfma_f32_32x32x16_bf16 v[34:49], v[216:219], v[228:231], v[34:49]
	ds_read_b128 v[248:251], v213 offset:4096
	s_waitcnt lgkmcnt(4)
	v_mfma_f32_32x32x16_bf16 v[18:33], v[220:223], v[224:227], v[18:33]
	ds_read_b128 v[244:247], v213 offset:8192
	v_mfma_f32_32x32x16_bf16 v[2:17], v[216:219], v[224:227], v[2:17]
	s_waitcnt lgkmcnt(1)
	v_mfma_f32_32x32x16_bf16 v[82:97], v[240:243], v[252:255], v[82:97]
	ds_read_b128 v[220:223], v208 offset:0
	v_mfma_f32_32x32x16_bf16 v[66:81], v[236:239], v[252:255], v[66:81]
	ds_read_b128 v[232:235], v212 offset:0
	v_mfma_f32_32x32x16_bf16 v[50:65], v[240:243], v[248:251], v[50:65]
	ds_read_b128 v[216:219], v208 offset:4096
	v_mfma_f32_32x32x16_bf16 v[34:49], v[236:239], v[248:251], v[34:49]
	ds_read_b128 v[228:231], v212 offset:4096
	s_waitcnt lgkmcnt(4)
	v_mfma_f32_32x32x16_bf16 v[18:33], v[240:243], v[244:247], v[18:33]
	ds_read_b128 v[224:227], v212 offset:8192
	v_mfma_f32_32x32x16_bf16 v[2:17], v[236:239], v[244:247], v[2:17]
	s_waitcnt vmcnt(0) lgkmcnt(0)
	s_barrier
	v_mfma_f32_32x32x16_bf16 v[82:97], v[220:223], v[232:235], v[82:97]
	ds_read_b128 v[240:243], v211 offset:16384
	v_mfma_f32_32x32x16_bf16 v[66:81], v[216:219], v[232:235], v[66:81]
	ds_read_b128 v[252:255], v215 offset:24576
	v_mfma_f32_32x32x16_bf16 v[50:65], v[220:223], v[228:231], v[50:65]
	ds_read_b128 v[236:239], v211 offset:20480
	v_mfma_f32_32x32x16_bf16 v[34:49], v[216:219], v[228:231], v[34:49]
	ds_read_b128 v[248:251], v215 offset:28672
	v_mfma_f32_32x32x16_bf16 v[18:33], v[220:223], v[224:227], v[18:33]
	ds_read_b128 v[244:247], v215 offset:32768
	v_mfma_f32_32x32x16_bf16 v[2:17], v[216:219], v[224:227], v[2:17]
	s_waitcnt lgkmcnt(1)
	v_mfma_f32_32x32x16_bf16 v[82:97], v[240:243], v[252:255], v[82:97]
	ds_read_b128 v[220:223], v210 offset:16384
	v_mfma_f32_32x32x16_bf16 v[66:81], v[236:239], v[252:255], v[66:81]
	ds_read_b128 v[232:235], v214 offset:24576
	v_mfma_f32_32x32x16_bf16 v[50:65], v[240:243], v[248:251], v[50:65]
	ds_read_b128 v[216:219], v210 offset:20480
	v_mfma_f32_32x32x16_bf16 v[34:49], v[236:239], v[248:251], v[34:49]
	ds_read_b128 v[228:231], v214 offset:28672
	s_waitcnt lgkmcnt(4)
	v_mfma_f32_32x32x16_bf16 v[18:33], v[240:243], v[244:247], v[18:33]
	ds_read_b128 v[224:227], v214 offset:32768
	v_mfma_f32_32x32x16_bf16 v[2:17], v[236:239], v[244:247], v[2:17]
	s_waitcnt lgkmcnt(1)
	v_mfma_f32_32x32x16_bf16 v[82:97], v[220:223], v[232:235], v[82:97]
	ds_read_b128 v[240:243], v209 offset:16384
	v_mfma_f32_32x32x16_bf16 v[66:81], v[216:219], v[232:235], v[66:81]
	ds_read_b128 v[252:255], v213 offset:24576
	v_mfma_f32_32x32x16_bf16 v[50:65], v[220:223], v[228:231], v[50:65]
	ds_read_b128 v[236:239], v209 offset:20480
	v_mfma_f32_32x32x16_bf16 v[34:49], v[216:219], v[228:231], v[34:49]
	ds_read_b128 v[248:251], v213 offset:28672
	s_waitcnt lgkmcnt(4)
	v_mfma_f32_32x32x16_bf16 v[18:33], v[220:223], v[224:227], v[18:33]
	ds_read_b128 v[244:247], v213 offset:32768
	v_mfma_f32_32x32x16_bf16 v[2:17], v[216:219], v[224:227], v[2:17]
	s_waitcnt lgkmcnt(1)
	v_mfma_f32_32x32x16_bf16 v[82:97], v[240:243], v[252:255], v[82:97]
	ds_read_b128 v[220:223], v208 offset:16384
	v_mfma_f32_32x32x16_bf16 v[66:81], v[236:239], v[252:255], v[66:81]
	ds_read_b128 v[232:235], v212 offset:24576
	v_mfma_f32_32x32x16_bf16 v[50:65], v[240:243], v[248:251], v[50:65]
	ds_read_b128 v[216:219], v208 offset:20480
	v_mfma_f32_32x32x16_bf16 v[34:49], v[236:239], v[248:251], v[34:49]
	ds_read_b128 v[228:231], v212 offset:28672
	s_waitcnt lgkmcnt(4)
	v_mfma_f32_32x32x16_bf16 v[18:33], v[240:243], v[244:247], v[18:33]
	ds_read_b128 v[224:227], v212 offset:32768
	v_mfma_f32_32x32x16_bf16 v[2:17], v[236:239], v[244:247], v[2:17]
	s_waitcnt vmcnt(0) lgkmcnt(0)
	s_barrier
	v_mfma_f32_32x32x16_bf16 v[82:97], v[220:223], v[232:235], v[82:97]
	v_mfma_f32_32x32x16_bf16 v[66:81], v[216:219], v[232:235], v[66:81]
	v_mfma_f32_32x32x16_bf16 v[50:65], v[220:223], v[228:231], v[50:65]
	v_mfma_f32_32x32x16_bf16 v[34:49], v[216:219], v[228:231], v[34:49]
	v_mfma_f32_32x32x16_bf16 v[18:33], v[220:223], v[224:227], v[18:33]
	v_mfma_f32_32x32x16_bf16 v[2:17], v[216:219], v[224:227], v[2:17]
	s_nop 7
	s_nop 7
	v_add_u32_e32 v147, v115, v118
	s_nop 4
	v_add_u32_e32 v98, v117, v121
	s_nop 4
	s_waitcnt lgkmcnt(0)
	v_or_b32_e32 v142, s5, v122
	v_cmp_lt_i32_e64 s[6:7], s3, v142
	v_add_u32_e32 v106, s4, v114
	v_ashrrev_i32_e32 v107, 31, v106
	v_lshlrev_b64 v[110:111], 11, v[106:107]
	v_or_b32_e32 v104, v142, v123
	v_lshl_add_u64 v[108:109], s[10:11], 0, v[110:111]
	s_and_saveexec_b64 s[4:5], s[6:7]
	s_xor_b64 s[4:5], exec, s[4:5]
	s_cbranch_execz .LBB0_154
	v_mul_f32_e32 v98, 0xbfb8aa3b, v82
	v_exp_f32_e32 v144, v98
	v_mul_f32_e32 v98, 0xbfb8aa3b, v83
	v_exp_f32_e32 v145, v98
	s_nop 0
	v_pk_add_f32 v[144:145], v[144:145], 1.0 op_sel_hi:[1,0]
	s_nop 0
	v_div_scale_f32 v98, s[30:31], v145, v145, v83
	v_rcp_f32_e32 v105, v98
	v_div_scale_f32 v107, vcc, v83, v145, v83
	v_fma_f32 v143, -v98, v105, 1.0
	v_fmac_f32_e32 v105, v143, v105
	v_mul_f32_e32 v143, v107, v105
	v_fma_f32 v147, -v98, v143, v107
	v_fmac_f32_e32 v143, v147, v105
	v_fma_f32 v98, -v98, v143, v107
	v_div_scale_f32 v107, s[30:31], v144, v144, v82
	v_rcp_f32_e32 v147, v107
	v_div_fmas_f32 v98, v98, v105, v143
	v_div_fixup_f32 v98, v98, v145, v83
	v_mul_f32_e32 v145, 0xbfb8aa3b, v84
	v_exp_f32_e32 v150, v145
	v_mul_f32_e32 v145, 0xbfb8aa3b, v85
	v_fma_f32 v105, -v107, v147, 1.0
	v_exp_f32_e32 v151, v145
	v_fmac_f32_e32 v147, v105, v147
	v_div_scale_f32 v105, vcc, v82, v144, v82
	v_mul_f32_e32 v143, v105, v147
	v_fma_f32 v145, -v107, v143, v105
	v_fmac_f32_e32 v143, v145, v147
	v_pk_add_f32 v[150:151], v[150:151], 1.0 op_sel_hi:[1,0]
	v_fma_f32 v105, -v107, v143, v105
	v_div_scale_f32 v107, s[30:31], v151, v151, v85
	v_rcp_f32_e32 v145, v107
	v_div_fmas_f32 v105, v105, v147, v143
	v_div_fixup_f32 v105, v105, v144, v82
	v_cvt_pk_bf16_f32 v144, v105, v98
	v_fma_f32 v98, -v107, v145, 1.0
	v_fmac_f32_e32 v145, v98, v145
	v_div_scale_f32 v98, vcc, v85, v151, v85
	v_mul_f32_e32 v105, v98, v145
	v_fma_f32 v143, -v107, v105, v98
	v_fmac_f32_e32 v105, v143, v145
	v_fma_f32 v98, -v107, v105, v98
	v_div_scale_f32 v107, s[30:31], v150, v150, v84
	v_rcp_f32_e32 v143, v107
	v_div_fmas_f32 v98, v98, v145, v105
	v_div_fixup_f32 v98, v98, v151, v85
	v_fma_f32 v105, -v107, v143, 1.0
	v_fmac_f32_e32 v143, v105, v143
	v_div_scale_f32 v105, vcc, v84, v150, v84
	v_mul_f32_e32 v145, v105, v143
	v_fma_f32 v147, -v107, v145, v105
	v_fmac_f32_e32 v145, v147, v143
	v_fma_f32 v105, -v107, v145, v105
	v_div_fmas_f32 v105, v105, v143, v145
	v_div_fixup_f32 v105, v105, v150, v84
	v_cvt_pk_bf16_f32 v145, v105, v98
	v_mov_b32_e32 v105, v99
	v_lshl_add_u64 v[150:151], v[104:105], 1, v[108:109]
	global_store_dwordx2 v[150:151], v[144:145], off offset:-2048

.LBB0_489:
	s_ashr_i32 s10, s28, 31
	s_lshr_b32 s10, s10, 26
	s_add_i32 s10, s28, s10
	s_ashr_i32 s31, s10, 6
	s_and_b32 s10, s10, 0x3ffffc0
	s_sub_i32 s29, s28, s10
	s_mulk_i32 s29, 0xc0
	v_add_u32_e32 v2, s29, v108
	s_lshr_b32 s10, s29, 6
	s_lshl_b32 s30, s31, 7
	v_ashrrev_i32_e32 v3, 31, v2
	s_add_i32 s10, s10, s31
	v_lshlrev_b64 v[2:3], 11, v[2:3]
	v_or_b32_e32 v4, s30, v108
	s_lshl_b32 s31, s10, 6
	s_lshl_b32 s10, s10, 7
	v_ashrrev_i32_e32 v5, 31, v4
	v_lshl_add_u64 v[104:105], v[100:101], 0, v[2:3]
	s_and_b32 s10, s10, 0x780
	v_readfirstlane_b32 s34, v109
	v_lshlrev_b64 v[4:5], 11, v[4:5]
	v_lshl_add_u64 v[2:3], v[104:105], 0, s[10:11]
	s_mov_b32 m0, s34
	v_readfirstlane_b32 s34, v128
	v_lshl_add_u64 v[106:107], v[102:103], 0, v[4:5]
	s_waitcnt vmcnt(0)
	s_barrier
	s_load_dwordx2 s[66:67], s[0:1], 0x118
	s_load_dwordx2 s[68:69], s[0:1], 0xd0
	v_and_b32_e32 v201, 0x3ff, v0
	v_readfirstlane_b32 s76, v0
	v_and_b32_e32 v200, 31, v201
	v_bfe_u32 v214, v201, 1, 3
	v_bfe_u32 v213, v201, 5, 1
	v_xor_b32_e32 v214, v214, v213
	v_lshlrev_b32_e32 v214, 4, v214
	s_and_b32 s76, s76, 0x3ff
	s_lshr_b32 s79, s76, 6
	s_lshl_b32 s76, s76, 4
	s_lshr_b32 s80, s79, 1
	s_and_b32 s79, s79, 1
	s_mul_i32 s80, s80, 0x3000
	s_lshl_b32 s79, s79, 13
	s_add_u32 s79, s79, 0xc000
	v_lshlrev_b32_e32 v200, 7, v200
	v_or_b32_e32 v200, v200, v214
	v_add_u32_e32 v215, s80, v200
	v_add_u32_e32 v211, s79, v200
	v_xor_b32_e32 v214, 0x20, v215
	v_xor_b32_e32 v210, 0x20, v211
	v_xor_b32_e32 v213, 0x40, v215
	v_xor_b32_e32 v209, 0x40, v211
	v_xor_b32_e32 v212, 0x60, v215
	v_xor_b32_e32 v208, 0x60, v211
	v_bfe_u32 v200, v201, 4, 3
	v_and_b32_e32 v206, 7, v201
	v_xor_b32_e32 v200, v200, v206
	v_lshlrev_b32_e32 v200, 4, v200
	v_lshrrev_b32_e32 v206, 3, v201
	v_lshl_or_b32 v207, v206, 11, v200
	v_add_u32_e32 v206, 0x10000, v207
	v_add_u32_e32 v205, 0x20000, v207
	v_add_u32_e32 v204, 0x30000, v207
	v_add_u32_e32 v203, 0x40000, v207
	v_add_u32_e32 v202, 0x50000, v207
	s_lshr_b32 s79, s28, 6
	s_and_b32 s80, s28, 63
	s_mov_b32 s75, 0
	s_mul_i32 s80, s80, 0x60000
	s_lshl_b32 s79, s79, 18
	s_waitcnt lgkmcnt(0)
	s_add_u32 s66, s66, s80
	s_addc_u32 s67, s67, 0
	s_add_u32 s68, s68, s79
	s_addc_u32 s69, s69, 0
	s_add_u32 s79, s75, 0
	s_and_b32 s79, s79, 15
	s_lshl_b32 s79, s79, 7
	s_add_u32 s70, s66, s79
	s_addc_u32 s71, s67, 0
	s_add_u32 s72, s68, s79
	s_addc_u32 s73, s69, 0
	s_add_u32 s77, s76, 0x0
	s_add_u32 s78, s76, 0xc000
	s_add_u32 m0, s77, 0x0
	s_nop 0
	global_load_lds_dwordx4 v207, s[70:71]
	s_add_u32 m0, s77, 0x1000
	s_nop 0
	global_load_lds_dwordx4 v206, s[70:71]
	s_add_u32 m0, s77, 0x2000
	s_nop 0
	global_load_lds_dwordx4 v205, s[70:71]
	s_add_u32 m0, s77, 0x3000
	s_nop 0
	global_load_lds_dwordx4 v204, s[70:71]
	s_add_u32 m0, s77, 0x4000
	s_nop 0
	global_load_lds_dwordx4 v203, s[70:71]
	s_add_u32 m0, s77, 0x5000
	s_nop 0
	global_load_lds_dwordx4 v202, s[70:71]
	s_add_u32 m0, s78, 0x0
	s_nop 0
	global_load_lds_dwordx4 v207, s[72:73]
	s_add_u32 m0, s78, 0x1000
	s_nop 0
	global_load_lds_dwordx4 v206, s[72:73]
	s_add_u32 m0, s78, 0x2000
	s_nop 0
	global_load_lds_dwordx4 v205, s[72:73]
	s_add_u32 m0, s78, 0x3000
	s_nop 0
	global_load_lds_dwordx4 v204, s[72:73]
	s_add_u32 s79, s75, 1
	s_and_b32 s79, s79, 15
	s_lshl_b32 s79, s79, 7
	s_add_u32 s70, s66, s79
	s_addc_u32 s71, s67, 0
	s_add_u32 s72, s68, s79
	s_addc_u32 s73, s69, 0
	s_add_u32 s77, s76, 0x6000
	s_add_u32 s78, s76, 0x10000
	s_add_u32 m0, s77, 0x0
	s_nop 0
	global_load_lds_dwordx4 v207, s[70:71]
	s_add_u32 m0, s77, 0x1000
	s_nop 0
	global_load_lds_dwordx4 v206, s[70:71]
	s_add_u32 m0, s77, 0x2000
	s_nop 0
	global_load_lds_dwordx4 v205, s[70:71]
	s_add_u32 m0, s77, 0x3000
	s_nop 0
	global_load_lds_dwordx4 v204, s[70:71]
	s_add_u32 m0, s77, 0x4000
	s_nop 0
	global_load_lds_dwordx4 v203, s[70:71]
	s_add_u32 m0, s77, 0x5000
	s_nop 0
	global_load_lds_dwordx4 v202, s[70:71]
	s_add_u32 m0, s78, 0x0
	s_nop 0
	global_load_lds_dwordx4 v207, s[72:73]
	s_add_u32 m0, s78, 0x1000
	s_nop 0
	global_load_lds_dwordx4 v206, s[72:73]
	s_add_u32 m0, s78, 0x2000
	s_nop 0
	global_load_lds_dwordx4 v205, s[72:73]
	s_add_u32 m0, s78, 0x3000
	s_nop 0
	global_load_lds_dwordx4 v204, s[72:73]
	v_mov_b32_e32 v2, 0
	v_mov_b32_e32 v3, 0
	v_mov_b32_e32 v4, 0
	v_mov_b32_e32 v5, 0
	v_mov_b32_e32 v6, 0
	v_mov_b32_e32 v7, 0
	v_mov_b32_e32 v8, 0
	v_mov_b32_e32 v9, 0
	v_mov_b32_e32 v10, 0
	v_mov_b32_e32 v11, 0
	v_mov_b32_e32 v12, 0
	v_mov_b32_e32 v13, 0
	v_mov_b32_e32 v14, 0
	v_mov_b32_e32 v15, 0
	v_mov_b32_e32 v16, 0
	v_mov_b32_e32 v17, 0
	v_mov_b32_e32 v18, 0
	v_mov_b32_e32 v19, 0
	v_mov_b32_e32 v20, 0
	v_mov_b32_e32 v21, 0
	v_mov_b32_e32 v22, 0
	v_mov_b32_e32 v23, 0
	v_mov_b32_e32 v24, 0
	v_mov_b32_e32 v25, 0
	v_mov_b32_e32 v26, 0
	v_mov_b32_e32 v27, 0
	v_mov_b32_e32 v28, 0
	v_mov_b32_e32 v29, 0
	v_mov_b32_e32 v30, 0
	v_mov_b32_e32 v31, 0
	v_mov_b32_e32 v32, 0
	v_mov_b32_e32 v33, 0
	v_mov_b32_e32 v34, 0
	v_mov_b32_e32 v35, 0
	v_mov_b32_e32 v36, 0
	v_mov_b32_e32 v37, 0
	v_mov_b32_e32 v38, 0
	v_mov_b32_e32 v39, 0
	v_mov_b32_e32 v40, 0
	v_mov_b32_e32 v41, 0
	v_mov_b32_e32 v42, 0
	v_mov_b32_e32 v43, 0
	v_mov_b32_e32 v44, 0
	v_mov_b32_e32 v45, 0
	v_mov_b32_e32 v46, 0
	v_mov_b32_e32 v47, 0
	v_mov_b32_e32 v48, 0
	v_mov_b32_e32 v49, 0
	v_mov_b32_e32 v50, 0
	v_mov_b32_e32 v51, 0
	v_mov_b32_e32 v52, 0
	v_mov_b32_e32 v53, 0
	v_mov_b32_e32 v54, 0
	v_mov_b32_e32 v55, 0
	v_mov_b32_e32 v56, 0
	v_mov_b32_e32 v57, 0
	v_mov_b32_e32 v58, 0
	v_mov_b32_e32 v59, 0
	v_mov_b32_e32 v60, 0
	v_mov_b32_e32 v61, 0
	v_mov_b32_e32 v62, 0
	v_mov_b32_e32 v63, 0
	v_mov_b32_e32 v64, 0
	v_mov_b32_e32 v65, 0
	v_mov_b32_e32 v66, 0
	v_mov_b32_e32 v67, 0
	v_mov_b32_e32 v68, 0
	v_mov_b32_e32 v69, 0
	v_mov_b32_e32 v70, 0
	v_mov_b32_e32 v71, 0
	v_mov_b32_e32 v72, 0
	v_mov_b32_e32 v73, 0
	v_mov_b32_e32 v74, 0
	v_mov_b32_e32 v75, 0
	v_mov_b32_e32 v76, 0
	v_mov_b32_e32 v77, 0
	v_mov_b32_e32 v78, 0
	v_mov_b32_e32 v79, 0
	v_mov_b32_e32 v80, 0
	v_mov_b32_e32 v81, 0
	v_mov_b32_e32 v82, 0
	v_mov_b32_e32 v83, 0
	v_mov_b32_e32 v84, 0
	v_mov_b32_e32 v85, 0
	v_mov_b32_e32 v86, 0
	v_mov_b32_e32 v87, 0
	v_mov_b32_e32 v88, 0
	v_mov_b32_e32 v89, 0
	v_mov_b32_e32 v90, 0
	v_mov_b32_e32 v91, 0
	v_mov_b32_e32 v92, 0
	v_mov_b32_e32 v93, 0
	v_mov_b32_e32 v94, 0
	v_mov_b32_e32 v95, 0
	v_mov_b32_e32 v96, 0
	v_mov_b32_e32 v97, 0
	s_waitcnt vmcnt(10)
	s_barrier
	ds_read_b128 v[240:243], v211 offset:0
	ds_read_b128 v[252:255], v215 offset:0
	ds_read_b128 v[236:239], v211 offset:4096
	ds_read_b128 v[248:251], v215 offset:4096
	ds_read_b128 v[244:247], v215 offset:8192
	s_mov_b32 s74, 0
.Lgm_ph5_loop:
	s_waitcnt lgkmcnt(1)
	v_mfma_f32_32x32x16_bf16 v[82:97], v[240:243], v[252:255], v[82:97]
	ds_read_b128 v[220:223], v210 offset:0
	v_mfma_f32_32x32x16_bf16 v[66:81], v[236:239], v[252:255], v[66:81]
	ds_read_b128 v[232:235], v214 offset:0
	v_mfma_f32_32x32x16_bf16 v[50:65], v[240:243], v[248:251], v[50:65]
	ds_read_b128 v[216:219], v210 offset:4096
	v_mfma_f32_32x32x16_bf16 v[34:49], v[236:239], v[248:251], v[34:49]
	ds_read_b128 v[228:231], v214 offset:4096
	s_waitcnt lgkmcnt(4)
	v_mfma_f32_32x32x16_bf16 v[18:33], v[240:243], v[244:247], v[18:33]
	ds_read_b128 v[224:227], v214 offset:8192
	v_mfma_f32_32x32x16_bf16 v[2:17], v[236:239], v[244:247], v[2:17]
	s_waitcnt lgkmcnt(1)
	v_mfma_f32_32x32x16_bf16 v[82:97], v[220:223], v[232:235], v[82:97]
	ds_read_b128 v[240:243], v209 offset:0
	v_mfma_f32_32x32x16_bf16 v[66:81], v[216:219], v[232:235], v[66:81]
	ds_read_b128 v[252:255], v213 offset:0
	v_mfma_f32_32x32x16_bf16 v[50:65], v[220:223], v[228:231], v[50:65]
	ds_read_b128 v[236:239], v209 offset:4096
	v_mfma_f32_32x32x16_bf16 v[34:49], v[216:219], v[228:231], v[34:49]
	ds_read_b128 v[248:251], v213 offset:4096
	s_waitcnt lgkmcnt(4)
	v_mfma_f32_32x32x16_bf16 v[18:33], v[220:223], v[224:227], v[18:33]
	ds_read_b128 v[244:247], v213 offset:8192
	v_mfma_f32_32x32x16_bf16 v[2:17], v[216:219], v[224:227], v[2:17]
	s_waitcnt lgkmcnt(1)
	v_mfma_f32_32x32x16_bf16 v[82:97], v[240:243], v[252:255], v[82:97]
	ds_read_b128 v[220:223], v208 offset:0
	s_add_u32 s79, s75, s74
	s_add_u32 s79, s79, 2
	s_and_b32 s79, s79, 15
	v_mfma_f32_32x32x16_bf16 v[66:81], v[236:239], v[252:255], v[66:81]
	ds_read_b128 v[232:235], v212 offset:0
	s_lshl_b32 s79, s79, 7
	s_add_u32 s70, s66, s79
	v_mfma_f32_32x32x16_bf16 v[50:65], v[240:243], v[248:251], v[50:65]
	ds_read_b128 v[216:219], v208 offset:4096
	s_addc_u32 s71, s67, 0
	s_add_u32 s72, s68, s79
	v_mfma_f32_32x32x16_bf16 v[34:49], v[236:239], v[248:251], v[34:49]
	ds_read_b128 v[228:231], v212 offset:4096
	s_addc_u32 s73, s69, 0
	s_add_u32 s77, s76, 0x0
	s_add_u32 s78, s76, 0xc000
	s_waitcnt lgkmcnt(4)
	v_mfma_f32_32x32x16_bf16 v[18:33], v[240:243], v[244:247], v[18:33]
	ds_read_b128 v[224:227], v212 offset:8192
	v_mfma_f32_32x32x16_bf16 v[2:17], v[236:239], v[244:247], v[2:17]
	s_waitcnt vmcnt(0) lgkmcnt(0)
	s_barrier
	v_mfma_f32_32x32x16_bf16 v[82:97], v[220:223], v[232:235], v[82:97]
	s_add_u32 m0, s77, 0x0
	ds_read_b128 v[240:243], v211 offset:16384
	global_load_lds_dwordx4 v207, s[70:71]
	s_add_u32 m0, s77, 0x1000
	s_nop 0
	global_load_lds_dwordx4 v206, s[70:71]
	v_mfma_f32_32x32x16_bf16 v[66:81], v[216:219], v[232:235], v[66:81]
	s_add_u32 m0, s77, 0x2000
	ds_read_b128 v[252:255], v215 offset:24576
	global_load_lds_dwordx4 v205, s[70:71]
	s_add_u32 m0, s77, 0x3000
	s_nop 0
	global_load_lds_dwordx4 v204, s[70:71]
	v_mfma_f32_32x32x16_bf16 v[50:65], v[220:223], v[228:231], v[50:65]
	s_add_u32 m0, s77, 0x4000
	ds_read_b128 v[236:239], v211 offset:20480
	global_load_lds_dwordx4 v203, s[70:71]
	s_add_u32 m0, s77, 0x5000
	s_nop 0
	global_load_lds_dwordx4 v202, s[70:71]
	v_mfma_f32_32x32x16_bf16 v[34:49], v[216:219], v[228:231], v[34:49]
	s_add_u32 m0, s78, 0x0
	ds_read_b128 v[248:251], v215 offset:28672
	global_load_lds_dwordx4 v207, s[72:73]
	s_add_u32 m0, s78, 0x1000
	s_nop 0
	global_load_lds_dwordx4 v206, s[72:73]
	v_mfma_f32_32x32x16_bf16 v[18:33], v[220:223], v[224:227], v[18:33]
	s_add_u32 m0, s78, 0x2000
	ds_read_b128 v[244:247], v215 offset:32768
	global_load_lds_dwordx4 v205, s[72:73]
	s_add_u32 m0, s78, 0x3000
	s_nop 0
	global_load_lds_dwordx4 v204, s[72:73]
	v_mfma_f32_32x32x16_bf16 v[2:17], v[216:219], v[224:227], v[2:17]
	s_waitcnt lgkmcnt(1)
	v_mfma_f32_32x32x16_bf16 v[82:97], v[240:243], v[252:255], v[82:97]
	ds_read_b128 v[220:223], v210 offset:16384
	v_mfma_f32_32x32x16_bf16 v[66:81], v[236:239], v[252:255], v[66:81]
	ds_read_b128 v[232:235], v214 offset:24576
	v_mfma_f32_32x32x16_bf16 v[50:65], v[240:243], v[248:251], v[50:65]
	ds_read_b128 v[216:219], v210 offset:20480
	v_mfma_f32_32x32x16_bf16 v[34:49], v[236:239], v[248:251], v[34:49]
	ds_read_b128 v[228:231], v214 offset:28672
	s_waitcnt lgkmcnt(4)
	v_mfma_f32_32x32x16_bf16 v[18:33], v[240:243], v[244:247], v[18:33]
	ds_read_b128 v[224:227], v214 offset:32768
	v_mfma_f32_32x32x16_bf16 v[2:17], v[236:239], v[244:247], v[2:17]
	s_waitcnt lgkmcnt(1)
	v_mfma_f32_32x32x16_bf16 v[82:97], v[220:223], v[232:235], v[82:97]
	ds_read_b128 v[240:243], v209 offset:16384
	v_mfma_f32_32x32x16_bf16 v[66:81], v[216:219], v[232:235], v[66:81]
	ds_read_b128 v[252:255], v213 offset:24576
	v_mfma_f32_32x32x16_bf16 v[50:65], v[220:223], v[228:231], v[50:65]
	ds_read_b128 v[236:239], v209 offset:20480
	v_mfma_f32_32x32x16_bf16 v[34:49], v[216:219], v[228:231], v[34:49]
	ds_read_b128 v[248:251], v213 offset:28672
	s_waitcnt lgkmcnt(4)
	v_mfma_f32_32x32x16_bf16 v[18:33], v[220:223], v[224:227], v[18:33]
	ds_read_b128 v[244:247], v213 offset:32768
	v_mfma_f32_32x32x16_bf16 v[2:17], v[216:219], v[224:227], v[2:17]
	s_waitcnt lgkmcnt(1)
	v_mfma_f32_32x32x16_bf16 v[82:97], v[240:243], v[252:255], v[82:97]
	ds_read_b128 v[220:223], v208 offset:16384
	s_add_u32 s79, s75, s74
	s_add_u32 s79, s79, 3
	s_and_b32 s79, s79, 15
	v_mfma_f32_32x32x16_bf16 v[66:81], v[236:239], v[252:255], v[66:81]
	ds_read_b128 v[232:235], v212 offset:24576
	s_lshl_b32 s79, s79, 7
	s_add_u32 s70, s66, s79
	v_mfma_f32_32x32x16_bf16 v[50:65], v[240:243], v[248:251], v[50:65]
	ds_read_b128 v[216:219], v208 offset:20480
	s_addc_u32 s71, s67, 0
	s_add_u32 s72, s68, s79
	v_mfma_f32_32x32x16_bf16 v[34:49], v[236:239], v[248:251], v[34:49]
	ds_read_b128 v[228:231], v212 offset:28672
	s_addc_u32 s73, s69, 0
	s_add_u32 s77, s76, 0x6000
	s_add_u32 s78, s76, 0x10000
	s_waitcnt lgkmcnt(4)
	v_mfma_f32_32x32x16_bf16 v[18:33], v[240:243], v[244:247], v[18:33]
	ds_read_b128 v[224:227], v212 offset:32768
	v_mfma_f32_32x32x16_bf16 v[2:17], v[236:239], v[244:247], v[2:17]
	s_waitcnt vmcnt(0) lgkmcnt(0)
	s_barrier
	v_mfma_f32_32x32x16_bf16 v[82:97], v[220:223], v[232:235], v[82:97]
	s_add_u32 m0, s77, 0x0
	ds_read_b128 v[240:243], v211 offset:0
	global_load_lds_dwordx4 v207, s[70:71]
	s_add_u32 m0, s77, 0x1000
	s_nop 0
	global_load_lds_dwordx4 v206, s[70:71]
	v_mfma_f32_32x32x16_bf16 v[66:81], v[216:219], v[232:235], v[66:81]
	s_add_u32 m0, s77, 0x2000
	ds_read_b128 v[252:255], v215 offset:0
	global_load_lds_dwordx4 v205, s[70:71]
	s_add_u32 m0, s77, 0x3000
	s_nop 0
	global_load_lds_dwordx4 v204, s[70:71]
	v_mfma_f32_32x32x16_bf16 v[50:65], v[220:223], v[228:231], v[50:65]
	s_add_u32 m0, s77, 0x4000
	ds_read_b128 v[236:239], v211 offset:4096
	global_load_lds_dwordx4 v203, s[70:71]
	s_add_u32 m0, s77, 0x5000
	s_nop 0
	global_load_lds_dwordx4 v202, s[70:71]
	v_mfma_f32_32x32x16_bf16 v[34:49], v[216:219], v[228:231], v[34:49]
	s_add_u32 m0, s78, 0x0
	ds_read_b128 v[248:251], v215 offset:4096
	global_load_lds_dwordx4 v207, s[72:73]
	s_add_u32 m0, s78, 0x1000
	s_nop 0
	global_load_lds_dwordx4 v206, s[72:73]
	v_mfma_f32_32x32x16_bf16 v[18:33], v[220:223], v[224:227], v[18:33]
	s_add_u32 m0, s78, 0x2000
	ds_read_b128 v[244:247], v215 offset:8192
	global_load_lds_dwordx4 v205, s[72:73]
	s_add_u32 m0, s78, 0x3000
	s_nop 0
	global_load_lds_dwordx4 v204, s[72:73]
	v_mfma_f32_32x32x16_bf16 v[2:17], v[216:219], v[224:227], v[2:17]
	s_add_u32 s74, s74, 2
	s_cmp_lt_u32 s74, 14
	s_cbranch_scc1 .Lgm_ph5_loop
	s_waitcnt lgkmcnt(1)
	v_mfma_f32_32x32x16_bf16 v[82:97], v[240:243], v[252:255], v[82:97]
	ds_read_b128 v[220:223], v210 offset:0
	v_mfma_f32_32x32x16_bf16 v[66:81], v[236:239], v[252:255], v[66:81]
	ds_read_b128 v[232:235], v214 offset:0
	v_mfma_f32_32x32x16_bf16 v[50:65], v[240:243], v[248:251], v[50:65]
	ds_read_b128 v[216:219], v210 offset:4096
	v_mfma_f32_32x32x16_bf16 v[34:49], v[236:239], v[248:251], v[34:49]
	ds_read_b128 v[228:231], v214 offset:4096
	s_waitcnt lgkmcnt(4)
	v_mfma_f32_32x32x16_bf16 v[18:33], v[240:243], v[244:247], v[18:33]
	ds_read_b128 v[224:227], v214 offset:8192
	v_mfma_f32_32x32x16_bf16 v[2:17], v[236:239], v[244:247], v[2:17]
	s_waitcnt lgkmcnt(1)
	v_mfma_f32_32x32x16_bf16 v[82:97], v[220:223], v[232:235], v[82:97]
	ds_read_b128 v[240:243], v209 offset:0
	v_mfma_f32_32x32x16_bf16 v[66:81], v[216:219], v[232:235], v[66:81]
	ds_read_b128 v[252:255], v213 offset:0
	v_mfma_f32_32x32x16_bf16 v[50:65], v[220:223], v[228:231], v[50:65]
	ds_read_b128 v[236:239], v209 offset:4096
	v_mfma_f32_32x32x16_bf16 v[34:49], v[216:219], v[228:231], v[34:49]
	ds_read_b128 v[248:251], v213 offset:4096
	s_waitcnt lgkmcnt(4)
	v_mfma_f32_32x32x16_bf16 v[18:33], v[220:223], v[224:227], v[18:33]
	ds_read_b128 v[244:247], v213 offset:8192
	v_mfma_f32_32x32x16_bf16 v[2:17], v[216:219], v[224:227], v[2:17]
	s_waitcnt lgkmcnt(1)
	v_mfma_f32_32x32x16_bf16 v[82:97], v[240:243], v[252:255], v[82:97]
	ds_read_b128 v[220:223], v208 offset:0
	v_mfma_f32_32x32x16_bf16 v[66:81], v[236:239], v[252:255], v[66:81]
	ds_read_b128 v[232:235], v212 offset:0
	v_mfma_f32_32x32x16_bf16 v[50:65], v[240:243], v[248:251], v[50:65]
	ds_read_b128 v[216:219], v208 offset:4096
	v_mfma_f32_32x32x16_bf16 v[34:49], v[236:239], v[248:251], v[34:49]
	ds_read_b128 v[228:231], v212 offset:4096
	s_waitcnt lgkmcnt(4)
	v_mfma_f32_32x32x16_bf16 v[18:33], v[240:243], v[244:247], v[18:33]
	ds_read_b128 v[224:227], v212 offset:8192
	v_mfma_f32_32x32x16_bf16 v[2:17], v[236:239], v[244:247], v[2:17]
	s_waitcnt vmcnt(0) lgkmcnt(0)
	s_barrier
	v_mfma_f32_32x32x16_bf16 v[82:97], v[220:223], v[232:235], v[82:97]
	ds_read_b128 v[240:243], v211 offset:16384
	v_mfma_f32_32x32x16_bf16 v[66:81], v[216:219], v[232:235], v[66:81]
	ds_read_b128 v[252:255], v215 offset:24576
	v_mfma_f32_32x32x16_bf16 v[50:65], v[220:223], v[228:231], v[50:65]
	ds_read_b128 v[236:239], v211 offset:20480
	v_mfma_f32_32x32x16_bf16 v[34:49], v[216:219], v[228:231], v[34:49]
	ds_read_b128 v[248:251], v215 offset:28672
	v_mfma_f32_32x32x16_bf16 v[18:33], v[220:223], v[224:227], v[18:33]
	ds_read_b128 v[244:247], v215 offset:32768
	v_mfma_f32_32x32x16_bf16 v[2:17], v[216:219], v[224:227], v[2:17]
	s_waitcnt lgkmcnt(1)
	v_mfma_f32_32x32x16_bf16 v[82:97], v[240:243], v[252:255], v[82:97]
	ds_read_b128 v[220:223], v210 offset:16384
	v_mfma_f32_32x32x16_bf16 v[66:81], v[236:239], v[252:255], v[66:81]
	ds_read_b128 v[232:235], v214 offset:24576
	v_mfma_f32_32x32x16_bf16 v[50:65], v[240:243], v[248:251], v[50:65]
	ds_read_b128 v[216:219], v210 offset:20480
	v_mfma_f32_32x32x16_bf16 v[34:49], v[236:239], v[248:251], v[34:49]
	ds_read_b128 v[228:231], v214 offset:28672
	s_waitcnt lgkmcnt(4)
	v_mfma_f32_32x32x16_bf16 v[18:33], v[240:243], v[244:247], v[18:33]
	ds_read_b128 v[224:227], v214 offset:32768
	v_mfma_f32_32x32x16_bf16 v[2:17], v[236:239], v[244:247], v[2:17]
	s_waitcnt lgkmcnt(1)
	v_mfma_f32_32x32x16_bf16 v[82:97], v[220:223], v[232:235], v[82:97]
	ds_read_b128 v[240:243], v209 offset:16384
	v_mfma_f32_32x32x16_bf16 v[66:81], v[216:219], v[232:235], v[66:81]
	ds_read_b128 v[252:255], v213 offset:24576
	v_mfma_f32_32x32x16_bf16 v[50:65], v[220:223], v[228:231], v[50:65]
	ds_read_b128 v[236:239], v209 offset:20480
	v_mfma_f32_32x32x16_bf16 v[34:49], v[216:219], v[228:231], v[34:49]
	ds_read_b128 v[248:251], v213 offset:28672
	s_waitcnt lgkmcnt(4)
	v_mfma_f32_32x32x16_bf16 v[18:33], v[220:223], v[224:227], v[18:33]
	ds_read_b128 v[244:247], v213 offset:32768
	v_mfma_f32_32x32x16_bf16 v[2:17], v[216:219], v[224:227], v[2:17]
	s_waitcnt lgkmcnt(1)
	v_mfma_f32_32x32x16_bf16 v[82:97], v[240:243], v[252:255], v[82:97]
	ds_read_b128 v[220:223], v208 offset:16384
	v_mfma_f32_32x32x16_bf16 v[66:81], v[236:239], v[252:255], v[66:81]
	ds_read_b128 v[232:235], v212 offset:24576
	v_mfma_f32_32x32x16_bf16 v[50:65], v[240:243], v[248:251], v[50:65]
	ds_read_b128 v[216:219], v208 offset:20480
	v_mfma_f32_32x32x16_bf16 v[34:49], v[236:239], v[248:251], v[34:49]
	ds_read_b128 v[228:231], v212 offset:28672
	s_waitcnt lgkmcnt(4)
	v_mfma_f32_32x32x16_bf16 v[18:33], v[240:243], v[244:247], v[18:33]
	ds_read_b128 v[224:227], v212 offset:32768
	v_mfma_f32_32x32x16_bf16 v[2:17], v[236:239], v[244:247], v[2:17]
	s_waitcnt vmcnt(0) lgkmcnt(0)
	s_barrier
	v_mfma_f32_32x32x16_bf16 v[82:97], v[220:223], v[232:235], v[82:97]
	v_mfma_f32_32x32x16_bf16 v[66:81], v[216:219], v[232:235], v[66:81]
	v_mfma_f32_32x32x16_bf16 v[50:65], v[220:223], v[228:231], v[50:65]
	v_mfma_f32_32x32x16_bf16 v[34:49], v[216:219], v[228:231], v[34:49]
	v_mfma_f32_32x32x16_bf16 v[18:33], v[220:223], v[224:227], v[18:33]
	v_mfma_f32_32x32x16_bf16 v[2:17], v[216:219], v[224:227], v[2:17]
	s_nop 7
	s_nop 7
	s_waitcnt lgkmcnt(0)
	s_nop 10
	ds_write_b128 v147, v[82:85]
	ds_write_b128 v147, v[86:89] offset:32
	ds_write_b128 v147, v[90:93] offset:64
	ds_write_b128 v147, v[94:97] offset:96
	ds_write_b128 v147, v[66:69] offset:128
	ds_write_b128 v147, v[70:73] offset:160
	ds_write_b128 v147, v[74:77] offset:192
	ds_write_b128 v147, v[78:81] offset:224
	s_waitcnt lgkmcnt(0)
	v_add_u32_e32 v104, s29, v111
	v_add_u32_e32 v67, 0xfffff000, v104
	v_or_b32_e32 v66, v104, v119
	v_lshrrev_b32_e32 v67, 11, v67
	v_or_b32_e32 v106, s30, v120
	v_mad_u32_u24 v80, v67, s26, s26
	v_cmp_lt_i32_e32 vcc, s27, v66
	v_ashrrev_i32_e32 v107, 31, v106
	v_lshlrev_b64 v[68:69], 2, v[106:107]
	v_cndmask_b32_e32 v98, 0, v80, vcc
	v_lshl_add_u64 v[70:71], v[98:99], 2, s[4:5]
	v_lshl_add_u64 v[74:75], v[70:71], 0, v[68:69]
	v_add_co_u32_e32 v74, vcc, s3, v74
	ds_read_b128 v[70:73], v149
	s_nop 0
	v_addc_co_u32_e32 v75, vcc, 0, v75, vcc
	global_load_dwordx4 v[74:77], v[74:75], off
	v_ashrrev_i32_e32 v67, 31, v66
	v_lshlrev_b64 v[66:67], 11, v[66:67]
	v_or_b32_e32 v78, v104, v121
	v_cmp_lt_i32_e32 vcc, s27, v78
	v_ashrrev_i32_e32 v79, 31, v78
	v_cndmask_b32_e32 v98, 0, v80, vcc
	s_waitcnt vmcnt(0) lgkmcnt(0)
	v_mul_f32_e64 v70, v70, v74
	v_mul_f32_e64 v71, v71, v75
	v_mul_f32_e64 v72, v72, v76
	v_mul_f32_e64 v73, v73, v77
	v_cvt_pk_bf16_f32 v70, v70, v71
	v_cvt_pk_bf16_f32 v71, v72, v73
	v_lshl_add_u64 v[72:73], s[6:7], 0, v[66:67]
	v_lshlrev_b64 v[66:67], 1, v[106:107]
	v_lshl_add_u64 v[72:73], v[72:73], 0, v[66:67]
	global_store_dwordx2 v[72:73], v[70:71], off
	v_lshl_add_u64 v[70:71], v[98:99], 2, s[4:5]
	v_lshl_add_u64 v[74:75], v[70:71], 0, v[68:69]
	v_add_co_u32_e32 v74, vcc, s3, v74
	ds_read_b128 v[70:73], v149 offset:1088
	s_nop 0
	v_addc_co_u32_e32 v75, vcc, 0, v75, vcc
	global_load_dwordx4 v[74:77], v[74:75], off
	s_waitcnt vmcnt(0) lgkmcnt(0)
	v_mul_f32_e64 v70, v70, v74
	v_mul_f32_e64 v71, v71, v75
	v_mul_f32_e64 v72, v72, v76
	v_mul_f32_e64 v73, v73, v77
	v_cvt_pk_bf16_f32 v70, v70, v71
	v_cvt_pk_bf16_f32 v71, v72, v73
	v_lshlrev_b64 v[72:73], 11, v[78:79]
	v_or_b32_e32 v78, v104, v122
	v_lshl_add_u64 v[72:73], s[6:7], 0, v[72:73]
	v_cmp_lt_i32_e32 vcc, s27, v78
	v_lshl_add_u64 v[72:73], v[72:73], 0, v[66:67]
	global_store_dwordx2 v[72:73], v[70:71], off
	v_cndmask_b32_e32 v98, 0, v80, vcc
	v_lshl_add_u64 v[70:71], v[98:99], 2, s[4:5]
	v_lshl_add_u64 v[74:75], v[70:71], 0, v[68:69]
	v_add_co_u32_e32 v74, vcc, s3, v74
	ds_read_b128 v[70:73], v149 offset:2176
	s_nop 0
	v_addc_co_u32_e32 v75, vcc, 0, v75, vcc
	global_load_dwordx4 v[74:77], v[74:75], off
	v_ashrrev_i32_e32 v79, 31, v78
	s_waitcnt vmcnt(0) lgkmcnt(0)
	v_mul_f32_e64 v70, v70, v74
	v_mul_f32_e64 v71, v71, v75
	v_mul_f32_e64 v72, v72, v76
	v_mul_f32_e64 v73, v73, v77
	v_cvt_pk_bf16_f32 v70, v70, v71
	v_cvt_pk_bf16_f32 v71, v72, v73
	v_lshlrev_b64 v[72:73], 11, v[78:79]
	v_or_b32_e32 v78, v104, v123
	v_lshl_add_u64 v[72:73], s[6:7], 0, v[72:73]
	v_cmp_lt_i32_e32 vcc, s27, v78
	v_lshl_add_u64 v[72:73], v[72:73], 0, v[66:67]
	global_store_dwordx2 v[72:73], v[70:71], off
	v_cndmask_b32_e32 v98, 0, v80, vcc
	v_lshl_add_u64 v[70:71], v[98:99], 2, s[4:5]
	v_lshl_add_u64 v[74:75], v[70:71], 0, v[68:69]
	v_add_co_u32_e32 v74, vcc, s3, v74
	ds_read_b128 v[70:73], v149 offset:3264
	s_nop 0
	v_addc_co_u32_e32 v75, vcc, 0, v75, vcc
	global_load_dwordx4 v[74:77], v[74:75], off
	v_ashrrev_i32_e32 v79, 31, v78
	s_waitcnt vmcnt(0) lgkmcnt(0)
	v_mul_f32_e64 v70, v70, v74
	v_mul_f32_e64 v71, v71, v75
	v_mul_f32_e64 v72, v72, v76
	v_mul_f32_e64 v73, v73, v77
	v_cvt_pk_bf16_f32 v70, v70, v71
	v_cvt_pk_bf16_f32 v71, v72, v73
	v_lshlrev_b64 v[72:73], 11, v[78:79]
	v_or_b32_e32 v78, v104, v124
	v_lshl_add_u64 v[72:73], s[6:7], 0, v[72:73]
	v_cmp_lt_i32_e32 vcc, s27, v78
	v_lshl_add_u64 v[72:73], v[72:73], 0, v[66:67]
	global_store_dwordx2 v[72:73], v[70:71], off
	v_cndmask_b32_e32 v98, 0, v80, vcc
	v_lshl_add_u64 v[70:71], v[98:99], 2, s[4:5]
	v_lshl_add_u64 v[74:75], v[70:71], 0, v[68:69]
	v_add_co_u32_e32 v74, vcc, s3, v74
	ds_read_b128 v[70:73], v149 offset:4352
	s_nop 0
	v_addc_co_u32_e32 v75, vcc, 0, v75, vcc
	global_load_dwordx4 v[74:77], v[74:75], off
	v_ashrrev_i32_e32 v79, 31, v78
	s_waitcnt vmcnt(0) lgkmcnt(0)
	v_mul_f32_e64 v70, v70, v74
	v_mul_f32_e64 v71, v71, v75
	v_mul_f32_e64 v72, v72, v76
	v_mul_f32_e64 v73, v73, v77
	v_cvt_pk_bf16_f32 v70, v70, v71
	v_cvt_pk_bf16_f32 v71, v72, v73
	v_lshlrev_b64 v[72:73], 11, v[78:79]
	v_or_b32_e32 v78, v104, v125
	v_lshl_add_u64 v[72:73], s[6:7], 0, v[72:73]
	v_cmp_lt_i32_e32 vcc, s27, v78
	v_lshl_add_u64 v[72:73], v[72:73], 0, v[66:67]
	global_store_dwordx2 v[72:73], v[70:71], off
	v_cndmask_b32_e32 v98, 0, v80, vcc
	v_lshl_add_u64 v[70:71], v[98:99], 2, s[4:5]
	v_lshl_add_u64 v[74:75], v[70:71], 0, v[68:69]
	v_add_co_u32_e32 v74, vcc, s3, v74
	ds_read_b128 v[70:73], v149 offset:5440
	s_nop 0
	v_addc_co_u32_e32 v75, vcc, 0, v75, vcc
	global_load_dwordx4 v[74:77], v[74:75], off
	v_ashrrev_i32_e32 v79, 31, v78
	s_waitcnt vmcnt(0) lgkmcnt(0)
	v_mul_f32_e64 v70, v70, v74
	v_mul_f32_e64 v71, v71, v75
	v_mul_f32_e64 v72, v72, v76
	v_mul_f32_e64 v73, v73, v77
	v_cvt_pk_bf16_f32 v70, v70, v71
	v_cvt_pk_bf16_f32 v71, v72, v73
	v_lshlrev_b64 v[72:73], 11, v[78:79]
	v_or_b32_e32 v78, v104, v126
	v_lshl_add_u64 v[72:73], s[6:7], 0, v[72:73]
	v_cmp_lt_i32_e32 vcc, s27, v78
	v_lshl_add_u64 v[72:73], v[72:73], 0, v[66:67]
	global_store_dwordx2 v[72:73], v[70:71], off
	v_cndmask_b32_e32 v98, 0, v80, vcc
	v_lshl_add_u64 v[70:71], v[98:99], 2, s[4:5]
	v_lshl_add_u64 v[74:75], v[70:71], 0, v[68:69]
	v_add_co_u32_e32 v74, vcc, s3, v74
	ds_read_b128 v[70:73], v149 offset:6528
	s_nop 0
	v_addc_co_u32_e32 v75, vcc, 0, v75, vcc
	global_load_dwordx4 v[74:77], v[74:75], off
	v_ashrrev_i32_e32 v79, 31, v78
	s_waitcnt vmcnt(0) lgkmcnt(0)
	v_mul_f32_e64 v70, v70, v74
	v_mul_f32_e64 v71, v71, v75
	v_mul_f32_e64 v72, v72, v76
	v_mul_f32_e64 v73, v73, v77
	v_cvt_pk_bf16_f32 v70, v70, v71
	v_cvt_pk_bf16_f32 v71, v72, v73
	v_lshlrev_b64 v[72:73], 11, v[78:79]
	v_or_b32_e32 v78, v104, v127
	v_lshl_add_u64 v[72:73], s[6:7], 0, v[72:73]
	v_cmp_lt_i32_e32 vcc, s27, v78
	v_lshl_add_u64 v[72:73], v[72:73], 0, v[66:67]
	global_store_dwordx2 v[72:73], v[70:71], off
	v_cndmask_b32_e32 v98, 0, v80, vcc
	v_lshl_add_u64 v[70:71], v[98:99], 2, s[4:5]
	v_lshl_add_u64 v[74:75], v[70:71], 0, v[68:69]
	v_add_co_u32_e32 v74, vcc, s3, v74
	ds_read_b128 v[70:73], v149 offset:7616
	s_nop 0
	v_addc_co_u32_e32 v75, vcc, 0, v75, vcc
	global_load_dwordx4 v[74:77], v[74:75], off
	v_ashrrev_i32_e32 v79, 31, v78
	s_waitcnt vmcnt(0) lgkmcnt(0)
	v_mul_f32_e64 v70, v70, v74
	v_mul_f32_e64 v71, v71, v75
	v_mul_f32_e64 v72, v72, v76
	v_mul_f32_e64 v73, v73, v77
	v_cvt_pk_bf16_f32 v70, v70, v71
	v_cvt_pk_bf16_f32 v71, v72, v73
	v_lshlrev_b64 v[72:73], 11, v[78:79]
	v_lshl_add_u64 v[72:73], s[6:7], 0, v[72:73]
	v_lshl_add_u64 v[72:73], v[72:73], 0, v[66:67]
	global_store_dwordx2 v[72:73], v[70:71], off
	s_waitcnt lgkmcnt(0)
	ds_write_b128 v147, v[50:53]
	ds_write_b128 v147, v[54:57] offset:32
	ds_write_b128 v147, v[58:61] offset:64
	ds_write_b128 v147, v[62:65] offset:96
	ds_write_b128 v147, v[34:37] offset:128
	ds_write_b128 v147, v[38:41] offset:160
	ds_write_b128 v147, v[42:45] offset:192
	ds_write_b128 v147, v[46:49] offset:224
	v_add_u32_e32 v34, 32, v104
	v_add_u32_e32 v35, 0xfffff020, v104
	v_or_b32_e32 v44, v34, v119
	v_lshrrev_b32_e32 v35, 11, v35
	v_mad_u32_u24 v35, v35, s26, s26
	v_cmp_lt_i32_e32 vcc, s27, v44
	s_waitcnt lgkmcnt(0)
	v_ashrrev_i32_e32 v45, 31, v44
	v_cndmask_b32_e32 v98, 0, v35, vcc
	v_lshl_add_u64 v[36:37], v[98:99], 2, s[4:5]
	v_lshl_add_u64 v[40:41], v[36:37], 0, v[68:69]
	v_add_co_u32_e32 v40, vcc, s3, v40
	ds_read_b128 v[36:39], v149
	s_nop 0
	v_addc_co_u32_e32 v41, vcc, 0, v41, vcc
	global_load_dwordx4 v[40:43], v[40:41], off
	s_waitcnt vmcnt(0) lgkmcnt(0)
	v_mul_f32_e64 v36, v36, v40
	v_mul_f32_e64 v37, v37, v41
	v_mul_f32_e64 v38, v38, v42
	v_mul_f32_e64 v39, v39, v43
	v_cvt_pk_bf16_f32 v36, v36, v37
	v_cvt_pk_bf16_f32 v37, v38, v39
	v_lshlrev_b64 v[38:39], 11, v[44:45]
	v_or_b32_e32 v44, v34, v121
	v_lshl_add_u64 v[38:39], s[6:7], 0, v[38:39]
	v_cmp_lt_i32_e32 vcc, s27, v44
	v_lshl_add_u64 v[38:39], v[38:39], 0, v[66:67]
	global_store_dwordx2 v[38:39], v[36:37], off
	v_cndmask_b32_e32 v98, 0, v35, vcc
	v_lshl_add_u64 v[36:37], v[98:99], 2, s[4:5]
	v_lshl_add_u64 v[40:41], v[36:37], 0, v[68:69]
	v_add_co_u32_e32 v40, vcc, s3, v40
	ds_read_b128 v[36:39], v149 offset:1088
	s_nop 0
	v_addc_co_u32_e32 v41, vcc, 0, v41, vcc
	global_load_dwordx4 v[40:43], v[40:41], off
	v_ashrrev_i32_e32 v45, 31, v44
	s_waitcnt vmcnt(0) lgkmcnt(0)
	v_mul_f32_e64 v36, v36, v40
	v_mul_f32_e64 v37, v37, v41
	v_mul_f32_e64 v38, v38, v42
	v_mul_f32_e64 v39, v39, v43
	v_cvt_pk_bf16_f32 v36, v36, v37
	v_cvt_pk_bf16_f32 v37, v38, v39
	v_lshlrev_b64 v[38:39], 11, v[44:45]
	v_or_b32_e32 v44, v34, v122
	v_lshl_add_u64 v[38:39], s[6:7], 0, v[38:39]
	v_cmp_lt_i32_e32 vcc, s27, v44
	v_lshl_add_u64 v[38:39], v[38:39], 0, v[66:67]
	global_store_dwordx2 v[38:39], v[36:37], off
	v_cndmask_b32_e32 v98, 0, v35, vcc
	v_lshl_add_u64 v[36:37], v[98:99], 2, s[4:5]
	v_lshl_add_u64 v[40:41], v[36:37], 0, v[68:69]
	v_add_co_u32_e32 v40, vcc, s3, v40
	ds_read_b128 v[36:39], v149 offset:2176
	s_nop 0
	v_addc_co_u32_e32 v41, vcc, 0, v41, vcc
	global_load_dwordx4 v[40:43], v[40:41], off
	v_ashrrev_i32_e32 v45, 31, v44
	s_waitcnt vmcnt(0) lgkmcnt(0)
	v_mul_f32_e64 v36, v36, v40
	v_mul_f32_e64 v37, v37, v41
	v_mul_f32_e64 v38, v38, v42
	v_mul_f32_e64 v39, v39, v43
	v_cvt_pk_bf16_f32 v36, v36, v37
	v_cvt_pk_bf16_f32 v37, v38, v39
	v_lshlrev_b64 v[38:39], 11, v[44:45]
	v_or_b32_e32 v44, v34, v123
	v_lshl_add_u64 v[38:39], s[6:7], 0, v[38:39]
	v_cmp_lt_i32_e32 vcc, s27, v44
	v_lshl_add_u64 v[38:39], v[38:39], 0, v[66:67]
	global_store_dwordx2 v[38:39], v[36:37], off
	v_cndmask_b32_e32 v98, 0, v35, vcc
	v_lshl_add_u64 v[36:37], v[98:99], 2, s[4:5]
	v_lshl_add_u64 v[40:41], v[36:37], 0, v[68:69]
	v_add_co_u32_e32 v40, vcc, s3, v40
	ds_read_b128 v[36:39], v149 offset:3264
	s_nop 0
	v_addc_co_u32_e32 v41, vcc, 0, v41, vcc
	global_load_dwordx4 v[40:43], v[40:41], off
	v_ashrrev_i32_e32 v45, 31, v44
	s_waitcnt vmcnt(0) lgkmcnt(0)
	v_mul_f32_e64 v36, v36, v40
	v_mul_f32_e64 v37, v37, v41
	v_mul_f32_e64 v38, v38, v42
	v_mul_f32_e64 v39, v39, v43
	v_cvt_pk_bf16_f32 v36, v36, v37
	v_cvt_pk_bf16_f32 v37, v38, v39
	v_lshlrev_b64 v[38:39], 11, v[44:45]
	v_or_b32_e32 v44, v34, v124
	v_lshl_add_u64 v[38:39], s[6:7], 0, v[38:39]
	v_cmp_lt_i32_e32 vcc, s27, v44
	v_lshl_add_u64 v[38:39], v[38:39], 0, v[66:67]
	global_store_dwordx2 v[38:39], v[36:37], off
	v_cndmask_b32_e32 v98, 0, v35, vcc
	v_lshl_add_u64 v[36:37], v[98:99], 2, s[4:5]
	v_lshl_add_u64 v[40:41], v[36:37], 0, v[68:69]
	v_add_co_u32_e32 v40, vcc, s3, v40
	ds_read_b128 v[36:39], v149 offset:4352
	s_nop 0
	v_addc_co_u32_e32 v41, vcc, 0, v41, vcc
	global_load_dwordx4 v[40:43], v[40:41], off
	v_ashrrev_i32_e32 v45, 31, v44
	s_waitcnt vmcnt(0) lgkmcnt(0)
	v_mul_f32_e64 v36, v36, v40
	v_mul_f32_e64 v37, v37, v41
	v_mul_f32_e64 v38, v38, v42
	v_mul_f32_e64 v39, v39, v43
	v_cvt_pk_bf16_f32 v36, v36, v37
	v_cvt_pk_bf16_f32 v37, v38, v39
	v_lshlrev_b64 v[38:39], 11, v[44:45]
	v_or_b32_e32 v44, v34, v125
	v_lshl_add_u64 v[38:39], s[6:7], 0, v[38:39]
	v_cmp_lt_i32_e32 vcc, s27, v44
	v_lshl_add_u64 v[38:39], v[38:39], 0, v[66:67]
	global_store_dwordx2 v[38:39], v[36:37], off
	v_cndmask_b32_e32 v98, 0, v35, vcc
	v_lshl_add_u64 v[36:37], v[98:99], 2, s[4:5]
	v_lshl_add_u64 v[40:41], v[36:37], 0, v[68:69]
	v_add_co_u32_e32 v40, vcc, s3, v40
	ds_read_b128 v[36:39], v149 offset:5440
	s_nop 0
	v_addc_co_u32_e32 v41, vcc, 0, v41, vcc
	global_load_dwordx4 v[40:43], v[40:41], off
	v_ashrrev_i32_e32 v45, 31, v44
	s_waitcnt vmcnt(0) lgkmcnt(0)
	v_pk_mul_f32 v[36:37], v[36:37], v[40:41]
	v_pk_mul_f32 v[38:39], v[38:39], v[42:43]
	v_cvt_pk_bf16_f32 v36, v36, v37
	v_cvt_pk_bf16_f32 v37, v38, v39
	v_lshlrev_b64 v[38:39], 11, v[44:45]
	v_or_b32_e32 v44, v34, v126
	v_lshl_add_u64 v[38:39], s[6:7], 0, v[38:39]
	v_cmp_lt_i32_e32 vcc, s27, v44
	v_lshl_add_u64 v[38:39], v[38:39], 0, v[66:67]
	global_store_dwordx2 v[38:39], v[36:37], off
	v_cndmask_b32_e32 v98, 0, v35, vcc
	v_lshl_add_u64 v[36:37], v[98:99], 2, s[4:5]
	v_lshl_add_u64 v[40:41], v[36:37], 0, v[68:69]
	v_add_co_u32_e32 v40, vcc, s3, v40
	ds_read_b128 v[36:39], v149 offset:6528
	s_nop 0
	v_addc_co_u32_e32 v41, vcc, 0, v41, vcc
	global_load_dwordx4 v[40:43], v[40:41], off
	v_ashrrev_i32_e32 v45, 31, v44
	s_waitcnt vmcnt(0) lgkmcnt(0)
	v_pk_mul_f32 v[36:37], v[36:37], v[40:41]
	v_pk_mul_f32 v[38:39], v[38:39], v[42:43]
	v_or_b32_e32 v42, v34, v127
	v_cvt_pk_bf16_f32 v36, v36, v37
	v_cvt_pk_bf16_f32 v37, v38, v39
	v_lshlrev_b64 v[38:39], 11, v[44:45]
	v_cmp_lt_i32_e32 vcc, s27, v42
	v_lshl_add_u64 v[38:39], s[6:7], 0, v[38:39]
	v_lshl_add_u64 v[38:39], v[38:39], 0, v[66:67]
	v_cndmask_b32_e32 v98, 0, v35, vcc
	v_lshl_add_u64 v[34:35], v[98:99], 2, s[4:5]
	global_store_dwordx2 v[38:39], v[36:37], off
	v_lshl_add_u64 v[38:39], v[34:35], 0, v[68:69]
	v_add_co_u32_e32 v38, vcc, s3, v38
	ds_read_b128 v[34:37], v149 offset:7616
	s_nop 0
	v_addc_co_u32_e32 v39, vcc, 0, v39, vcc
	global_load_dwordx4 v[38:41], v[38:39], off
	v_ashrrev_i32_e32 v43, 31, v42
	s_waitcnt vmcnt(0) lgkmcnt(0)
	v_pk_mul_f32 v[34:35], v[34:35], v[38:39]
	v_pk_mul_f32 v[36:37], v[36:37], v[40:41]
	v_cvt_pk_bf16_f32 v34, v34, v35
	v_cvt_pk_bf16_f32 v35, v36, v37
	v_lshlrev_b64 v[36:37], 11, v[42:43]
	v_lshl_add_u64 v[36:37], s[6:7], 0, v[36:37]
	v_lshl_add_u64 v[36:37], v[36:37], 0, v[66:67]
	global_store_dwordx2 v[36:37], v[34:35], off
	s_waitcnt lgkmcnt(0)
	ds_write_b128 v147, v[18:21]
	ds_write_b128 v147, v[22:25] offset:32
	ds_write_b128 v147, v[26:29] offset:64
	ds_write_b128 v147, v[30:33] offset:96
	ds_write_b128 v147, v[2:5] offset:128
	ds_write_b128 v147, v[6:9] offset:160
	ds_write_b128 v147, v[10:13] offset:192
	ds_write_b128 v147, v[14:17] offset:224
	v_add_u32_e32 v2, 64, v104
	v_add_u32_e32 v3, 0xfffff040, v104
	v_or_b32_e32 v12, v2, v119
	v_lshrrev_b32_e32 v3, 11, v3
	v_mad_u32_u24 v3, v3, s26, s26
	v_cmp_lt_i32_e32 vcc, s27, v12
	s_waitcnt lgkmcnt(0)
	v_ashrrev_i32_e32 v13, 31, v12
	s_nop 0
	v_cndmask_b32_e32 v98, 0, v3, vcc
	v_lshl_add_u64 v[4:5], v[98:99], 2, s[4:5]
	v_lshl_add_u64 v[8:9], v[4:5], 0, v[68:69]
	v_add_co_u32_e32 v8, vcc, s3, v8
	ds_read_b128 v[4:7], v149
	s_nop 0
	v_addc_co_u32_e32 v9, vcc, 0, v9, vcc
	global_load_dwordx4 v[8:11], v[8:9], off
	s_waitcnt vmcnt(0) lgkmcnt(0)
	v_pk_mul_f32 v[4:5], v[4:5], v[8:9]
	v_pk_mul_f32 v[6:7], v[6:7], v[10:11]
	v_cvt_pk_bf16_f32 v4, v4, v5
	v_cvt_pk_bf16_f32 v5, v6, v7
	v_lshlrev_b64 v[6:7], 11, v[12:13]
	v_or_b32_e32 v12, v2, v121
	v_lshl_add_u64 v[6:7], s[6:7], 0, v[6:7]
	v_cmp_lt_i32_e32 vcc, s27, v12
	v_lshl_add_u64 v[6:7], v[6:7], 0, v[66:67]
	global_store_dwordx2 v[6:7], v[4:5], off
	v_cndmask_b32_e32 v98, 0, v3, vcc
	v_lshl_add_u64 v[4:5], v[98:99], 2, s[4:5]
	v_lshl_add_u64 v[8:9], v[4:5], 0, v[68:69]
	v_add_co_u32_e32 v8, vcc, s3, v8
	ds_read_b128 v[4:7], v149 offset:1088
	s_nop 0
	v_addc_co_u32_e32 v9, vcc, 0, v9, vcc
	global_load_dwordx4 v[8:11], v[8:9], off
	v_ashrrev_i32_e32 v13, 31, v12
	s_waitcnt vmcnt(0) lgkmcnt(0)
	v_pk_mul_f32 v[4:5], v[4:5], v[8:9]
	v_pk_mul_f32 v[6:7], v[6:7], v[10:11]
	v_cvt_pk_bf16_f32 v4, v4, v5
	v_cvt_pk_bf16_f32 v5, v6, v7
	v_lshlrev_b64 v[6:7], 11, v[12:13]
	v_or_b32_e32 v12, v2, v122
	v_lshl_add_u64 v[6:7], s[6:7], 0, v[6:7]
	v_cmp_lt_i32_e32 vcc, s27, v12
	v_lshl_add_u64 v[6:7], v[6:7], 0, v[66:67]
	global_store_dwordx2 v[6:7], v[4:5], off
	v_cndmask_b32_e32 v98, 0, v3, vcc
	v_lshl_add_u64 v[4:5], v[98:99], 2, s[4:5]
	v_lshl_add_u64 v[8:9], v[4:5], 0, v[68:69]
	v_add_co_u32_e32 v8, vcc, s3, v8
	ds_read_b128 v[4:7], v149 offset:2176
	s_nop 0
	v_addc_co_u32_e32 v9, vcc, 0, v9, vcc
	global_load_dwordx4 v[8:11], v[8:9], off
	v_ashrrev_i32_e32 v13, 31, v12
	s_waitcnt vmcnt(0) lgkmcnt(0)
	v_pk_mul_f32 v[4:5], v[4:5], v[8:9]
	v_pk_mul_f32 v[6:7], v[6:7], v[10:11]
	v_cvt_pk_bf16_f32 v4, v4, v5
	v_cvt_pk_bf16_f32 v5, v6, v7
	v_lshlrev_b64 v[6:7], 11, v[12:13]
	v_or_b32_e32 v12, v2, v123
	v_lshl_add_u64 v[6:7], s[6:7], 0, v[6:7]
	v_cmp_lt_i32_e32 vcc, s27, v12
	v_lshl_add_u64 v[6:7], v[6:7], 0, v[66:67]
	global_store_dwordx2 v[6:7], v[4:5], off
	v_cndmask_b32_e32 v98, 0, v3, vcc
	v_lshl_add_u64 v[4:5], v[98:99], 2, s[4:5]
	v_lshl_add_u64 v[8:9], v[4:5], 0, v[68:69]
	v_add_co_u32_e32 v8, vcc, s3, v8
	ds_read_b128 v[4:7], v149 offset:3264
	s_nop 0
	v_addc_co_u32_e32 v9, vcc, 0, v9, vcc
	global_load_dwordx4 v[8:11], v[8:9], off
	v_ashrrev_i32_e32 v13, 31, v12
	s_waitcnt vmcnt(0) lgkmcnt(0)
	v_pk_mul_f32 v[4:5], v[4:5], v[8:9]
	v_pk_mul_f32 v[6:7], v[6:7], v[10:11]
	v_cvt_pk_bf16_f32 v4, v4, v5
	v_cvt_pk_bf16_f32 v5, v6, v7
	v_lshlrev_b64 v[6:7], 11, v[12:13]
	v_or_b32_e32 v12, v2, v124
	v_lshl_add_u64 v[6:7], s[6:7], 0, v[6:7]
	v_cmp_lt_i32_e32 vcc, s27, v12
	v_lshl_add_u64 v[6:7], v[6:7], 0, v[66:67]
	global_store_dwordx2 v[6:7], v[4:5], off
	v_cndmask_b32_e32 v98, 0, v3, vcc
	v_lshl_add_u64 v[4:5], v[98:99], 2, s[4:5]
	v_lshl_add_u64 v[8:9], v[4:5], 0, v[68:69]
	v_add_co_u32_e32 v8, vcc, s3, v8
	ds_read_b128 v[4:7], v149 offset:4352
	s_nop 0
	v_addc_co_u32_e32 v9, vcc, 0, v9, vcc
	global_load_dwordx4 v[8:11], v[8:9], off
	v_ashrrev_i32_e32 v13, 31, v12
	s_waitcnt vmcnt(0) lgkmcnt(0)
	v_pk_mul_f32 v[4:5], v[4:5], v[8:9]
	v_pk_mul_f32 v[6:7], v[6:7], v[10:11]
	v_cvt_pk_bf16_f32 v4, v4, v5
	v_cvt_pk_bf16_f32 v5, v6, v7
	v_lshlrev_b64 v[6:7], 11, v[12:13]
	v_or_b32_e32 v12, v2, v125
	v_lshl_add_u64 v[6:7], s[6:7], 0, v[6:7]
	v_cmp_lt_i32_e32 vcc, s27, v12
	v_lshl_add_u64 v[6:7], v[6:7], 0, v[66:67]
	global_store_dwordx2 v[6:7], v[4:5], off
	v_cndmask_b32_e32 v98, 0, v3, vcc
	v_lshl_add_u64 v[4:5], v[98:99], 2, s[4:5]
	v_lshl_add_u64 v[8:9], v[4:5], 0, v[68:69]
	v_add_co_u32_e32 v8, vcc, s3, v8
	ds_read_b128 v[4:7], v149 offset:5440
	s_nop 0
	v_addc_co_u32_e32 v9, vcc, 0, v9, vcc
	global_load_dwordx4 v[8:11], v[8:9], off
	v_ashrrev_i32_e32 v13, 31, v12
	s_waitcnt vmcnt(0) lgkmcnt(0)
	v_pk_mul_f32 v[4:5], v[4:5], v[8:9]
	v_pk_mul_f32 v[6:7], v[6:7], v[10:11]
	v_cvt_pk_bf16_f32 v4, v4, v5
	v_cvt_pk_bf16_f32 v5, v6, v7
	v_lshlrev_b64 v[6:7], 11, v[12:13]
	v_or_b32_e32 v12, v2, v126
	v_lshl_add_u64 v[6:7], s[6:7], 0, v[6:7]
	v_cmp_lt_i32_e32 vcc, s27, v12
	v_lshl_add_u64 v[6:7], v[6:7], 0, v[66:67]
	global_store_dwordx2 v[6:7], v[4:5], off
	v_cndmask_b32_e32 v98, 0, v3, vcc
	v_lshl_add_u64 v[4:5], v[98:99], 2, s[4:5]
	v_lshl_add_u64 v[8:9], v[4:5], 0, v[68:69]
	v_add_co_u32_e32 v8, vcc, s3, v8
	ds_read_b128 v[4:7], v149 offset:6528
	s_nop 0
	v_addc_co_u32_e32 v9, vcc, 0, v9, vcc
	global_load_dwordx4 v[8:11], v[8:9], off
	v_ashrrev_i32_e32 v13, 31, v12
	s_waitcnt vmcnt(0) lgkmcnt(0)
	v_pk_mul_f32 v[4:5], v[4:5], v[8:9]
	v_pk_mul_f32 v[6:7], v[6:7], v[10:11]
	v_or_b32_e32 v10, v2, v127
	v_cvt_pk_bf16_f32 v4, v4, v5
	v_cvt_pk_bf16_f32 v5, v6, v7
	v_lshlrev_b64 v[6:7], 11, v[12:13]
	v_cmp_lt_i32_e32 vcc, s27, v10
	v_lshl_add_u64 v[6:7], s[6:7], 0, v[6:7]
	v_lshl_add_u64 v[6:7], v[6:7], 0, v[66:67]
	v_cndmask_b32_e32 v98, 0, v3, vcc
	v_lshl_add_u64 v[2:3], v[98:99], 2, s[4:5]
	global_store_dwordx2 v[6:7], v[4:5], off
	v_lshl_add_u64 v[6:7], v[2:3], 0, v[68:69]
	v_add_co_u32_e32 v6, vcc, s3, v6
	ds_read_b128 v[2:5], v149 offset:7616
	s_nop 0
	v_addc_co_u32_e32 v7, vcc, 0, v7, vcc
	global_load_dwordx4 v[6:9], v[6:7], off
	v_ashrrev_i32_e32 v11, 31, v10
	s_waitcnt vmcnt(0) lgkmcnt(0)
	v_pk_mul_f32 v[2:3], v[2:3], v[6:7]
	v_pk_mul_f32 v[4:5], v[4:5], v[8:9]
	v_cvt_pk_bf16_f32 v2, v2, v3
	v_cvt_pk_bf16_f32 v3, v4, v5
	v_lshlrev_b64 v[4:5], 11, v[10:11]
	v_lshl_add_u64 v[4:5], s[6:7], 0, v[4:5]
	v_lshl_add_u64 v[4:5], v[4:5], 0, v[66:67]
	global_store_dwordx2 v[4:5], v[2:3], off
	s_waitcnt lgkmcnt(0)
	s_load_dword s10, s[8:9], 0x0
	s_waitcnt lgkmcnt(0)
	s_add_i32 s28, s10, s28
	s_cmpk_lt_i32 s28, 0x200
	s_cbranch_scc1 .LBB0_489

.LBB0_626:
	s_ashr_i32 s4, s56, 31
	s_lshr_b32 s4, s4, 26
	s_add_i32 s4, s56, s4
	s_ashr_i32 s6, s4, 6
	s_and_b32 s4, s4, 0x3ffffc0
	s_sub_i32 s4, s56, s4
	s_mulk_i32 s4, 0xc0
	v_add_u32_e32 v2, s4, v147
	s_lshr_b32 s7, s4, 6
	s_lshl_b32 s5, s6, 7
	v_ashrrev_i32_e32 v3, 31, v2
	s_add_i32 s7, s7, s6
	v_lshlrev_b64 v[2:3], 11, v[2:3]
	v_or_b32_e32 v4, s5, v147
	s_lshl_b32 s6, s7, 6
	s_lshl_b32 s7, s7, 7
	v_ashrrev_i32_e32 v5, 31, v4
	v_lshl_add_u64 v[138:139], v[100:101], 0, v[2:3]
	s_and_b32 s12, s7, 0x780
	v_readfirstlane_b32 s7, v149
	v_lshlrev_b64 v[4:5], 11, v[4:5]
	v_lshl_add_u64 v[2:3], v[138:139], 0, s[12:13]
	s_mov_b32 m0, s7
	v_readfirstlane_b32 s7, v172
	v_lshl_add_u64 v[140:141], v[102:103], 0, v[4:5]
	s_waitcnt vmcnt(0)
	s_barrier
	s_load_dwordx2 s[66:67], s[0:1], 0x90
	s_load_dwordx2 s[68:69], s[0:1], 0xd8
	v_and_b32_e32 v201, 0x3ff, v0
	v_readfirstlane_b32 s76, v0
	v_and_b32_e32 v200, 31, v201
	v_bfe_u32 v214, v201, 1, 3
	v_bfe_u32 v213, v201, 5, 1
	v_xor_b32_e32 v214, v214, v213
	v_lshlrev_b32_e32 v214, 4, v214
	s_and_b32 s76, s76, 0x3ff
	s_lshr_b32 s79, s76, 6
	s_lshl_b32 s76, s76, 4
	s_lshr_b32 s80, s79, 1
	s_and_b32 s79, s79, 1
	s_mul_i32 s80, s80, 0x3000
	s_lshl_b32 s79, s79, 13
	s_add_u32 s79, s79, 0xc000
	v_lshlrev_b32_e32 v200, 7, v200
	v_or_b32_e32 v200, v200, v214
	v_add_u32_e32 v215, s80, v200
	v_add_u32_e32 v211, s79, v200
	v_xor_b32_e32 v214, 0x20, v215
	v_xor_b32_e32 v210, 0x20, v211
	v_xor_b32_e32 v213, 0x40, v215
	v_xor_b32_e32 v209, 0x40, v211
	v_xor_b32_e32 v212, 0x60, v215
	v_xor_b32_e32 v208, 0x60, v211
	v_bfe_u32 v200, v201, 4, 3
	v_and_b32_e32 v206, 7, v201
	v_xor_b32_e32 v200, v200, v206
	v_lshlrev_b32_e32 v200, 4, v200
	v_lshrrev_b32_e32 v206, 3, v201
	v_lshl_or_b32 v207, v206, 11, v200
	v_add_u32_e32 v206, 0x10000, v207
	v_add_u32_e32 v205, 0x20000, v207
	v_add_u32_e32 v204, 0x30000, v207
	v_add_u32_e32 v203, 0x40000, v207
	v_add_u32_e32 v202, 0x50000, v207
	s_lshr_b32 s79, s56, 6
	s_and_b32 s80, s56, 63
	s_mov_b32 s75, 0
	s_mul_i32 s80, s80, 0x60000
	s_lshl_b32 s79, s79, 18
	s_waitcnt lgkmcnt(0)
	s_add_u32 s66, s66, s80
	s_addc_u32 s67, s67, 0
	s_add_u32 s68, s68, s79
	s_addc_u32 s69, s69, 0
	s_add_u32 s79, s75, 0
	s_and_b32 s79, s79, 15
	s_lshl_b32 s79, s79, 7
	s_add_u32 s70, s66, s79
	s_addc_u32 s71, s67, 0
	s_add_u32 s72, s68, s79
	s_addc_u32 s73, s69, 0
	s_add_u32 s77, s76, 0x0
	s_add_u32 s78, s76, 0xc000
	s_add_u32 m0, s77, 0x0
	s_nop 0
	global_load_lds_dwordx4 v207, s[70:71]
	s_add_u32 m0, s77, 0x1000
	s_nop 0
	global_load_lds_dwordx4 v206, s[70:71]
	s_add_u32 m0, s77, 0x2000
	s_nop 0
	global_load_lds_dwordx4 v205, s[70:71]
	s_add_u32 m0, s77, 0x3000
	s_nop 0
	global_load_lds_dwordx4 v204, s[70:71]
	s_add_u32 m0, s77, 0x4000
	s_nop 0
	global_load_lds_dwordx4 v203, s[70:71]
	s_add_u32 m0, s77, 0x5000
	s_nop 0
	global_load_lds_dwordx4 v202, s[70:71]
	s_add_u32 m0, s78, 0x0
	s_nop 0
	global_load_lds_dwordx4 v207, s[72:73]
	s_add_u32 m0, s78, 0x1000
	s_nop 0
	global_load_lds_dwordx4 v206, s[72:73]
	s_add_u32 m0, s78, 0x2000
	s_nop 0
	global_load_lds_dwordx4 v205, s[72:73]
	s_add_u32 m0, s78, 0x3000
	s_nop 0
	global_load_lds_dwordx4 v204, s[72:73]
	s_add_u32 s79, s75, 1
	s_and_b32 s79, s79, 15
	s_lshl_b32 s79, s79, 7
	s_add_u32 s70, s66, s79
	s_addc_u32 s71, s67, 0
	s_add_u32 s72, s68, s79
	s_addc_u32 s73, s69, 0
	s_add_u32 s77, s76, 0x6000
	s_add_u32 s78, s76, 0x10000
	s_add_u32 m0, s77, 0x0
	s_nop 0
	global_load_lds_dwordx4 v207, s[70:71]
	s_add_u32 m0, s77, 0x1000
	s_nop 0
	global_load_lds_dwordx4 v206, s[70:71]
	s_add_u32 m0, s77, 0x2000
	s_nop 0
	global_load_lds_dwordx4 v205, s[70:71]
	s_add_u32 m0, s77, 0x3000
	s_nop 0
	global_load_lds_dwordx4 v204, s[70:71]
	s_add_u32 m0, s77, 0x4000
	s_nop 0
	global_load_lds_dwordx4 v203, s[70:71]
	s_add_u32 m0, s77, 0x5000
	s_nop 0
	global_load_lds_dwordx4 v202, s[70:71]
	s_add_u32 m0, s78, 0x0
	s_nop 0
	global_load_lds_dwordx4 v207, s[72:73]
	s_add_u32 m0, s78, 0x1000
	s_nop 0
	global_load_lds_dwordx4 v206, s[72:73]
	s_add_u32 m0, s78, 0x2000
	s_nop 0
	global_load_lds_dwordx4 v205, s[72:73]
	s_add_u32 m0, s78, 0x3000
	s_nop 0
	global_load_lds_dwordx4 v204, s[72:73]
	v_mov_b32_e32 v2, 0
	v_mov_b32_e32 v3, 0
	v_mov_b32_e32 v4, 0
	v_mov_b32_e32 v5, 0
	v_mov_b32_e32 v6, 0
	v_mov_b32_e32 v7, 0
	v_mov_b32_e32 v8, 0
	v_mov_b32_e32 v9, 0
	v_mov_b32_e32 v10, 0
	v_mov_b32_e32 v11, 0
	v_mov_b32_e32 v12, 0
	v_mov_b32_e32 v13, 0
	v_mov_b32_e32 v14, 0
	v_mov_b32_e32 v15, 0
	v_mov_b32_e32 v16, 0
	v_mov_b32_e32 v17, 0
	v_mov_b32_e32 v18, 0
	v_mov_b32_e32 v19, 0
	v_mov_b32_e32 v20, 0
	v_mov_b32_e32 v21, 0
	v_mov_b32_e32 v22, 0
	v_mov_b32_e32 v23, 0
	v_mov_b32_e32 v24, 0
	v_mov_b32_e32 v25, 0
	v_mov_b32_e32 v26, 0
	v_mov_b32_e32 v27, 0
	v_mov_b32_e32 v28, 0
	v_mov_b32_e32 v29, 0
	v_mov_b32_e32 v30, 0
	v_mov_b32_e32 v31, 0
	v_mov_b32_e32 v32, 0
	v_mov_b32_e32 v33, 0
	v_mov_b32_e32 v34, 0
	v_mov_b32_e32 v35, 0
	v_mov_b32_e32 v36, 0
	v_mov_b32_e32 v37, 0
	v_mov_b32_e32 v38, 0
	v_mov_b32_e32 v39, 0
	v_mov_b32_e32 v40, 0
	v_mov_b32_e32 v41, 0
	v_mov_b32_e32 v42, 0
	v_mov_b32_e32 v43, 0
	v_mov_b32_e32 v44, 0
	v_mov_b32_e32 v45, 0
	v_mov_b32_e32 v46, 0
	v_mov_b32_e32 v47, 0
	v_mov_b32_e32 v48, 0
	v_mov_b32_e32 v49, 0
	v_mov_b32_e32 v50, 0
	v_mov_b32_e32 v51, 0
	v_mov_b32_e32 v52, 0
	v_mov_b32_e32 v53, 0
	v_mov_b32_e32 v54, 0
	v_mov_b32_e32 v55, 0
	v_mov_b32_e32 v56, 0
	v_mov_b32_e32 v57, 0
	v_mov_b32_e32 v58, 0
	v_mov_b32_e32 v59, 0
	v_mov_b32_e32 v60, 0
	v_mov_b32_e32 v61, 0
	v_mov_b32_e32 v62, 0
	v_mov_b32_e32 v63, 0
	v_mov_b32_e32 v64, 0
	v_mov_b32_e32 v65, 0
	v_mov_b32_e32 v66, 0
	v_mov_b32_e32 v67, 0
	v_mov_b32_e32 v68, 0
	v_mov_b32_e32 v69, 0
	v_mov_b32_e32 v70, 0
	v_mov_b32_e32 v71, 0
	v_mov_b32_e32 v72, 0
	v_mov_b32_e32 v73, 0
	v_mov_b32_e32 v74, 0
	v_mov_b32_e32 v75, 0
	v_mov_b32_e32 v76, 0
	v_mov_b32_e32 v77, 0
	v_mov_b32_e32 v78, 0
	v_mov_b32_e32 v79, 0
	v_mov_b32_e32 v80, 0
	v_mov_b32_e32 v81, 0
	v_mov_b32_e32 v82, 0
	v_mov_b32_e32 v83, 0
	v_mov_b32_e32 v84, 0
	v_mov_b32_e32 v85, 0
	v_mov_b32_e32 v86, 0
	v_mov_b32_e32 v87, 0
	v_mov_b32_e32 v88, 0
	v_mov_b32_e32 v89, 0
	v_mov_b32_e32 v90, 0
	v_mov_b32_e32 v91, 0
	v_mov_b32_e32 v92, 0
	v_mov_b32_e32 v93, 0
	v_mov_b32_e32 v94, 0
	v_mov_b32_e32 v95, 0
	v_mov_b32_e32 v96, 0
	v_mov_b32_e32 v97, 0
	s_waitcnt vmcnt(10)
	s_barrier
	ds_read_b128 v[240:243], v211 offset:0
	ds_read_b128 v[252:255], v215 offset:0
	ds_read_b128 v[236:239], v211 offset:4096
	ds_read_b128 v[248:251], v215 offset:4096
	ds_read_b128 v[244:247], v215 offset:8192
	s_mov_b32 s74, 0
.Lgm_ph7_loop:
	s_waitcnt lgkmcnt(1)
	v_mfma_f32_32x32x16_bf16 v[82:97], v[240:243], v[252:255], v[82:97]
	ds_read_b128 v[220:223], v210 offset:0
	v_mfma_f32_32x32x16_bf16 v[66:81], v[236:239], v[252:255], v[66:81]
	ds_read_b128 v[232:235], v214 offset:0
	v_mfma_f32_32x32x16_bf16 v[50:65], v[240:243], v[248:251], v[50:65]
	ds_read_b128 v[216:219], v210 offset:4096
	v_mfma_f32_32x32x16_bf16 v[34:49], v[236:239], v[248:251], v[34:49]
	ds_read_b128 v[228:231], v214 offset:4096
	s_waitcnt lgkmcnt(4)
	v_mfma_f32_32x32x16_bf16 v[18:33], v[240:243], v[244:247], v[18:33]
	ds_read_b128 v[224:227], v214 offset:8192
	v_mfma_f32_32x32x16_bf16 v[2:17], v[236:239], v[244:247], v[2:17]
	s_waitcnt lgkmcnt(1)
	v_mfma_f32_32x32x16_bf16 v[82:97], v[220:223], v[232:235], v[82:97]
	ds_read_b128 v[240:243], v209 offset:0
	v_mfma_f32_32x32x16_bf16 v[66:81], v[216:219], v[232:235], v[66:81]
	ds_read_b128 v[252:255], v213 offset:0
	v_mfma_f32_32x32x16_bf16 v[50:65], v[220:223], v[228:231], v[50:65]
	ds_read_b128 v[236:239], v209 offset:4096
	v_mfma_f32_32x32x16_bf16 v[34:49], v[216:219], v[228:231], v[34:49]
	ds_read_b128 v[248:251], v213 offset:4096
	s_waitcnt lgkmcnt(4)
	v_mfma_f32_32x32x16_bf16 v[18:33], v[220:223], v[224:227], v[18:33]
	ds_read_b128 v[244:247], v213 offset:8192
	v_mfma_f32_32x32x16_bf16 v[2:17], v[216:219], v[224:227], v[2:17]
	s_waitcnt lgkmcnt(1)
	v_mfma_f32_32x32x16_bf16 v[82:97], v[240:243], v[252:255], v[82:97]
	ds_read_b128 v[220:223], v208 offset:0
	s_add_u32 s79, s75, s74
	s_add_u32 s79, s79, 2
	s_and_b32 s79, s79, 15
	v_mfma_f32_32x32x16_bf16 v[66:81], v[236:239], v[252:255], v[66:81]
	ds_read_b128 v[232:235], v212 offset:0
	s_lshl_b32 s79, s79, 7
	s_add_u32 s70, s66, s79
	v_mfma_f32_32x32x16_bf16 v[50:65], v[240:243], v[248:251], v[50:65]
	ds_read_b128 v[216:219], v208 offset:4096
	s_addc_u32 s71, s67, 0
	s_add_u32 s72, s68, s79
	v_mfma_f32_32x32x16_bf16 v[34:49], v[236:239], v[248:251], v[34:49]
	ds_read_b128 v[228:231], v212 offset:4096
	s_addc_u32 s73, s69, 0
	s_add_u32 s77, s76, 0x0
	s_add_u32 s78, s76, 0xc000
	s_waitcnt lgkmcnt(4)
	v_mfma_f32_32x32x16_bf16 v[18:33], v[240:243], v[244:247], v[18:33]
	ds_read_b128 v[224:227], v212 offset:8192
	v_mfma_f32_32x32x16_bf16 v[2:17], v[236:239], v[244:247], v[2:17]
	s_waitcnt vmcnt(0) lgkmcnt(0)
	s_barrier
	v_mfma_f32_32x32x16_bf16 v[82:97], v[220:223], v[232:235], v[82:97]
	s_add_u32 m0, s77, 0x0
	ds_read_b128 v[240:243], v211 offset:16384
	global_load_lds_dwordx4 v207, s[70:71]
	s_add_u32 m0, s77, 0x1000
	s_nop 0
	global_load_lds_dwordx4 v206, s[70:71]
	v_mfma_f32_32x32x16_bf16 v[66:81], v[216:219], v[232:235], v[66:81]
	s_add_u32 m0, s77, 0x2000
	ds_read_b128 v[252:255], v215 offset:24576
	global_load_lds_dwordx4 v205, s[70:71]
	s_add_u32 m0, s77, 0x3000
	s_nop 0
	global_load_lds_dwordx4 v204, s[70:71]
	v_mfma_f32_32x32x16_bf16 v[50:65], v[220:223], v[228:231], v[50:65]
	s_add_u32 m0, s77, 0x4000
	ds_read_b128 v[236:239], v211 offset:20480
	global_load_lds_dwordx4 v203, s[70:71]
	s_add_u32 m0, s77, 0x5000
	s_nop 0
	global_load_lds_dwordx4 v202, s[70:71]
	v_mfma_f32_32x32x16_bf16 v[34:49], v[216:219], v[228:231], v[34:49]
	s_add_u32 m0, s78, 0x0
	ds_read_b128 v[248:251], v215 offset:28672
	global_load_lds_dwordx4 v207, s[72:73]
	s_add_u32 m0, s78, 0x1000
	s_nop 0
	global_load_lds_dwordx4 v206, s[72:73]
	v_mfma_f32_32x32x16_bf16 v[18:33], v[220:223], v[224:227], v[18:33]
	s_add_u32 m0, s78, 0x2000
	ds_read_b128 v[244:247], v215 offset:32768
	global_load_lds_dwordx4 v205, s[72:73]
	s_add_u32 m0, s78, 0x3000
	s_nop 0
	global_load_lds_dwordx4 v204, s[72:73]
	v_mfma_f32_32x32x16_bf16 v[2:17], v[216:219], v[224:227], v[2:17]
	s_waitcnt lgkmcnt(1)
	v_mfma_f32_32x32x16_bf16 v[82:97], v[240:243], v[252:255], v[82:97]
	ds_read_b128 v[220:223], v210 offset:16384
	v_mfma_f32_32x32x16_bf16 v[66:81], v[236:239], v[252:255], v[66:81]
	ds_read_b128 v[232:235], v214 offset:24576
	v_mfma_f32_32x32x16_bf16 v[50:65], v[240:243], v[248:251], v[50:65]
	ds_read_b128 v[216:219], v210 offset:20480
	v_mfma_f32_32x32x16_bf16 v[34:49], v[236:239], v[248:251], v[34:49]
	ds_read_b128 v[228:231], v214 offset:28672
	s_waitcnt lgkmcnt(4)
	v_mfma_f32_32x32x16_bf16 v[18:33], v[240:243], v[244:247], v[18:33]
	ds_read_b128 v[224:227], v214 offset:32768
	v_mfma_f32_32x32x16_bf16 v[2:17], v[236:239], v[244:247], v[2:17]
	s_waitcnt lgkmcnt(1)
	v_mfma_f32_32x32x16_bf16 v[82:97], v[220:223], v[232:235], v[82:97]
	ds_read_b128 v[240:243], v209 offset:16384
	v_mfma_f32_32x32x16_bf16 v[66:81], v[216:219], v[232:235], v[66:81]
	ds_read_b128 v[252:255], v213 offset:24576
	v_mfma_f32_32x32x16_bf16 v[50:65], v[220:223], v[228:231], v[50:65]
	ds_read_b128 v[236:239], v209 offset:20480
	v_mfma_f32_32x32x16_bf16 v[34:49], v[216:219], v[228:231], v[34:49]
	ds_read_b128 v[248:251], v213 offset:28672
	s_waitcnt lgkmcnt(4)
	v_mfma_f32_32x32x16_bf16 v[18:33], v[220:223], v[224:227], v[18:33]
	ds_read_b128 v[244:247], v213 offset:32768
	v_mfma_f32_32x32x16_bf16 v[2:17], v[216:219], v[224:227], v[2:17]
	s_waitcnt lgkmcnt(1)
	v_mfma_f32_32x32x16_bf16 v[82:97], v[240:243], v[252:255], v[82:97]
	ds_read_b128 v[220:223], v208 offset:16384
	s_add_u32 s79, s75, s74
	s_add_u32 s79, s79, 3
	s_and_b32 s79, s79, 15
	v_mfma_f32_32x32x16_bf16 v[66:81], v[236:239], v[252:255], v[66:81]
	ds_read_b128 v[232:235], v212 offset:24576
	s_lshl_b32 s79, s79, 7
	s_add_u32 s70, s66, s79
	v_mfma_f32_32x32x16_bf16 v[50:65], v[240:243], v[248:251], v[50:65]
	ds_read_b128 v[216:219], v208 offset:20480
	s_addc_u32 s71, s67, 0
	s_add_u32 s72, s68, s79
	v_mfma_f32_32x32x16_bf16 v[34:49], v[236:239], v[248:251], v[34:49]
	ds_read_b128 v[228:231], v212 offset:28672
	s_addc_u32 s73, s69, 0
	s_add_u32 s77, s76, 0x6000
	s_add_u32 s78, s76, 0x10000
	s_waitcnt lgkmcnt(4)
	v_mfma_f32_32x32x16_bf16 v[18:33], v[240:243], v[244:247], v[18:33]
	ds_read_b128 v[224:227], v212 offset:32768
	v_mfma_f32_32x32x16_bf16 v[2:17], v[236:239], v[244:247], v[2:17]
	s_waitcnt vmcnt(0) lgkmcnt(0)
	s_barrier
	v_mfma_f32_32x32x16_bf16 v[82:97], v[220:223], v[232:235], v[82:97]
	s_add_u32 m0, s77, 0x0
	ds_read_b128 v[240:243], v211 offset:0
	global_load_lds_dwordx4 v207, s[70:71]
	s_add_u32 m0, s77, 0x1000
	s_nop 0
	global_load_lds_dwordx4 v206, s[70:71]
	v_mfma_f32_32x32x16_bf16 v[66:81], v[216:219], v[232:235], v[66:81]
	s_add_u32 m0, s77, 0x2000
	ds_read_b128 v[252:255], v215 offset:0
	global_load_lds_dwordx4 v205, s[70:71]
	s_add_u32 m0, s77, 0x3000
	s_nop 0
	global_load_lds_dwordx4 v204, s[70:71]
	v_mfma_f32_32x32x16_bf16 v[50:65], v[220:223], v[228:231], v[50:65]
	s_add_u32 m0, s77, 0x4000
	ds_read_b128 v[236:239], v211 offset:4096
	global_load_lds_dwordx4 v203, s[70:71]
	s_add_u32 m0, s77, 0x5000
	s_nop 0
	global_load_lds_dwordx4 v202, s[70:71]
	v_mfma_f32_32x32x16_bf16 v[34:49], v[216:219], v[228:231], v[34:49]
	s_add_u32 m0, s78, 0x0
	ds_read_b128 v[248:251], v215 offset:4096
	global_load_lds_dwordx4 v207, s[72:73]
	s_add_u32 m0, s78, 0x1000
	s_nop 0
	global_load_lds_dwordx4 v206, s[72:73]
	v_mfma_f32_32x32x16_bf16 v[18:33], v[220:223], v[224:227], v[18:33]
	s_add_u32 m0, s78, 0x2000
	ds_read_b128 v[244:247], v215 offset:8192
	global_load_lds_dwordx4 v205, s[72:73]
	s_add_u32 m0, s78, 0x3000
	s_nop 0
	global_load_lds_dwordx4 v204, s[72:73]
	v_mfma_f32_32x32x16_bf16 v[2:17], v[216:219], v[224:227], v[2:17]
	s_add_u32 s74, s74, 2
	s_cmp_lt_u32 s74, 14
	s_cbranch_scc1 .Lgm_ph7_loop
	s_waitcnt lgkmcnt(1)
	v_mfma_f32_32x32x16_bf16 v[82:97], v[240:243], v[252:255], v[82:97]
	ds_read_b128 v[220:223], v210 offset:0
	v_mfma_f32_32x32x16_bf16 v[66:81], v[236:239], v[252:255], v[66:81]
	ds_read_b128 v[232:235], v214 offset:0
	v_mfma_f32_32x32x16_bf16 v[50:65], v[240:243], v[248:251], v[50:65]
	ds_read_b128 v[216:219], v210 offset:4096
	v_mfma_f32_32x32x16_bf16 v[34:49], v[236:239], v[248:251], v[34:49]
	ds_read_b128 v[228:231], v214 offset:4096
	s_waitcnt lgkmcnt(4)
	v_mfma_f32_32x32x16_bf16 v[18:33], v[240:243], v[244:247], v[18:33]
	ds_read_b128 v[224:227], v214 offset:8192
	v_mfma_f32_32x32x16_bf16 v[2:17], v[236:239], v[244:247], v[2:17]
	s_waitcnt lgkmcnt(1)
	v_mfma_f32_32x32x16_bf16 v[82:97], v[220:223], v[232:235], v[82:97]
	ds_read_b128 v[240:243], v209 offset:0
	v_mfma_f32_32x32x16_bf16 v[66:81], v[216:219], v[232:235], v[66:81]
	ds_read_b128 v[252:255], v213 offset:0
	v_mfma_f32_32x32x16_bf16 v[50:65], v[220:223], v[228:231], v[50:65]
	ds_read_b128 v[236:239], v209 offset:4096
	v_mfma_f32_32x32x16_bf16 v[34:49], v[216:219], v[228:231], v[34:49]
	ds_read_b128 v[248:251], v213 offset:4096
	s_waitcnt lgkmcnt(4)
	v_mfma_f32_32x32x16_bf16 v[18:33], v[220:223], v[224:227], v[18:33]
	ds_read_b128 v[244:247], v213 offset:8192
	v_mfma_f32_32x32x16_bf16 v[2:17], v[216:219], v[224:227], v[2:17]
	s_waitcnt lgkmcnt(1)
	v_mfma_f32_32x32x16_bf16 v[82:97], v[240:243], v[252:255], v[82:97]
	ds_read_b128 v[220:223], v208 offset:0
	v_mfma_f32_32x32x16_bf16 v[66:81], v[236:239], v[252:255], v[66:81]
	ds_read_b128 v[232:235], v212 offset:0
	v_mfma_f32_32x32x16_bf16 v[50:65], v[240:243], v[248:251], v[50:65]
	ds_read_b128 v[216:219], v208 offset:4096
	v_mfma_f32_32x32x16_bf16 v[34:49], v[236:239], v[248:251], v[34:49]
	ds_read_b128 v[228:231], v212 offset:4096
	s_waitcnt lgkmcnt(4)
	v_mfma_f32_32x32x16_bf16 v[18:33], v[240:243], v[244:247], v[18:33]
	ds_read_b128 v[224:227], v212 offset:8192
	v_mfma_f32_32x32x16_bf16 v[2:17], v[236:239], v[244:247], v[2:17]
	s_waitcnt vmcnt(0) lgkmcnt(0)
	s_barrier
	v_mfma_f32_32x32x16_bf16 v[82:97], v[220:223], v[232:235], v[82:97]
	ds_read_b128 v[240:243], v211 offset:16384
	v_mfma_f32_32x32x16_bf16 v[66:81], v[216:219], v[232:235], v[66:81]
	ds_read_b128 v[252:255], v215 offset:24576
	v_mfma_f32_32x32x16_bf16 v[50:65], v[220:223], v[228:231], v[50:65]
	ds_read_b128 v[236:239], v211 offset:20480
	v_mfma_f32_32x32x16_bf16 v[34:49], v[216:219], v[228:231], v[34:49]
	ds_read_b128 v[248:251], v215 offset:28672
	v_mfma_f32_32x32x16_bf16 v[18:33], v[220:223], v[224:227], v[18:33]
	ds_read_b128 v[244:247], v215 offset:32768
	v_mfma_f32_32x32x16_bf16 v[2:17], v[216:219], v[224:227], v[2:17]
	s_waitcnt lgkmcnt(1)
	v_mfma_f32_32x32x16_bf16 v[82:97], v[240:243], v[252:255], v[82:97]
	ds_read_b128 v[220:223], v210 offset:16384
	v_mfma_f32_32x32x16_bf16 v[66:81], v[236:239], v[252:255], v[66:81]
	ds_read_b128 v[232:235], v214 offset:24576
	v_mfma_f32_32x32x16_bf16 v[50:65], v[240:243], v[248:251], v[50:65]
	ds_read_b128 v[216:219], v210 offset:20480
	v_mfma_f32_32x32x16_bf16 v[34:49], v[236:239], v[248:251], v[34:49]
	ds_read_b128 v[228:231], v214 offset:28672
	s_waitcnt lgkmcnt(4)
	v_mfma_f32_32x32x16_bf16 v[18:33], v[240:243], v[244:247], v[18:33]
	ds_read_b128 v[224:227], v214 offset:32768
	v_mfma_f32_32x32x16_bf16 v[2:17], v[236:239], v[244:247], v[2:17]
	s_waitcnt lgkmcnt(1)
	v_mfma_f32_32x32x16_bf16 v[82:97], v[220:223], v[232:235], v[82:97]
	ds_read_b128 v[240:243], v209 offset:16384
	v_mfma_f32_32x32x16_bf16 v[66:81], v[216:219], v[232:235], v[66:81]
	ds_read_b128 v[252:255], v213 offset:24576
	v_mfma_f32_32x32x16_bf16 v[50:65], v[220:223], v[228:231], v[50:65]
	ds_read_b128 v[236:239], v209 offset:20480
	v_mfma_f32_32x32x16_bf16 v[34:49], v[216:219], v[228:231], v[34:49]
	ds_read_b128 v[248:251], v213 offset:28672
	s_waitcnt lgkmcnt(4)
	v_mfma_f32_32x32x16_bf16 v[18:33], v[220:223], v[224:227], v[18:33]
	ds_read_b128 v[244:247], v213 offset:32768
	v_mfma_f32_32x32x16_bf16 v[2:17], v[216:219], v[224:227], v[2:17]
	s_waitcnt lgkmcnt(1)
	v_mfma_f32_32x32x16_bf16 v[82:97], v[240:243], v[252:255], v[82:97]
	ds_read_b128 v[220:223], v208 offset:16384
	v_mfma_f32_32x32x16_bf16 v[66:81], v[236:239], v[252:255], v[66:81]
	ds_read_b128 v[232:235], v212 offset:24576
	v_mfma_f32_32x32x16_bf16 v[50:65], v[240:243], v[248:251], v[50:65]
	ds_read_b128 v[216:219], v208 offset:20480
	v_mfma_f32_32x32x16_bf16 v[34:49], v[236:239], v[248:251], v[34:49]
	ds_read_b128 v[228:231], v212 offset:28672
	s_waitcnt lgkmcnt(4)
	v_mfma_f32_32x32x16_bf16 v[18:33], v[240:243], v[244:247], v[18:33]
	ds_read_b128 v[224:227], v212 offset:32768
	v_mfma_f32_32x32x16_bf16 v[2:17], v[236:239], v[244:247], v[2:17]
	s_waitcnt vmcnt(0) lgkmcnt(0)
	s_barrier
	v_mfma_f32_32x32x16_bf16 v[82:97], v[220:223], v[232:235], v[82:97]
	v_mfma_f32_32x32x16_bf16 v[66:81], v[216:219], v[232:235], v[66:81]
	v_mfma_f32_32x32x16_bf16 v[50:65], v[220:223], v[228:231], v[50:65]
	v_mfma_f32_32x32x16_bf16 v[34:49], v[216:219], v[228:231], v[34:49]
	v_mfma_f32_32x32x16_bf16 v[18:33], v[220:223], v[224:227], v[18:33]
	v_mfma_f32_32x32x16_bf16 v[2:17], v[216:219], v[224:227], v[2:17]
	s_nop 7
	s_nop 7
	s_waitcnt lgkmcnt(0)
	v_add_u32_e32 v140, s4, v154
	v_add_u32_e32 v98, 0xfffff000, v140
	v_lshrrev_b32_e32 v98, 11, v98
	v_or_b32_e32 v138, s5, v162
	v_ashrrev_i32_e32 v141, 31, v140
	v_mul_u32_u24_e32 v98, 0x900, v98
	v_and_b32_e32 v139, 0x7ff, v140
	v_cmp_lt_i32_e64 s[6:7], s48, v140
	v_cmp_gt_i32_e64 s[8:9], s3, v140
	v_add3_u32 v139, v139, v98, s49
	v_mad_i64_i32 v[152:153], s[4:5], v140, s50, 0
	v_cmp_gt_i32_e64 s[10:11], s51, v138
	v_lshlrev_b64 v[142:143], 11, v[140:141]
	v_lshlrev_b64 v[144:145], 6, v[140:141]
	s_and_saveexec_b64 s[4:5], s[10:11]
	s_cbranch_execz .LBB0_656
	v_cmp_lt_i32_e32 vcc, s52, v138
	s_and_saveexec_b64 s[40:41], vcc
	s_xor_b64 s[40:41], exec, s[40:41]
	s_cbranch_execz .LBB0_654
	v_cmp_lt_u32_e32 vcc, s53, v138
	s_and_saveexec_b64 s[42:43], vcc
	s_xor_b64 s[42:43], exec, s[42:43]
	s_cbranch_execz .LBB0_632
	v_mul_f32_e32 v98, 0xbfb8aa3b, v82
	v_exp_f32_e32 v190, v98
	v_mul_f32_e32 v98, 0xbfb8aa3b, v83
	v_exp_f32_e32 v191, v98
	v_or_b32_e32 v98, v138, v104
	v_pk_add_f32 v[190:191], v[190:191], 1.0 op_sel_hi:[1,0]
	s_nop 0
	v_div_scale_f32 v141, s[44:45], v191, v191, v83
	v_rcp_f32_e32 v192, v141
	v_div_scale_f32 v193, vcc, v83, v191, v83
	v_fma_f32 v194, -v141, v192, 1.0
	v_fmac_f32_e32 v192, v194, v192
	v_mul_f32_e32 v194, v193, v192
	v_fma_f32 v195, -v141, v194, v193
	v_fmac_f32_e32 v194, v195, v192
	v_div_scale_f32 v195, s[44:45], v190, v190, v82
	v_rcp_f32_e32 v196, v195
	v_fma_f32 v141, -v141, v194, v193
	v_div_fmas_f32 v141, v141, v192, v194
	v_mul_f32_e32 v192, 0xbfb8aa3b, v84
	v_mul_f32_e32 v193, 0xbfb8aa3b, v85
	v_exp_f32_e32 v192, v192
	v_exp_f32_e32 v193, v193
	v_div_fixup_f32 v83, v141, v191, v83
	v_fma_f32 v141, -v195, v196, 1.0
	v_fmac_f32_e32 v196, v141, v196
	v_div_scale_f32 v141, vcc, v82, v190, v82
	v_mul_f32_e32 v191, v141, v196
	v_fma_f32 v194, -v195, v191, v141
	v_pk_add_f32 v[192:193], v[192:193], 1.0 op_sel_hi:[1,0]
	v_fmac_f32_e32 v191, v194, v196
	v_div_scale_f32 v194, s[44:45], v193, v193, v85
	v_fma_f32 v141, -v195, v191, v141
	v_rcp_f32_e32 v195, v194
	v_div_fmas_f32 v141, v141, v196, v191
	v_div_fixup_f32 v82, v141, v190, v82
	v_cvt_pk_bf16_f32 v190, v82, v83
	v_fma_f32 v82, -v194, v195, 1.0
	v_fmac_f32_e32 v195, v82, v195
	v_div_scale_f32 v82, vcc, v85, v193, v85
	v_mul_f32_e32 v83, v82, v195
	v_fma_f32 v141, -v194, v83, v82
	v_fmac_f32_e32 v83, v141, v195
	v_div_scale_f32 v141, s[44:45], v192, v192, v84
	v_rcp_f32_e32 v191, v141
	v_fma_f32 v82, -v194, v83, v82
	v_div_fmas_f32 v82, v82, v195, v83
	v_div_fixup_f32 v85, v82, v193, v85
	v_fma_f32 v82, -v141, v191, 1.0
	v_fmac_f32_e32 v191, v82, v191
	v_div_scale_f32 v82, vcc, v84, v192, v84
	v_mul_f32_e32 v193, v82, v191
	v_fma_f32 v83, -v141, v193, v82
	v_fmac_f32_e32 v193, v83, v191
	v_fma_f32 v141, -v141, v193, v82
	v_mul_f32_e32 v82, 0xbfb8aa3b, v86
	v_mul_f32_e32 v83, 0xbfb8aa3b, v87
	v_exp_f32_e32 v82, v82
	v_exp_f32_e32 v83, v83
	v_div_fmas_f32 v141, v141, v191, v193
	v_div_fixup_f32 v84, v141, v192, v84
	v_cvt_pk_bf16_f32 v191, v84, v85
	v_pk_add_f32 v[84:85], v[82:83], 1.0 op_sel_hi:[1,0]
	v_lshl_add_u64 v[82:83], s[14:15], 0, v[142:143]
	v_div_scale_f32 v141, s[44:45], v85, v85, v87
	v_rcp_f32_e32 v192, v141
	v_lshl_add_u64 v[82:83], v[98:99], 1, v[82:83]
	global_store_dwordx2 v[82:83], v[190:191], off offset:-1664
	v_fma_f32 v98, -v141, v192, 1.0
	v_fmac_f32_e32 v192, v98, v192
	v_div_scale_f32 v98, vcc, v87, v85, v87
	v_mul_f32_e32 v190, v98, v192
	v_fma_f32 v191, -v141, v190, v98
	v_fmac_f32_e32 v190, v191, v192
	v_fma_f32 v98, -v141, v190, v98
	v_div_scale_f32 v141, s[44:45], v84, v84, v86
	v_rcp_f32_e32 v193, v141
	v_div_fmas_f32 v98, v98, v192, v190
	v_mul_f32_e32 v190, 0xbfb8aa3b, v88
	v_mul_f32_e32 v191, 0xbfb8aa3b, v89
	v_div_fixup_f32 v85, v98, v85, v87
	v_fma_f32 v87, -v141, v193, 1.0
	v_exp_f32_e32 v190, v190
	v_exp_f32_e32 v191, v191
	v_fmac_f32_e32 v193, v87, v193
	v_div_scale_f32 v87, vcc, v86, v84, v86
	v_mul_f32_e32 v98, v87, v193
	v_fma_f32 v192, -v141, v98, v87
	v_fmac_f32_e32 v98, v192, v193
	v_pk_add_f32 v[190:191], v[190:191], 1.0 op_sel_hi:[1,0]
	v_fma_f32 v87, -v141, v98, v87
	v_div_scale_f32 v141, s[44:45], v191, v191, v89
	v_rcp_f32_e32 v192, v141
	v_div_fmas_f32 v87, v87, v193, v98
	v_div_fixup_f32 v84, v87, v84, v86
	v_cvt_pk_bf16_f32 v84, v84, v85
	v_fma_f32 v85, -v141, v192, 1.0
	v_fmac_f32_e32 v192, v85, v192
	v_div_scale_f32 v85, vcc, v89, v191, v89
	v_mul_f32_e32 v86, v85, v192
	v_fma_f32 v87, -v141, v86, v85
	v_fmac_f32_e32 v86, v87, v192
	v_div_scale_f32 v98, s[44:45], v190, v190, v88
	v_fma_f32 v85, -v141, v86, v85
	v_rcp_f32_e32 v141, v98
	v_div_fmas_f32 v85, v85, v192, v86
	v_div_fixup_f32 v85, v85, v191, v89
	v_div_scale_f32 v89, vcc, v88, v190, v88
	v_fma_f32 v86, -v98, v141, 1.0
	v_fmac_f32_e32 v141, v86, v141
	v_mul_f32_e32 v191, v89, v141
	v_fma_f32 v86, -v98, v191, v89
	v_fmac_f32_e32 v191, v86, v141
	v_mul_f32_e32 v86, 0xbfb8aa3b, v90
	v_mul_f32_e32 v87, 0xbfb8aa3b, v91
	v_exp_f32_e32 v86, v86
	v_exp_f32_e32 v87, v87
	v_fma_f32 v89, -v98, v191, v89
	v_div_fmas_f32 v89, v89, v141, v191
	v_div_fixup_f32 v88, v89, v190, v88
	v_pk_add_f32 v[86:87], v[86:87], 1.0 op_sel_hi:[1,0]
	v_cvt_pk_bf16_f32 v85, v88, v85
	v_div_scale_f32 v98, s[44:45], v87, v87, v91
	v_rcp_f32_e32 v141, v98
	global_store_dwordx2 v[82:83], v[84:85], off offset:-1648
	v_fma_f32 v84, -v98, v141, 1.0
	v_fmac_f32_e32 v141, v84, v141
	v_div_scale_f32 v84, vcc, v91, v87, v91
	v_mul_f32_e32 v85, v84, v141
	v_fma_f32 v88, -v98, v85, v84
	v_fmac_f32_e32 v85, v88, v141
	v_div_scale_f32 v88, s[44:45], v86, v86, v90
	v_rcp_f32_e32 v89, v88
	v_fma_f32 v84, -v98, v85, v84
	v_div_fmas_f32 v84, v84, v141, v85
	v_div_fixup_f32 v87, v84, v87, v91
	v_fma_f32 v84, -v88, v89, 1.0
	v_fmac_f32_e32 v89, v84, v89
	v_mul_f32_e32 v84, 0xbfb8aa3b, v92
	v_mul_f32_e32 v85, 0xbfb8aa3b, v93
	v_exp_f32_e32 v84, v84
	v_exp_f32_e32 v85, v85
	v_div_scale_f32 v91, vcc, v90, v86, v90
	v_mul_f32_e32 v98, v91, v89
	v_fma_f32 v141, -v88, v98, v91
	v_fmac_f32_e32 v98, v141, v89
	v_pk_add_f32 v[84:85], v[84:85], 1.0 op_sel_hi:[1,0]
	v_fma_f32 v88, -v88, v98, v91
	v_div_scale_f32 v91, s[44:45], v85, v85, v93
	v_rcp_f32_e32 v141, v91
	v_div_fmas_f32 v88, v88, v89, v98
	v_div_fixup_f32 v86, v88, v86, v90
	v_cvt_pk_bf16_f32 v86, v86, v87
	v_fma_f32 v87, -v91, v141, 1.0
	v_fmac_f32_e32 v141, v87, v141
	v_div_scale_f32 v87, vcc, v93, v85, v93
	v_mul_f32_e32 v88, v87, v141
	v_fma_f32 v89, -v91, v88, v87
	v_fmac_f32_e32 v88, v89, v141
	v_div_scale_f32 v90, s[44:45], v84, v84, v92
	v_fma_f32 v87, -v91, v88, v87
	v_rcp_f32_e32 v91, v90
	v_div_fmas_f32 v87, v87, v141, v88
	v_div_fixup_f32 v85, v87, v85, v93
	v_mul_f32_e32 v89, 0xbfb8aa3b, v95
	v_fma_f32 v87, -v90, v91, 1.0
	v_fmac_f32_e32 v91, v87, v91
	v_div_scale_f32 v87, vcc, v92, v84, v92
	v_mul_f32_e32 v93, v87, v91
	v_fma_f32 v88, -v90, v93, v87
	v_fmac_f32_e32 v93, v88, v91
	v_mul_f32_e32 v88, 0xbfb8aa3b, v94
	v_exp_f32_e32 v88, v88
	v_exp_f32_e32 v89, v89
	v_fma_f32 v87, -v90, v93, v87
	v_div_fmas_f32 v87, v87, v91, v93
	v_div_fixup_f32 v84, v87, v84, v92
	v_pk_add_f32 v[88:89], v[88:89], 1.0 op_sel_hi:[1,0]
	v_cvt_pk_bf16_f32 v87, v84, v85
	v_div_scale_f32 v90, s[44:45], v89, v89, v95
	v_rcp_f32_e32 v91, v90
	global_store_dwordx2 v[82:83], v[86:87], off offset:-1632
	v_fma_f32 v84, -v90, v91, 1.0
	v_fmac_f32_e32 v91, v84, v91
	v_div_scale_f32 v84, vcc, v95, v89, v95
	v_mul_f32_e32 v85, v84, v91
	v_fma_f32 v86, -v90, v85, v84
	v_fmac_f32_e32 v85, v86, v91
	v_div_scale_f32 v86, s[44:45], v88, v88, v94
	v_rcp_f32_e32 v87, v86
	v_fma_f32 v84, -v90, v85, v84
	v_div_fmas_f32 v84, v84, v91, v85
	v_div_fixup_f32 v89, v84, v89, v95
	v_fma_f32 v84, -v86, v87, 1.0
	v_fmac_f32_e32 v87, v84, v87
	v_mul_f32_e32 v84, 0xbfb8aa3b, v96
	v_mul_f32_e32 v85, 0xbfb8aa3b, v97
	v_exp_f32_e32 v84, v84
	v_exp_f32_e32 v85, v85
	v_div_scale_f32 v90, vcc, v94, v88, v94
	v_mul_f32_e32 v91, v90, v87
	v_fma_f32 v92, -v86, v91, v90
	v_fmac_f32_e32 v91, v92, v87
	v_pk_add_f32 v[84:85], v[84:85], 1.0 op_sel_hi:[1,0]
	v_fma_f32 v86, -v86, v91, v90
	v_div_scale_f32 v90, s[44:45], v85, v85, v97
	v_rcp_f32_e32 v92, v90
	v_div_fmas_f32 v86, v86, v87, v91
	v_div_fixup_f32 v86, v86, v88, v94
	v_cvt_pk_bf16_f32 v86, v86, v89
	v_fma_f32 v87, -v90, v92, 1.0
	v_fmac_f32_e32 v92, v87, v92
	v_div_scale_f32 v87, vcc, v97, v85, v97
	v_mul_f32_e32 v88, v87, v92
	v_fma_f32 v89, -v90, v88, v87
	v_fmac_f32_e32 v88, v89, v92
	v_div_scale_f32 v89, s[44:45], v84, v84, v96
	v_fma_f32 v87, -v90, v88, v87
	v_rcp_f32_e32 v90, v89
	v_div_fmas_f32 v87, v87, v92, v88
	v_div_fixup_f32 v85, v87, v85, v97
	v_fma_f32 v87, -v89, v90, 1.0
	v_fmac_f32_e32 v90, v87, v90
	v_div_scale_f32 v87, vcc, v96, v84, v96
	v_mul_f32_e32 v88, v87, v90
	v_fma_f32 v91, -v89, v88, v87
	v_fmac_f32_e32 v88, v91, v90
	v_fma_f32 v87, -v89, v88, v87
	v_div_fmas_f32 v87, v87, v90, v88
	v_div_fixup_f32 v84, v87, v84, v96
	v_cvt_pk_bf16_f32 v87, v84, v85
	global_store_dwordx2 v[82:83], v[86:87], off offset:-1616

.LBB0_1133:
	s_ashr_i32 s10, s28, 31
	s_lshr_b32 s10, s10, 26
	s_add_i32 s10, s28, s10
	s_ashr_i32 s31, s10, 6
	s_and_b32 s10, s10, 0x3ffffc0
	s_sub_i32 s29, s28, s10
	s_mulk_i32 s29, 0xc0
	v_add_u32_e32 v2, s29, v108
	s_lshr_b32 s10, s29, 6
	s_lshl_b32 s30, s31, 7
	v_ashrrev_i32_e32 v3, 31, v2
	s_add_i32 s10, s10, s31
	v_lshlrev_b64 v[2:3], 11, v[2:3]
	v_or_b32_e32 v4, s30, v108
	s_lshl_b32 s31, s10, 6
	s_lshl_b32 s10, s10, 7
	v_ashrrev_i32_e32 v5, 31, v4
	v_lshl_add_u64 v[104:105], v[100:101], 0, v[2:3]
	s_and_b32 s10, s10, 0x780
	v_readfirstlane_b32 s34, v109
	v_lshlrev_b64 v[4:5], 11, v[4:5]
	v_lshl_add_u64 v[2:3], v[104:105], 0, s[10:11]
	s_mov_b32 m0, s34
	v_readfirstlane_b32 s34, v128
	v_lshl_add_u64 v[106:107], v[102:103], 0, v[4:5]
	s_waitcnt vmcnt(0)
	s_barrier
	s_load_dwordx2 s[66:67], s[0:1], 0x128
	s_load_dwordx2 s[68:69], s[0:1], 0xf0
	v_and_b32_e32 v201, 0x3ff, v0
	v_readfirstlane_b32 s76, v0
	v_and_b32_e32 v200, 31, v201
	v_bfe_u32 v214, v201, 1, 3
	v_bfe_u32 v213, v201, 5, 1
	v_xor_b32_e32 v214, v214, v213
	v_lshlrev_b32_e32 v214, 4, v214
	s_and_b32 s76, s76, 0x3ff
	s_lshr_b32 s79, s76, 6
	s_lshl_b32 s76, s76, 4
	s_lshr_b32 s80, s79, 1
	s_and_b32 s79, s79, 1
	s_mul_i32 s80, s80, 0x3000
	s_lshl_b32 s79, s79, 13
	s_add_u32 s79, s79, 0xc000
	v_lshlrev_b32_e32 v200, 7, v200
	v_or_b32_e32 v200, v200, v214
	v_add_u32_e32 v215, s80, v200
	v_add_u32_e32 v211, s79, v200
	v_xor_b32_e32 v214, 0x20, v215
	v_xor_b32_e32 v210, 0x20, v211
	v_xor_b32_e32 v213, 0x40, v215
	v_xor_b32_e32 v209, 0x40, v211
	v_xor_b32_e32 v212, 0x60, v215
	v_xor_b32_e32 v208, 0x60, v211
	v_bfe_u32 v200, v201, 4, 3
	v_and_b32_e32 v206, 7, v201
	v_xor_b32_e32 v200, v200, v206
	v_lshlrev_b32_e32 v200, 4, v200
	v_lshrrev_b32_e32 v206, 3, v201
	v_lshl_or_b32 v207, v206, 11, v200
	v_add_u32_e32 v206, 0x10000, v207
	v_add_u32_e32 v205, 0x20000, v207
	v_add_u32_e32 v204, 0x30000, v207
	v_add_u32_e32 v203, 0x40000, v207
	v_add_u32_e32 v202, 0x50000, v207
	s_lshr_b32 s79, s28, 6
	s_and_b32 s80, s28, 63
	s_mov_b32 s75, 0
	s_mul_i32 s80, s80, 0x60000
	s_lshl_b32 s79, s79, 18
	s_waitcnt lgkmcnt(0)
	s_add_u32 s66, s66, s80
	s_addc_u32 s67, s67, 0
	s_add_u32 s68, s68, s79
	s_addc_u32 s69, s69, 0
	s_add_u32 s79, s75, 0
	s_and_b32 s79, s79, 15
	s_lshl_b32 s79, s79, 7
	s_add_u32 s70, s66, s79
	s_addc_u32 s71, s67, 0
	s_add_u32 s72, s68, s79
	s_addc_u32 s73, s69, 0
	s_add_u32 s77, s76, 0x0
	s_add_u32 s78, s76, 0xc000
	s_add_u32 m0, s77, 0x0
	s_nop 0
	global_load_lds_dwordx4 v207, s[70:71]
	s_add_u32 m0, s77, 0x1000
	s_nop 0
	global_load_lds_dwordx4 v206, s[70:71]
	s_add_u32 m0, s77, 0x2000
	s_nop 0
	global_load_lds_dwordx4 v205, s[70:71]
	s_add_u32 m0, s77, 0x3000
	s_nop 0
	global_load_lds_dwordx4 v204, s[70:71]
	s_add_u32 m0, s77, 0x4000
	s_nop 0
	global_load_lds_dwordx4 v203, s[70:71]
	s_add_u32 m0, s77, 0x5000
	s_nop 0
	global_load_lds_dwordx4 v202, s[70:71]
	s_add_u32 m0, s78, 0x0
	s_nop 0
	global_load_lds_dwordx4 v207, s[72:73]
	s_add_u32 m0, s78, 0x1000
	s_nop 0
	global_load_lds_dwordx4 v206, s[72:73]
	s_add_u32 m0, s78, 0x2000
	s_nop 0
	global_load_lds_dwordx4 v205, s[72:73]
	s_add_u32 m0, s78, 0x3000
	s_nop 0
	global_load_lds_dwordx4 v204, s[72:73]
	s_add_u32 s79, s75, 1
	s_and_b32 s79, s79, 15
	s_lshl_b32 s79, s79, 7
	s_add_u32 s70, s66, s79
	s_addc_u32 s71, s67, 0
	s_add_u32 s72, s68, s79
	s_addc_u32 s73, s69, 0
	s_add_u32 s77, s76, 0x6000
	s_add_u32 s78, s76, 0x10000
	s_add_u32 m0, s77, 0x0
	s_nop 0
	global_load_lds_dwordx4 v207, s[70:71]
	s_add_u32 m0, s77, 0x1000
	s_nop 0
	global_load_lds_dwordx4 v206, s[70:71]
	s_add_u32 m0, s77, 0x2000
	s_nop 0
	global_load_lds_dwordx4 v205, s[70:71]
	s_add_u32 m0, s77, 0x3000
	s_nop 0
	global_load_lds_dwordx4 v204, s[70:71]
	s_add_u32 m0, s77, 0x4000
	s_nop 0
	global_load_lds_dwordx4 v203, s[70:71]
	s_add_u32 m0, s77, 0x5000
	s_nop 0
	global_load_lds_dwordx4 v202, s[70:71]
	s_add_u32 m0, s78, 0x0
	s_nop 0
	global_load_lds_dwordx4 v207, s[72:73]
	s_add_u32 m0, s78, 0x1000
	s_nop 0
	global_load_lds_dwordx4 v206, s[72:73]
	s_add_u32 m0, s78, 0x2000
	s_nop 0
	global_load_lds_dwordx4 v205, s[72:73]
	s_add_u32 m0, s78, 0x3000
	s_nop 0
	global_load_lds_dwordx4 v204, s[72:73]
	v_mov_b32_e32 v2, 0
	v_mov_b32_e32 v3, 0
	v_mov_b32_e32 v4, 0
	v_mov_b32_e32 v5, 0
	v_mov_b32_e32 v6, 0
	v_mov_b32_e32 v7, 0
	v_mov_b32_e32 v8, 0
	v_mov_b32_e32 v9, 0
	v_mov_b32_e32 v10, 0
	v_mov_b32_e32 v11, 0
	v_mov_b32_e32 v12, 0
	v_mov_b32_e32 v13, 0
	v_mov_b32_e32 v14, 0
	v_mov_b32_e32 v15, 0
	v_mov_b32_e32 v16, 0
	v_mov_b32_e32 v17, 0
	v_mov_b32_e32 v18, 0
	v_mov_b32_e32 v19, 0
	v_mov_b32_e32 v20, 0
	v_mov_b32_e32 v21, 0
	v_mov_b32_e32 v22, 0
	v_mov_b32_e32 v23, 0
	v_mov_b32_e32 v24, 0
	v_mov_b32_e32 v25, 0
	v_mov_b32_e32 v26, 0
	v_mov_b32_e32 v27, 0
	v_mov_b32_e32 v28, 0
	v_mov_b32_e32 v29, 0
	v_mov_b32_e32 v30, 0
	v_mov_b32_e32 v31, 0
	v_mov_b32_e32 v32, 0
	v_mov_b32_e32 v33, 0
	v_mov_b32_e32 v34, 0
	v_mov_b32_e32 v35, 0
	v_mov_b32_e32 v36, 0
	v_mov_b32_e32 v37, 0
	v_mov_b32_e32 v38, 0
	v_mov_b32_e32 v39, 0
	v_mov_b32_e32 v40, 0
	v_mov_b32_e32 v41, 0
	v_mov_b32_e32 v42, 0
	v_mov_b32_e32 v43, 0
	v_mov_b32_e32 v44, 0
	v_mov_b32_e32 v45, 0
	v_mov_b32_e32 v46, 0
	v_mov_b32_e32 v47, 0
	v_mov_b32_e32 v48, 0
	v_mov_b32_e32 v49, 0
	v_mov_b32_e32 v50, 0
	v_mov_b32_e32 v51, 0
	v_mov_b32_e32 v52, 0
	v_mov_b32_e32 v53, 0
	v_mov_b32_e32 v54, 0
	v_mov_b32_e32 v55, 0
	v_mov_b32_e32 v56, 0
	v_mov_b32_e32 v57, 0
	v_mov_b32_e32 v58, 0
	v_mov_b32_e32 v59, 0
	v_mov_b32_e32 v60, 0
	v_mov_b32_e32 v61, 0
	v_mov_b32_e32 v62, 0
	v_mov_b32_e32 v63, 0
	v_mov_b32_e32 v64, 0
	v_mov_b32_e32 v65, 0
	v_mov_b32_e32 v66, 0
	v_mov_b32_e32 v67, 0
	v_mov_b32_e32 v68, 0
	v_mov_b32_e32 v69, 0
	v_mov_b32_e32 v70, 0
	v_mov_b32_e32 v71, 0
	v_mov_b32_e32 v72, 0
	v_mov_b32_e32 v73, 0
	v_mov_b32_e32 v74, 0
	v_mov_b32_e32 v75, 0
	v_mov_b32_e32 v76, 0
	v_mov_b32_e32 v77, 0
	v_mov_b32_e32 v78, 0
	v_mov_b32_e32 v79, 0
	v_mov_b32_e32 v80, 0
	v_mov_b32_e32 v81, 0
	v_mov_b32_e32 v82, 0
	v_mov_b32_e32 v83, 0
	v_mov_b32_e32 v84, 0
	v_mov_b32_e32 v85, 0
	v_mov_b32_e32 v86, 0
	v_mov_b32_e32 v87, 0
	v_mov_b32_e32 v88, 0
	v_mov_b32_e32 v89, 0
	v_mov_b32_e32 v90, 0
	v_mov_b32_e32 v91, 0
	v_mov_b32_e32 v92, 0
	v_mov_b32_e32 v93, 0
	v_mov_b32_e32 v94, 0
	v_mov_b32_e32 v95, 0
	v_mov_b32_e32 v96, 0
	v_mov_b32_e32 v97, 0
	s_waitcnt vmcnt(10)
	s_barrier
	ds_read_b128 v[240:243], v211 offset:0
	ds_read_b128 v[252:255], v215 offset:0
	ds_read_b128 v[236:239], v211 offset:4096
	ds_read_b128 v[248:251], v215 offset:4096
	ds_read_b128 v[244:247], v215 offset:8192
	s_mov_b32 s74, 0
.Lgm_ph11_loop:
	s_waitcnt lgkmcnt(1)
	v_mfma_f32_32x32x16_bf16 v[82:97], v[240:243], v[252:255], v[82:97]
	ds_read_b128 v[220:223], v210 offset:0
	v_mfma_f32_32x32x16_bf16 v[66:81], v[236:239], v[252:255], v[66:81]
	ds_read_b128 v[232:235], v214 offset:0
	v_mfma_f32_32x32x16_bf16 v[50:65], v[240:243], v[248:251], v[50:65]
	ds_read_b128 v[216:219], v210 offset:4096
	v_mfma_f32_32x32x16_bf16 v[34:49], v[236:239], v[248:251], v[34:49]
	ds_read_b128 v[228:231], v214 offset:4096
	s_waitcnt lgkmcnt(4)
	v_mfma_f32_32x32x16_bf16 v[18:33], v[240:243], v[244:247], v[18:33]
	ds_read_b128 v[224:227], v214 offset:8192
	v_mfma_f32_32x32x16_bf16 v[2:17], v[236:239], v[244:247], v[2:17]
	s_waitcnt lgkmcnt(1)
	v_mfma_f32_32x32x16_bf16 v[82:97], v[220:223], v[232:235], v[82:97]
	ds_read_b128 v[240:243], v209 offset:0
	v_mfma_f32_32x32x16_bf16 v[66:81], v[216:219], v[232:235], v[66:81]
	ds_read_b128 v[252:255], v213 offset:0
	v_mfma_f32_32x32x16_bf16 v[50:65], v[220:223], v[228:231], v[50:65]
	ds_read_b128 v[236:239], v209 offset:4096
	v_mfma_f32_32x32x16_bf16 v[34:49], v[216:219], v[228:231], v[34:49]
	ds_read_b128 v[248:251], v213 offset:4096
	s_waitcnt lgkmcnt(4)
	v_mfma_f32_32x32x16_bf16 v[18:33], v[220:223], v[224:227], v[18:33]
	ds_read_b128 v[244:247], v213 offset:8192
	v_mfma_f32_32x32x16_bf16 v[2:17], v[216:219], v[224:227], v[2:17]
	s_waitcnt lgkmcnt(1)
	v_mfma_f32_32x32x16_bf16 v[82:97], v[240:243], v[252:255], v[82:97]
	ds_read_b128 v[220:223], v208 offset:0
	s_add_u32 s79, s75, s74
	s_add_u32 s79, s79, 2
	s_and_b32 s79, s79, 15
	v_mfma_f32_32x32x16_bf16 v[66:81], v[236:239], v[252:255], v[66:81]
	ds_read_b128 v[232:235], v212 offset:0
	s_lshl_b32 s79, s79, 7
	s_add_u32 s70, s66, s79
	v_mfma_f32_32x32x16_bf16 v[50:65], v[240:243], v[248:251], v[50:65]
	ds_read_b128 v[216:219], v208 offset:4096
	s_addc_u32 s71, s67, 0
	s_add_u32 s72, s68, s79
	v_mfma_f32_32x32x16_bf16 v[34:49], v[236:239], v[248:251], v[34:49]
	ds_read_b128 v[228:231], v212 offset:4096
	s_addc_u32 s73, s69, 0
	s_add_u32 s77, s76, 0x0
	s_add_u32 s78, s76, 0xc000
	s_waitcnt lgkmcnt(4)
	v_mfma_f32_32x32x16_bf16 v[18:33], v[240:243], v[244:247], v[18:33]
	ds_read_b128 v[224:227], v212 offset:8192
	v_mfma_f32_32x32x16_bf16 v[2:17], v[236:239], v[244:247], v[2:17]
	s_waitcnt vmcnt(0) lgkmcnt(0)
	s_barrier
	v_mfma_f32_32x32x16_bf16 v[82:97], v[220:223], v[232:235], v[82:97]
	s_add_u32 m0, s77, 0x0
	ds_read_b128 v[240:243], v211 offset:16384
	global_load_lds_dwordx4 v207, s[70:71]
	s_add_u32 m0, s77, 0x1000
	s_nop 0
	global_load_lds_dwordx4 v206, s[70:71]
	v_mfma_f32_32x32x16_bf16 v[66:81], v[216:219], v[232:235], v[66:81]
	s_add_u32 m0, s77, 0x2000
	ds_read_b128 v[252:255], v215 offset:24576
	global_load_lds_dwordx4 v205, s[70:71]
	s_add_u32 m0, s77, 0x3000
	s_nop 0
	global_load_lds_dwordx4 v204, s[70:71]
	v_mfma_f32_32x32x16_bf16 v[50:65], v[220:223], v[228:231], v[50:65]
	s_add_u32 m0, s77, 0x4000
	ds_read_b128 v[236:239], v211 offset:20480
	global_load_lds_dwordx4 v203, s[70:71]
	s_add_u32 m0, s77, 0x5000
	s_nop 0
	global_load_lds_dwordx4 v202, s[70:71]
	v_mfma_f32_32x32x16_bf16 v[34:49], v[216:219], v[228:231], v[34:49]
	s_add_u32 m0, s78, 0x0
	ds_read_b128 v[248:251], v215 offset:28672
	global_load_lds_dwordx4 v207, s[72:73]
	s_add_u32 m0, s78, 0x1000
	s_nop 0
	global_load_lds_dwordx4 v206, s[72:73]
	v_mfma_f32_32x32x16_bf16 v[18:33], v[220:223], v[224:227], v[18:33]
	s_add_u32 m0, s78, 0x2000
	ds_read_b128 v[244:247], v215 offset:32768
	global_load_lds_dwordx4 v205, s[72:73]
	s_add_u32 m0, s78, 0x3000
	s_nop 0
	global_load_lds_dwordx4 v204, s[72:73]
	v_mfma_f32_32x32x16_bf16 v[2:17], v[216:219], v[224:227], v[2:17]
	s_waitcnt lgkmcnt(1)
	v_mfma_f32_32x32x16_bf16 v[82:97], v[240:243], v[252:255], v[82:97]
	ds_read_b128 v[220:223], v210 offset:16384
	v_mfma_f32_32x32x16_bf16 v[66:81], v[236:239], v[252:255], v[66:81]
	ds_read_b128 v[232:235], v214 offset:24576
	v_mfma_f32_32x32x16_bf16 v[50:65], v[240:243], v[248:251], v[50:65]
	ds_read_b128 v[216:219], v210 offset:20480
	v_mfma_f32_32x32x16_bf16 v[34:49], v[236:239], v[248:251], v[34:49]
	ds_read_b128 v[228:231], v214 offset:28672
	s_waitcnt lgkmcnt(4)
	v_mfma_f32_32x32x16_bf16 v[18:33], v[240:243], v[244:247], v[18:33]
	ds_read_b128 v[224:227], v214 offset:32768
	v_mfma_f32_32x32x16_bf16 v[2:17], v[236:239], v[244:247], v[2:17]
	s_waitcnt lgkmcnt(1)
	v_mfma_f32_32x32x16_bf16 v[82:97], v[220:223], v[232:235], v[82:97]
	ds_read_b128 v[240:243], v209 offset:16384
	v_mfma_f32_32x32x16_bf16 v[66:81], v[216:219], v[232:235], v[66:81]
	ds_read_b128 v[252:255], v213 offset:24576
	v_mfma_f32_32x32x16_bf16 v[50:65], v[220:223], v[228:231], v[50:65]
	ds_read_b128 v[236:239], v209 offset:20480
	v_mfma_f32_32x32x16_bf16 v[34:49], v[216:219], v[228:231], v[34:49]
	ds_read_b128 v[248:251], v213 offset:28672
	s_waitcnt lgkmcnt(4)
	v_mfma_f32_32x32x16_bf16 v[18:33], v[220:223], v[224:227], v[18:33]
	ds_read_b128 v[244:247], v213 offset:32768
	v_mfma_f32_32x32x16_bf16 v[2:17], v[216:219], v[224:227], v[2:17]
	s_waitcnt lgkmcnt(1)
	v_mfma_f32_32x32x16_bf16 v[82:97], v[240:243], v[252:255], v[82:97]
	ds_read_b128 v[220:223], v208 offset:16384
	s_add_u32 s79, s75, s74
	s_add_u32 s79, s79, 3
	s_and_b32 s79, s79, 15
	v_mfma_f32_32x32x16_bf16 v[66:81], v[236:239], v[252:255], v[66:81]
	ds_read_b128 v[232:235], v212 offset:24576
	s_lshl_b32 s79, s79, 7
	s_add_u32 s70, s66, s79
	v_mfma_f32_32x32x16_bf16 v[50:65], v[240:243], v[248:251], v[50:65]
	ds_read_b128 v[216:219], v208 offset:20480
	s_addc_u32 s71, s67, 0
	s_add_u32 s72, s68, s79
	v_mfma_f32_32x32x16_bf16 v[34:49], v[236:239], v[248:251], v[34:49]
	ds_read_b128 v[228:231], v212 offset:28672
	s_addc_u32 s73, s69, 0
	s_add_u32 s77, s76, 0x6000
	s_add_u32 s78, s76, 0x10000
	s_waitcnt lgkmcnt(4)
	v_mfma_f32_32x32x16_bf16 v[18:33], v[240:243], v[244:247], v[18:33]
	ds_read_b128 v[224:227], v212 offset:32768
	v_mfma_f32_32x32x16_bf16 v[2:17], v[236:239], v[244:247], v[2:17]
	s_waitcnt vmcnt(0) lgkmcnt(0)
	s_barrier
	v_mfma_f32_32x32x16_bf16 v[82:97], v[220:223], v[232:235], v[82:97]
	s_add_u32 m0, s77, 0x0
	ds_read_b128 v[240:243], v211 offset:0
	global_load_lds_dwordx4 v207, s[70:71]
	s_add_u32 m0, s77, 0x1000
	s_nop 0
	global_load_lds_dwordx4 v206, s[70:71]
	v_mfma_f32_32x32x16_bf16 v[66:81], v[216:219], v[232:235], v[66:81]
	s_add_u32 m0, s77, 0x2000
	ds_read_b128 v[252:255], v215 offset:0
	global_load_lds_dwordx4 v205, s[70:71]
	s_add_u32 m0, s77, 0x3000
	s_nop 0
	global_load_lds_dwordx4 v204, s[70:71]
	v_mfma_f32_32x32x16_bf16 v[50:65], v[220:223], v[228:231], v[50:65]
	s_add_u32 m0, s77, 0x4000
	ds_read_b128 v[236:239], v211 offset:4096
	global_load_lds_dwordx4 v203, s[70:71]
	s_add_u32 m0, s77, 0x5000
	s_nop 0
	global_load_lds_dwordx4 v202, s[70:71]
	v_mfma_f32_32x32x16_bf16 v[34:49], v[216:219], v[228:231], v[34:49]
	s_add_u32 m0, s78, 0x0
	ds_read_b128 v[248:251], v215 offset:4096
	global_load_lds_dwordx4 v207, s[72:73]
	s_add_u32 m0, s78, 0x1000
	s_nop 0
	global_load_lds_dwordx4 v206, s[72:73]
	v_mfma_f32_32x32x16_bf16 v[18:33], v[220:223], v[224:227], v[18:33]
	s_add_u32 m0, s78, 0x2000
	ds_read_b128 v[244:247], v215 offset:8192
	global_load_lds_dwordx4 v205, s[72:73]
	s_add_u32 m0, s78, 0x3000
	s_nop 0
	global_load_lds_dwordx4 v204, s[72:73]
	v_mfma_f32_32x32x16_bf16 v[2:17], v[216:219], v[224:227], v[2:17]
	s_add_u32 s74, s74, 2
	s_cmp_lt_u32 s74, 14
	s_cbranch_scc1 .Lgm_ph11_loop
	s_waitcnt lgkmcnt(1)
	v_mfma_f32_32x32x16_bf16 v[82:97], v[240:243], v[252:255], v[82:97]
	ds_read_b128 v[220:223], v210 offset:0
	v_mfma_f32_32x32x16_bf16 v[66:81], v[236:239], v[252:255], v[66:81]
	ds_read_b128 v[232:235], v214 offset:0
	v_mfma_f32_32x32x16_bf16 v[50:65], v[240:243], v[248:251], v[50:65]
	ds_read_b128 v[216:219], v210 offset:4096
	v_mfma_f32_32x32x16_bf16 v[34:49], v[236:239], v[248:251], v[34:49]
	ds_read_b128 v[228:231], v214 offset:4096
	s_waitcnt lgkmcnt(4)
	v_mfma_f32_32x32x16_bf16 v[18:33], v[240:243], v[244:247], v[18:33]
	ds_read_b128 v[224:227], v214 offset:8192
	v_mfma_f32_32x32x16_bf16 v[2:17], v[236:239], v[244:247], v[2:17]
	s_waitcnt lgkmcnt(1)
	v_mfma_f32_32x32x16_bf16 v[82:97], v[220:223], v[232:235], v[82:97]
	ds_read_b128 v[240:243], v209 offset:0
	v_mfma_f32_32x32x16_bf16 v[66:81], v[216:219], v[232:235], v[66:81]
	ds_read_b128 v[252:255], v213 offset:0
	v_mfma_f32_32x32x16_bf16 v[50:65], v[220:223], v[228:231], v[50:65]
	ds_read_b128 v[236:239], v209 offset:4096
	v_mfma_f32_32x32x16_bf16 v[34:49], v[216:219], v[228:231], v[34:49]
	ds_read_b128 v[248:251], v213 offset:4096
	s_waitcnt lgkmcnt(4)
	v_mfma_f32_32x32x16_bf16 v[18:33], v[220:223], v[224:227], v[18:33]
	ds_read_b128 v[244:247], v213 offset:8192
	v_mfma_f32_32x32x16_bf16 v[2:17], v[216:219], v[224:227], v[2:17]
	s_waitcnt lgkmcnt(1)
	v_mfma_f32_32x32x16_bf16 v[82:97], v[240:243], v[252:255], v[82:97]
	ds_read_b128 v[220:223], v208 offset:0
	v_mfma_f32_32x32x16_bf16 v[66:81], v[236:239], v[252:255], v[66:81]
	ds_read_b128 v[232:235], v212 offset:0
	v_mfma_f32_32x32x16_bf16 v[50:65], v[240:243], v[248:251], v[50:65]
	ds_read_b128 v[216:219], v208 offset:4096
	v_mfma_f32_32x32x16_bf16 v[34:49], v[236:239], v[248:251], v[34:49]
	ds_read_b128 v[228:231], v212 offset:4096
	s_waitcnt lgkmcnt(4)
	v_mfma_f32_32x32x16_bf16 v[18:33], v[240:243], v[244:247], v[18:33]
	ds_read_b128 v[224:227], v212 offset:8192
	v_mfma_f32_32x32x16_bf16 v[2:17], v[236:239], v[244:247], v[2:17]
	s_waitcnt vmcnt(0) lgkmcnt(0)
	s_barrier
	v_mfma_f32_32x32x16_bf16 v[82:97], v[220:223], v[232:235], v[82:97]
	ds_read_b128 v[240:243], v211 offset:16384
	v_mfma_f32_32x32x16_bf16 v[66:81], v[216:219], v[232:235], v[66:81]
	ds_read_b128 v[252:255], v215 offset:24576
	v_mfma_f32_32x32x16_bf16 v[50:65], v[220:223], v[228:231], v[50:65]
	ds_read_b128 v[236:239], v211 offset:20480
	v_mfma_f32_32x32x16_bf16 v[34:49], v[216:219], v[228:231], v[34:49]
	ds_read_b128 v[248:251], v215 offset:28672
	v_mfma_f32_32x32x16_bf16 v[18:33], v[220:223], v[224:227], v[18:33]
	ds_read_b128 v[244:247], v215 offset:32768
	v_mfma_f32_32x32x16_bf16 v[2:17], v[216:219], v[224:227], v[2:17]
	s_waitcnt lgkmcnt(1)
	v_mfma_f32_32x32x16_bf16 v[82:97], v[240:243], v[252:255], v[82:97]
	ds_read_b128 v[220:223], v210 offset:16384
	v_mfma_f32_32x32x16_bf16 v[66:81], v[236:239], v[252:255], v[66:81]
	ds_read_b128 v[232:235], v214 offset:24576
	v_mfma_f32_32x32x16_bf16 v[50:65], v[240:243], v[248:251], v[50:65]
	ds_read_b128 v[216:219], v210 offset:20480
	v_mfma_f32_32x32x16_bf16 v[34:49], v[236:239], v[248:251], v[34:49]
	ds_read_b128 v[228:231], v214 offset:28672
	s_waitcnt lgkmcnt(4)
	v_mfma_f32_32x32x16_bf16 v[18:33], v[240:243], v[244:247], v[18:33]
	ds_read_b128 v[224:227], v214 offset:32768
	v_mfma_f32_32x32x16_bf16 v[2:17], v[236:239], v[244:247], v[2:17]
	s_waitcnt lgkmcnt(1)
	v_mfma_f32_32x32x16_bf16 v[82:97], v[220:223], v[232:235], v[82:97]
	ds_read_b128 v[240:243], v209 offset:16384
	v_mfma_f32_32x32x16_bf16 v[66:81], v[216:219], v[232:235], v[66:81]
	ds_read_b128 v[252:255], v213 offset:24576
	v_mfma_f32_32x32x16_bf16 v[50:65], v[220:223], v[228:231], v[50:65]
	ds_read_b128 v[236:239], v209 offset:20480
	v_mfma_f32_32x32x16_bf16 v[34:49], v[216:219], v[228:231], v[34:49]
	ds_read_b128 v[248:251], v213 offset:28672
	s_waitcnt lgkmcnt(4)
	v_mfma_f32_32x32x16_bf16 v[18:33], v[220:223], v[224:227], v[18:33]
	ds_read_b128 v[244:247], v213 offset:32768
	v_mfma_f32_32x32x16_bf16 v[2:17], v[216:219], v[224:227], v[2:17]
	s_waitcnt lgkmcnt(1)
	v_mfma_f32_32x32x16_bf16 v[82:97], v[240:243], v[252:255], v[82:97]
	ds_read_b128 v[220:223], v208 offset:16384
	v_mfma_f32_32x32x16_bf16 v[66:81], v[236:239], v[252:255], v[66:81]
	ds_read_b128 v[232:235], v212 offset:24576
	v_mfma_f32_32x32x16_bf16 v[50:65], v[240:243], v[248:251], v[50:65]
	ds_read_b128 v[216:219], v208 offset:20480
	v_mfma_f32_32x32x16_bf16 v[34:49], v[236:239], v[248:251], v[34:49]
	ds_read_b128 v[228:231], v212 offset:28672
	s_waitcnt lgkmcnt(4)
	v_mfma_f32_32x32x16_bf16 v[18:33], v[240:243], v[244:247], v[18:33]
	ds_read_b128 v[224:227], v212 offset:32768
	v_mfma_f32_32x32x16_bf16 v[2:17], v[236:239], v[244:247], v[2:17]
	s_waitcnt vmcnt(0) lgkmcnt(0)
	s_barrier
	v_mfma_f32_32x32x16_bf16 v[82:97], v[220:223], v[232:235], v[82:97]
	v_mfma_f32_32x32x16_bf16 v[66:81], v[216:219], v[232:235], v[66:81]
	v_mfma_f32_32x32x16_bf16 v[50:65], v[220:223], v[228:231], v[50:65]
	v_mfma_f32_32x32x16_bf16 v[34:49], v[216:219], v[228:231], v[34:49]
	v_mfma_f32_32x32x16_bf16 v[18:33], v[220:223], v[224:227], v[18:33]
	v_mfma_f32_32x32x16_bf16 v[2:17], v[216:219], v[224:227], v[2:17]
	s_nop 7
	s_nop 7
	s_waitcnt lgkmcnt(0)
	s_nop 10
	ds_write_b128 v147, v[82:85]
	ds_write_b128 v147, v[86:89] offset:32
	ds_write_b128 v147, v[90:93] offset:64
	ds_write_b128 v147, v[94:97] offset:96
	ds_write_b128 v147, v[66:69] offset:128
	ds_write_b128 v147, v[70:73] offset:160
	ds_write_b128 v147, v[74:77] offset:192
	ds_write_b128 v147, v[78:81] offset:224
	s_waitcnt lgkmcnt(0)
	v_add_u32_e32 v104, s29, v111
	v_add_u32_e32 v67, 0xfffff000, v104
	v_or_b32_e32 v66, v104, v119
	v_lshrrev_b32_e32 v67, 11, v67
	v_or_b32_e32 v106, s30, v120
	v_mad_u32_u24 v80, v67, s26, s26
	v_cmp_lt_i32_e32 vcc, s27, v66
	v_ashrrev_i32_e32 v107, 31, v106
	v_lshlrev_b64 v[68:69], 2, v[106:107]
	v_cndmask_b32_e32 v98, 0, v80, vcc
	v_lshl_add_u64 v[70:71], v[98:99], 2, s[6:7]
	v_lshl_add_u64 v[74:75], v[70:71], 0, v[68:69]
	v_add_co_u32_e32 v74, vcc, s3, v74
	ds_read_b128 v[70:73], v149
	s_nop 0
	v_addc_co_u32_e32 v75, vcc, 0, v75, vcc
	global_load_dwordx4 v[74:77], v[74:75], off
	v_ashrrev_i32_e32 v67, 31, v66
	v_lshlrev_b64 v[66:67], 11, v[66:67]
	v_or_b32_e32 v78, v104, v121
	v_cmp_lt_i32_e32 vcc, s27, v78
	v_ashrrev_i32_e32 v79, 31, v78
	v_cndmask_b32_e32 v98, 0, v80, vcc
	s_waitcnt vmcnt(0) lgkmcnt(0)
	v_mul_f32_e64 v70, v70, v74
	v_mul_f32_e64 v71, v71, v75
	v_mul_f32_e64 v72, v72, v76
	v_mul_f32_e64 v73, v73, v77
	v_cvt_pk_bf16_f32 v70, v70, v71
	v_cvt_pk_bf16_f32 v71, v72, v73
	v_lshl_add_u64 v[72:73], s[4:5], 0, v[66:67]
	v_lshlrev_b64 v[66:67], 1, v[106:107]
	v_lshl_add_u64 v[72:73], v[72:73], 0, v[66:67]
	global_store_dwordx2 v[72:73], v[70:71], off
	v_lshl_add_u64 v[70:71], v[98:99], 2, s[6:7]
	v_lshl_add_u64 v[74:75], v[70:71], 0, v[68:69]
	v_add_co_u32_e32 v74, vcc, s3, v74
	ds_read_b128 v[70:73], v149 offset:1088
	s_nop 0
	v_addc_co_u32_e32 v75, vcc, 0, v75, vcc
	global_load_dwordx4 v[74:77], v[74:75], off
	s_waitcnt vmcnt(0) lgkmcnt(0)
	v_mul_f32_e64 v70, v70, v74
	v_mul_f32_e64 v71, v71, v75
	v_mul_f32_e64 v72, v72, v76
	v_mul_f32_e64 v73, v73, v77
	v_cvt_pk_bf16_f32 v70, v70, v71
	v_cvt_pk_bf16_f32 v71, v72, v73
	v_lshlrev_b64 v[72:73], 11, v[78:79]
	v_or_b32_e32 v78, v104, v122
	v_lshl_add_u64 v[72:73], s[4:5], 0, v[72:73]
	v_cmp_lt_i32_e32 vcc, s27, v78
	v_lshl_add_u64 v[72:73], v[72:73], 0, v[66:67]
	global_store_dwordx2 v[72:73], v[70:71], off
	v_cndmask_b32_e32 v98, 0, v80, vcc
	v_lshl_add_u64 v[70:71], v[98:99], 2, s[6:7]
	v_lshl_add_u64 v[74:75], v[70:71], 0, v[68:69]
	v_add_co_u32_e32 v74, vcc, s3, v74
	ds_read_b128 v[70:73], v149 offset:2176
	s_nop 0
	v_addc_co_u32_e32 v75, vcc, 0, v75, vcc
	global_load_dwordx4 v[74:77], v[74:75], off
	v_ashrrev_i32_e32 v79, 31, v78
	s_waitcnt vmcnt(0) lgkmcnt(0)
	v_mul_f32_e64 v70, v70, v74
	v_mul_f32_e64 v71, v71, v75
	v_mul_f32_e64 v72, v72, v76
	v_mul_f32_e64 v73, v73, v77
	v_cvt_pk_bf16_f32 v70, v70, v71
	v_cvt_pk_bf16_f32 v71, v72, v73
	v_lshlrev_b64 v[72:73], 11, v[78:79]
	v_or_b32_e32 v78, v104, v123
	v_lshl_add_u64 v[72:73], s[4:5], 0, v[72:73]
	v_cmp_lt_i32_e32 vcc, s27, v78
	v_lshl_add_u64 v[72:73], v[72:73], 0, v[66:67]
	global_store_dwordx2 v[72:73], v[70:71], off
	v_cndmask_b32_e32 v98, 0, v80, vcc
	v_lshl_add_u64 v[70:71], v[98:99], 2, s[6:7]
	v_lshl_add_u64 v[74:75], v[70:71], 0, v[68:69]
	v_add_co_u32_e32 v74, vcc, s3, v74
	ds_read_b128 v[70:73], v149 offset:3264
	s_nop 0
	v_addc_co_u32_e32 v75, vcc, 0, v75, vcc
	global_load_dwordx4 v[74:77], v[74:75], off
	v_ashrrev_i32_e32 v79, 31, v78
	s_waitcnt vmcnt(0) lgkmcnt(0)
	v_mul_f32_e64 v70, v70, v74
	v_mul_f32_e64 v71, v71, v75
	v_mul_f32_e64 v72, v72, v76
	v_mul_f32_e64 v73, v73, v77
	v_cvt_pk_bf16_f32 v70, v70, v71
	v_cvt_pk_bf16_f32 v71, v72, v73
	v_lshlrev_b64 v[72:73], 11, v[78:79]
	v_or_b32_e32 v78, v104, v124
	v_lshl_add_u64 v[72:73], s[4:5], 0, v[72:73]
	v_cmp_lt_i32_e32 vcc, s27, v78
	v_lshl_add_u64 v[72:73], v[72:73], 0, v[66:67]
	global_store_dwordx2 v[72:73], v[70:71], off
	v_cndmask_b32_e32 v98, 0, v80, vcc
	v_lshl_add_u64 v[70:71], v[98:99], 2, s[6:7]
	v_lshl_add_u64 v[74:75], v[70:71], 0, v[68:69]
	v_add_co_u32_e32 v74, vcc, s3, v74
	ds_read_b128 v[70:73], v149 offset:4352
	s_nop 0
	v_addc_co_u32_e32 v75, vcc, 0, v75, vcc
	global_load_dwordx4 v[74:77], v[74:75], off
	v_ashrrev_i32_e32 v79, 31, v78
	s_waitcnt vmcnt(0) lgkmcnt(0)
	v_mul_f32_e64 v70, v70, v74
	v_mul_f32_e64 v71, v71, v75
	v_mul_f32_e64 v72, v72, v76
	v_mul_f32_e64 v73, v73, v77
	v_cvt_pk_bf16_f32 v70, v70, v71
	v_cvt_pk_bf16_f32 v71, v72, v73
	v_lshlrev_b64 v[72:73], 11, v[78:79]
	v_or_b32_e32 v78, v104, v125
	v_lshl_add_u64 v[72:73], s[4:5], 0, v[72:73]
	v_cmp_lt_i32_e32 vcc, s27, v78
	v_lshl_add_u64 v[72:73], v[72:73], 0, v[66:67]
	global_store_dwordx2 v[72:73], v[70:71], off
	v_cndmask_b32_e32 v98, 0, v80, vcc
	v_lshl_add_u64 v[70:71], v[98:99], 2, s[6:7]
	v_lshl_add_u64 v[74:75], v[70:71], 0, v[68:69]
	v_add_co_u32_e32 v74, vcc, s3, v74
	ds_read_b128 v[70:73], v149 offset:5440
	s_nop 0
	v_addc_co_u32_e32 v75, vcc, 0, v75, vcc
	global_load_dwordx4 v[74:77], v[74:75], off
	v_ashrrev_i32_e32 v79, 31, v78
	s_waitcnt vmcnt(0) lgkmcnt(0)
	v_mul_f32_e64 v70, v70, v74
	v_mul_f32_e64 v71, v71, v75
	v_mul_f32_e64 v72, v72, v76
	v_mul_f32_e64 v73, v73, v77
	v_cvt_pk_bf16_f32 v70, v70, v71
	v_cvt_pk_bf16_f32 v71, v72, v73
	v_lshlrev_b64 v[72:73], 11, v[78:79]
	v_or_b32_e32 v78, v104, v126
	v_lshl_add_u64 v[72:73], s[4:5], 0, v[72:73]
	v_cmp_lt_i32_e32 vcc, s27, v78
	v_lshl_add_u64 v[72:73], v[72:73], 0, v[66:67]
	global_store_dwordx2 v[72:73], v[70:71], off
	v_cndmask_b32_e32 v98, 0, v80, vcc
	v_lshl_add_u64 v[70:71], v[98:99], 2, s[6:7]
	v_lshl_add_u64 v[74:75], v[70:71], 0, v[68:69]
	v_add_co_u32_e32 v74, vcc, s3, v74
	ds_read_b128 v[70:73], v149 offset:6528
	s_nop 0
	v_addc_co_u32_e32 v75, vcc, 0, v75, vcc
	global_load_dwordx4 v[74:77], v[74:75], off
	v_ashrrev_i32_e32 v79, 31, v78
	s_waitcnt vmcnt(0) lgkmcnt(0)
	v_mul_f32_e64 v70, v70, v74
	v_mul_f32_e64 v71, v71, v75
	v_mul_f32_e64 v72, v72, v76
	v_mul_f32_e64 v73, v73, v77
	v_cvt_pk_bf16_f32 v70, v70, v71
	v_cvt_pk_bf16_f32 v71, v72, v73
	v_lshlrev_b64 v[72:73], 11, v[78:79]
	v_or_b32_e32 v78, v104, v127
	v_lshl_add_u64 v[72:73], s[4:5], 0, v[72:73]
	v_cmp_lt_i32_e32 vcc, s27, v78
	v_lshl_add_u64 v[72:73], v[72:73], 0, v[66:67]
	global_store_dwordx2 v[72:73], v[70:71], off
	v_cndmask_b32_e32 v98, 0, v80, vcc
	v_lshl_add_u64 v[70:71], v[98:99], 2, s[6:7]
	v_lshl_add_u64 v[74:75], v[70:71], 0, v[68:69]
	v_add_co_u32_e32 v74, vcc, s3, v74
	ds_read_b128 v[70:73], v149 offset:7616
	s_nop 0
	v_addc_co_u32_e32 v75, vcc, 0, v75, vcc
	global_load_dwordx4 v[74:77], v[74:75], off
	v_ashrrev_i32_e32 v79, 31, v78
	s_waitcnt vmcnt(0) lgkmcnt(0)
	v_mul_f32_e64 v70, v70, v74
	v_mul_f32_e64 v71, v71, v75
	v_mul_f32_e64 v72, v72, v76
	v_mul_f32_e64 v73, v73, v77
	v_cvt_pk_bf16_f32 v70, v70, v71
	v_cvt_pk_bf16_f32 v71, v72, v73
	v_lshlrev_b64 v[72:73], 11, v[78:79]
	v_lshl_add_u64 v[72:73], s[4:5], 0, v[72:73]
	v_lshl_add_u64 v[72:73], v[72:73], 0, v[66:67]
	global_store_dwordx2 v[72:73], v[70:71], off
	s_waitcnt lgkmcnt(0)
	ds_write_b128 v147, v[50:53]
	ds_write_b128 v147, v[54:57] offset:32
	ds_write_b128 v147, v[58:61] offset:64
	ds_write_b128 v147, v[62:65] offset:96
	ds_write_b128 v147, v[34:37] offset:128
	ds_write_b128 v147, v[38:41] offset:160
	ds_write_b128 v147, v[42:45] offset:192
	ds_write_b128 v147, v[46:49] offset:224
	v_add_u32_e32 v34, 32, v104
	v_add_u32_e32 v35, 0xfffff020, v104
	v_or_b32_e32 v44, v34, v119
	v_lshrrev_b32_e32 v35, 11, v35
	v_mad_u32_u24 v35, v35, s26, s26
	v_cmp_lt_i32_e32 vcc, s27, v44
	s_waitcnt lgkmcnt(0)
	v_ashrrev_i32_e32 v45, 31, v44
	v_cndmask_b32_e32 v98, 0, v35, vcc
	v_lshl_add_u64 v[36:37], v[98:99], 2, s[6:7]
	v_lshl_add_u64 v[40:41], v[36:37], 0, v[68:69]
	v_add_co_u32_e32 v40, vcc, s3, v40
	ds_read_b128 v[36:39], v149
	s_nop 0
	v_addc_co_u32_e32 v41, vcc, 0, v41, vcc
	global_load_dwordx4 v[40:43], v[40:41], off
	s_waitcnt vmcnt(0) lgkmcnt(0)
	v_mul_f32_e64 v36, v36, v40
	v_mul_f32_e64 v37, v37, v41
	v_mul_f32_e64 v38, v38, v42
	v_mul_f32_e64 v39, v39, v43
	v_cvt_pk_bf16_f32 v36, v36, v37
	v_cvt_pk_bf16_f32 v37, v38, v39
	v_lshlrev_b64 v[38:39], 11, v[44:45]
	v_or_b32_e32 v44, v34, v121
	v_lshl_add_u64 v[38:39], s[4:5], 0, v[38:39]
	v_cmp_lt_i32_e32 vcc, s27, v44
	v_lshl_add_u64 v[38:39], v[38:39], 0, v[66:67]
	global_store_dwordx2 v[38:39], v[36:37], off
	v_cndmask_b32_e32 v98, 0, v35, vcc
	v_lshl_add_u64 v[36:37], v[98:99], 2, s[6:7]
	v_lshl_add_u64 v[40:41], v[36:37], 0, v[68:69]
	v_add_co_u32_e32 v40, vcc, s3, v40
	ds_read_b128 v[36:39], v149 offset:1088
	s_nop 0
	v_addc_co_u32_e32 v41, vcc, 0, v41, vcc
	global_load_dwordx4 v[40:43], v[40:41], off
	v_ashrrev_i32_e32 v45, 31, v44
	s_waitcnt vmcnt(0) lgkmcnt(0)
	v_mul_f32_e64 v36, v36, v40
	v_mul_f32_e64 v37, v37, v41
	v_mul_f32_e64 v38, v38, v42
	v_mul_f32_e64 v39, v39, v43
	v_cvt_pk_bf16_f32 v36, v36, v37
	v_cvt_pk_bf16_f32 v37, v38, v39
	v_lshlrev_b64 v[38:39], 11, v[44:45]
	v_or_b32_e32 v44, v34, v122
	v_lshl_add_u64 v[38:39], s[4:5], 0, v[38:39]
	v_cmp_lt_i32_e32 vcc, s27, v44
	v_lshl_add_u64 v[38:39], v[38:39], 0, v[66:67]
	global_store_dwordx2 v[38:39], v[36:37], off
	v_cndmask_b32_e32 v98, 0, v35, vcc
	v_lshl_add_u64 v[36:37], v[98:99], 2, s[6:7]
	v_lshl_add_u64 v[40:41], v[36:37], 0, v[68:69]
	v_add_co_u32_e32 v40, vcc, s3, v40
	ds_read_b128 v[36:39], v149 offset:2176
	s_nop 0
	v_addc_co_u32_e32 v41, vcc, 0, v41, vcc
	global_load_dwordx4 v[40:43], v[40:41], off
	v_ashrrev_i32_e32 v45, 31, v44
	s_waitcnt vmcnt(0) lgkmcnt(0)
	v_mul_f32_e64 v36, v36, v40
	v_mul_f32_e64 v37, v37, v41
	v_mul_f32_e64 v38, v38, v42
	v_mul_f32_e64 v39, v39, v43
	v_cvt_pk_bf16_f32 v36, v36, v37
	v_cvt_pk_bf16_f32 v37, v38, v39
	v_lshlrev_b64 v[38:39], 11, v[44:45]
	v_or_b32_e32 v44, v34, v123
	v_lshl_add_u64 v[38:39], s[4:5], 0, v[38:39]
	v_cmp_lt_i32_e32 vcc, s27, v44
	v_lshl_add_u64 v[38:39], v[38:39], 0, v[66:67]
	global_store_dwordx2 v[38:39], v[36:37], off
	v_cndmask_b32_e32 v98, 0, v35, vcc
	v_lshl_add_u64 v[36:37], v[98:99], 2, s[6:7]
	v_lshl_add_u64 v[40:41], v[36:37], 0, v[68:69]
	v_add_co_u32_e32 v40, vcc, s3, v40
	ds_read_b128 v[36:39], v149 offset:3264
	s_nop 0
	v_addc_co_u32_e32 v41, vcc, 0, v41, vcc
	global_load_dwordx4 v[40:43], v[40:41], off
	v_ashrrev_i32_e32 v45, 31, v44
	s_waitcnt vmcnt(0) lgkmcnt(0)
	v_mul_f32_e64 v36, v36, v40
	v_mul_f32_e64 v37, v37, v41
	v_mul_f32_e64 v38, v38, v42
	v_mul_f32_e64 v39, v39, v43
	v_cvt_pk_bf16_f32 v36, v36, v37
	v_cvt_pk_bf16_f32 v37, v38, v39
	v_lshlrev_b64 v[38:39], 11, v[44:45]
	v_or_b32_e32 v44, v34, v124
	v_lshl_add_u64 v[38:39], s[4:5], 0, v[38:39]
	v_cmp_lt_i32_e32 vcc, s27, v44
	v_lshl_add_u64 v[38:39], v[38:39], 0, v[66:67]
	global_store_dwordx2 v[38:39], v[36:37], off
	v_cndmask_b32_e32 v98, 0, v35, vcc
	v_lshl_add_u64 v[36:37], v[98:99], 2, s[6:7]
	v_lshl_add_u64 v[40:41], v[36:37], 0, v[68:69]
	v_add_co_u32_e32 v40, vcc, s3, v40
	ds_read_b128 v[36:39], v149 offset:4352
	s_nop 0
	v_addc_co_u32_e32 v41, vcc, 0, v41, vcc
	global_load_dwordx4 v[40:43], v[40:41], off
	v_ashrrev_i32_e32 v45, 31, v44
	s_waitcnt vmcnt(0) lgkmcnt(0)
	v_mul_f32_e64 v36, v36, v40
	v_mul_f32_e64 v37, v37, v41
	v_mul_f32_e64 v38, v38, v42
	v_mul_f32_e64 v39, v39, v43
	v_cvt_pk_bf16_f32 v36, v36, v37
	v_cvt_pk_bf16_f32 v37, v38, v39
	v_lshlrev_b64 v[38:39], 11, v[44:45]
	v_or_b32_e32 v44, v34, v125
	v_lshl_add_u64 v[38:39], s[4:5], 0, v[38:39]
	v_cmp_lt_i32_e32 vcc, s27, v44
	v_lshl_add_u64 v[38:39], v[38:39], 0, v[66:67]
	global_store_dwordx2 v[38:39], v[36:37], off
	v_cndmask_b32_e32 v98, 0, v35, vcc
	v_lshl_add_u64 v[36:37], v[98:99], 2, s[6:7]
	v_lshl_add_u64 v[40:41], v[36:37], 0, v[68:69]
	v_add_co_u32_e32 v40, vcc, s3, v40
	ds_read_b128 v[36:39], v149 offset:5440
	s_nop 0
	v_addc_co_u32_e32 v41, vcc, 0, v41, vcc
	global_load_dwordx4 v[40:43], v[40:41], off
	v_ashrrev_i32_e32 v45, 31, v44
	s_waitcnt vmcnt(0) lgkmcnt(0)
	v_pk_mul_f32 v[36:37], v[36:37], v[40:41]
	v_pk_mul_f32 v[38:39], v[38:39], v[42:43]
	v_cvt_pk_bf16_f32 v36, v36, v37
	v_cvt_pk_bf16_f32 v37, v38, v39
	v_lshlrev_b64 v[38:39], 11, v[44:45]
	v_or_b32_e32 v44, v34, v126
	v_lshl_add_u64 v[38:39], s[4:5], 0, v[38:39]
	v_cmp_lt_i32_e32 vcc, s27, v44
	v_lshl_add_u64 v[38:39], v[38:39], 0, v[66:67]
	global_store_dwordx2 v[38:39], v[36:37], off
	v_cndmask_b32_e32 v98, 0, v35, vcc
	v_lshl_add_u64 v[36:37], v[98:99], 2, s[6:7]
	v_lshl_add_u64 v[40:41], v[36:37], 0, v[68:69]
	v_add_co_u32_e32 v40, vcc, s3, v40
	ds_read_b128 v[36:39], v149 offset:6528
	s_nop 0
	v_addc_co_u32_e32 v41, vcc, 0, v41, vcc
	global_load_dwordx4 v[40:43], v[40:41], off
	v_ashrrev_i32_e32 v45, 31, v44
	s_waitcnt vmcnt(0) lgkmcnt(0)
	v_pk_mul_f32 v[36:37], v[36:37], v[40:41]
	v_pk_mul_f32 v[38:39], v[38:39], v[42:43]
	v_or_b32_e32 v42, v34, v127
	v_cvt_pk_bf16_f32 v36, v36, v37
	v_cvt_pk_bf16_f32 v37, v38, v39
	v_lshlrev_b64 v[38:39], 11, v[44:45]
	v_cmp_lt_i32_e32 vcc, s27, v42
	v_lshl_add_u64 v[38:39], s[4:5], 0, v[38:39]
	v_lshl_add_u64 v[38:39], v[38:39], 0, v[66:67]
	v_cndmask_b32_e32 v98, 0, v35, vcc
	v_lshl_add_u64 v[34:35], v[98:99], 2, s[6:7]
	global_store_dwordx2 v[38:39], v[36:37], off
	v_lshl_add_u64 v[38:39], v[34:35], 0, v[68:69]
	v_add_co_u32_e32 v38, vcc, s3, v38
	ds_read_b128 v[34:37], v149 offset:7616
	s_nop 0
	v_addc_co_u32_e32 v39, vcc, 0, v39, vcc
	global_load_dwordx4 v[38:41], v[38:39], off
	v_ashrrev_i32_e32 v43, 31, v42
	s_waitcnt vmcnt(0) lgkmcnt(0)
	v_pk_mul_f32 v[34:35], v[34:35], v[38:39]
	v_pk_mul_f32 v[36:37], v[36:37], v[40:41]
	v_cvt_pk_bf16_f32 v34, v34, v35
	v_cvt_pk_bf16_f32 v35, v36, v37
	v_lshlrev_b64 v[36:37], 11, v[42:43]
	v_lshl_add_u64 v[36:37], s[4:5], 0, v[36:37]
	v_lshl_add_u64 v[36:37], v[36:37], 0, v[66:67]
	global_store_dwordx2 v[36:37], v[34:35], off
	s_waitcnt lgkmcnt(0)
	ds_write_b128 v147, v[18:21]
	ds_write_b128 v147, v[22:25] offset:32
	ds_write_b128 v147, v[26:29] offset:64
	ds_write_b128 v147, v[30:33] offset:96
	ds_write_b128 v147, v[2:5] offset:128
	ds_write_b128 v147, v[6:9] offset:160
	ds_write_b128 v147, v[10:13] offset:192
	ds_write_b128 v147, v[14:17] offset:224
	v_add_u32_e32 v2, 64, v104
	v_add_u32_e32 v3, 0xfffff040, v104
	v_or_b32_e32 v12, v2, v119
	v_lshrrev_b32_e32 v3, 11, v3
	v_mad_u32_u24 v3, v3, s26, s26
	v_cmp_lt_i32_e32 vcc, s27, v12
	s_waitcnt lgkmcnt(0)
	v_ashrrev_i32_e32 v13, 31, v12
	s_nop 0
	v_cndmask_b32_e32 v98, 0, v3, vcc
	v_lshl_add_u64 v[4:5], v[98:99], 2, s[6:7]
	v_lshl_add_u64 v[8:9], v[4:5], 0, v[68:69]
	v_add_co_u32_e32 v8, vcc, s3, v8
	ds_read_b128 v[4:7], v149
	s_nop 0
	v_addc_co_u32_e32 v9, vcc, 0, v9, vcc
	global_load_dwordx4 v[8:11], v[8:9], off
	s_waitcnt vmcnt(0) lgkmcnt(0)
	v_pk_mul_f32 v[4:5], v[4:5], v[8:9]
	v_pk_mul_f32 v[6:7], v[6:7], v[10:11]
	v_cvt_pk_bf16_f32 v4, v4, v5
	v_cvt_pk_bf16_f32 v5, v6, v7
	v_lshlrev_b64 v[6:7], 11, v[12:13]
	v_or_b32_e32 v12, v2, v121
	v_lshl_add_u64 v[6:7], s[4:5], 0, v[6:7]
	v_cmp_lt_i32_e32 vcc, s27, v12
	v_lshl_add_u64 v[6:7], v[6:7], 0, v[66:67]
	global_store_dwordx2 v[6:7], v[4:5], off
	v_cndmask_b32_e32 v98, 0, v3, vcc
	v_lshl_add_u64 v[4:5], v[98:99], 2, s[6:7]
	v_lshl_add_u64 v[8:9], v[4:5], 0, v[68:69]
	v_add_co_u32_e32 v8, vcc, s3, v8
	ds_read_b128 v[4:7], v149 offset:1088
	s_nop 0
	v_addc_co_u32_e32 v9, vcc, 0, v9, vcc
	global_load_dwordx4 v[8:11], v[8:9], off
	v_ashrrev_i32_e32 v13, 31, v12
	s_waitcnt vmcnt(0) lgkmcnt(0)
	v_pk_mul_f32 v[4:5], v[4:5], v[8:9]
	v_pk_mul_f32 v[6:7], v[6:7], v[10:11]
	v_cvt_pk_bf16_f32 v4, v4, v5
	v_cvt_pk_bf16_f32 v5, v6, v7
	v_lshlrev_b64 v[6:7], 11, v[12:13]
	v_or_b32_e32 v12, v2, v122
	v_lshl_add_u64 v[6:7], s[4:5], 0, v[6:7]
	v_cmp_lt_i32_e32 vcc, s27, v12
	v_lshl_add_u64 v[6:7], v[6:7], 0, v[66:67]
	global_store_dwordx2 v[6:7], v[4:5], off
	v_cndmask_b32_e32 v98, 0, v3, vcc
	v_lshl_add_u64 v[4:5], v[98:99], 2, s[6:7]
	v_lshl_add_u64 v[8:9], v[4:5], 0, v[68:69]
	v_add_co_u32_e32 v8, vcc, s3, v8
	ds_read_b128 v[4:7], v149 offset:2176
	s_nop 0
	v_addc_co_u32_e32 v9, vcc, 0, v9, vcc
	global_load_dwordx4 v[8:11], v[8:9], off
	v_ashrrev_i32_e32 v13, 31, v12
	s_waitcnt vmcnt(0) lgkmcnt(0)
	v_pk_mul_f32 v[4:5], v[4:5], v[8:9]
	v_pk_mul_f32 v[6:7], v[6:7], v[10:11]
	v_cvt_pk_bf16_f32 v4, v4, v5
	v_cvt_pk_bf16_f32 v5, v6, v7
	v_lshlrev_b64 v[6:7], 11, v[12:13]
	v_or_b32_e32 v12, v2, v123
	v_lshl_add_u64 v[6:7], s[4:5], 0, v[6:7]
	v_cmp_lt_i32_e32 vcc, s27, v12
	v_lshl_add_u64 v[6:7], v[6:7], 0, v[66:67]
	global_store_dwordx2 v[6:7], v[4:5], off
	v_cndmask_b32_e32 v98, 0, v3, vcc
	v_lshl_add_u64 v[4:5], v[98:99], 2, s[6:7]
	v_lshl_add_u64 v[8:9], v[4:5], 0, v[68:69]
	v_add_co_u32_e32 v8, vcc, s3, v8
	ds_read_b128 v[4:7], v149 offset:3264
	s_nop 0
	v_addc_co_u32_e32 v9, vcc, 0, v9, vcc
	global_load_dwordx4 v[8:11], v[8:9], off
	v_ashrrev_i32_e32 v13, 31, v12
	s_waitcnt vmcnt(0) lgkmcnt(0)
	v_pk_mul_f32 v[4:5], v[4:5], v[8:9]
	v_pk_mul_f32 v[6:7], v[6:7], v[10:11]
	v_cvt_pk_bf16_f32 v4, v4, v5
	v_cvt_pk_bf16_f32 v5, v6, v7
	v_lshlrev_b64 v[6:7], 11, v[12:13]
	v_or_b32_e32 v12, v2, v124
	v_lshl_add_u64 v[6:7], s[4:5], 0, v[6:7]
	v_cmp_lt_i32_e32 vcc, s27, v12
	v_lshl_add_u64 v[6:7], v[6:7], 0, v[66:67]
	global_store_dwordx2 v[6:7], v[4:5], off
	v_cndmask_b32_e32 v98, 0, v3, vcc
	v_lshl_add_u64 v[4:5], v[98:99], 2, s[6:7]
	v_lshl_add_u64 v[8:9], v[4:5], 0, v[68:69]
	v_add_co_u32_e32 v8, vcc, s3, v8
	ds_read_b128 v[4:7], v149 offset:4352
	s_nop 0
	v_addc_co_u32_e32 v9, vcc, 0, v9, vcc
	global_load_dwordx4 v[8:11], v[8:9], off
	v_ashrrev_i32_e32 v13, 31, v12
	s_waitcnt vmcnt(0) lgkmcnt(0)
	v_pk_mul_f32 v[4:5], v[4:5], v[8:9]
	v_pk_mul_f32 v[6:7], v[6:7], v[10:11]
	v_cvt_pk_bf16_f32 v4, v4, v5
	v_cvt_pk_bf16_f32 v5, v6, v7
	v_lshlrev_b64 v[6:7], 11, v[12:13]
	v_or_b32_e32 v12, v2, v125
	v_lshl_add_u64 v[6:7], s[4:5], 0, v[6:7]
	v_cmp_lt_i32_e32 vcc, s27, v12
	v_lshl_add_u64 v[6:7], v[6:7], 0, v[66:67]
	global_store_dwordx2 v[6:7], v[4:5], off
	v_cndmask_b32_e32 v98, 0, v3, vcc
	v_lshl_add_u64 v[4:5], v[98:99], 2, s[6:7]
	v_lshl_add_u64 v[8:9], v[4:5], 0, v[68:69]
	v_add_co_u32_e32 v8, vcc, s3, v8
	ds_read_b128 v[4:7], v149 offset:5440
	s_nop 0
	v_addc_co_u32_e32 v9, vcc, 0, v9, vcc
	global_load_dwordx4 v[8:11], v[8:9], off
	v_ashrrev_i32_e32 v13, 31, v12
	s_waitcnt vmcnt(0) lgkmcnt(0)
	v_pk_mul_f32 v[4:5], v[4:5], v[8:9]
	v_pk_mul_f32 v[6:7], v[6:7], v[10:11]
	v_cvt_pk_bf16_f32 v4, v4, v5
	v_cvt_pk_bf16_f32 v5, v6, v7
	v_lshlrev_b64 v[6:7], 11, v[12:13]
	v_or_b32_e32 v12, v2, v126
	v_lshl_add_u64 v[6:7], s[4:5], 0, v[6:7]
	v_cmp_lt_i32_e32 vcc, s27, v12
	v_lshl_add_u64 v[6:7], v[6:7], 0, v[66:67]
	global_store_dwordx2 v[6:7], v[4:5], off
	v_cndmask_b32_e32 v98, 0, v3, vcc
	v_lshl_add_u64 v[4:5], v[98:99], 2, s[6:7]
	v_lshl_add_u64 v[8:9], v[4:5], 0, v[68:69]
	v_add_co_u32_e32 v8, vcc, s3, v8
	ds_read_b128 v[4:7], v149 offset:6528
	s_nop 0
	v_addc_co_u32_e32 v9, vcc, 0, v9, vcc
	global_load_dwordx4 v[8:11], v[8:9], off
	v_ashrrev_i32_e32 v13, 31, v12
	s_waitcnt vmcnt(0) lgkmcnt(0)
	v_pk_mul_f32 v[4:5], v[4:5], v[8:9]
	v_pk_mul_f32 v[6:7], v[6:7], v[10:11]
	v_or_b32_e32 v10, v2, v127
	v_cvt_pk_bf16_f32 v4, v4, v5
	v_cvt_pk_bf16_f32 v5, v6, v7
	v_lshlrev_b64 v[6:7], 11, v[12:13]
	v_cmp_lt_i32_e32 vcc, s27, v10
	v_lshl_add_u64 v[6:7], s[4:5], 0, v[6:7]
	v_lshl_add_u64 v[6:7], v[6:7], 0, v[66:67]
	v_cndmask_b32_e32 v98, 0, v3, vcc
	v_lshl_add_u64 v[2:3], v[98:99], 2, s[6:7]
	global_store_dwordx2 v[6:7], v[4:5], off
	v_lshl_add_u64 v[6:7], v[2:3], 0, v[68:69]
	v_add_co_u32_e32 v6, vcc, s3, v6
	ds_read_b128 v[2:5], v149 offset:7616
	s_nop 0
	v_addc_co_u32_e32 v7, vcc, 0, v7, vcc
	global_load_dwordx4 v[6:9], v[6:7], off
	v_ashrrev_i32_e32 v11, 31, v10
	s_waitcnt vmcnt(0) lgkmcnt(0)
	v_pk_mul_f32 v[2:3], v[2:3], v[6:7]
	v_pk_mul_f32 v[4:5], v[4:5], v[8:9]
	v_cvt_pk_bf16_f32 v2, v2, v3
	v_cvt_pk_bf16_f32 v3, v4, v5
	v_lshlrev_b64 v[4:5], 11, v[10:11]
	v_lshl_add_u64 v[4:5], s[4:5], 0, v[4:5]
	v_lshl_add_u64 v[4:5], v[4:5], 0, v[66:67]
	global_store_dwordx2 v[4:5], v[2:3], off
	s_waitcnt lgkmcnt(0)
	s_load_dword s10, s[8:9], 0x0
	s_waitcnt lgkmcnt(0)
	s_add_i32 s28, s10, s28
	s_cmpk_lt_i32 s28, 0x200
	s_cbranch_scc1 .LBB0_1133

.LBB0_1270:
	s_ashr_i32 s4, s64, 31
	s_lshr_b32 s4, s4, 26
	s_add_i32 s4, s64, s4
	s_ashr_i32 s5, s4, 6
	s_and_b32 s4, s4, 0x3ffffc0
	s_sub_i32 s6, s64, s4
	s_mulk_i32 s6, 0xc0
	v_add_u32_e32 v2, s6, v116
	s_lshr_b32 s7, s6, 6
	s_lshl_b32 s4, s5, 7
	v_ashrrev_i32_e32 v3, 31, v2
	s_add_i32 s7, s7, s5
	v_lshlrev_b64 v[2:3], 11, v[2:3]
	v_or_b32_e32 v4, s4, v116
	s_lshl_b32 s46, s7, 6
	s_lshl_b32 s7, s7, 7
	v_ashrrev_i32_e32 v5, 31, v4
	v_lshl_add_u64 v[112:113], v[104:105], 0, v[2:3]
	s_and_b32 s16, s7, 0x780
	v_readfirstlane_b32 s7, v117
	v_add_u32_e32 v6, 0x1000, v117
	v_lshlrev_b64 v[4:5], 11, v[4:5]
	v_lshl_add_u64 v[2:3], v[112:113], 0, s[16:17]
	s_mov_b32 m0, s7
	v_readfirstlane_b32 s7, v6
	v_add_u32_e32 v6, 0x2000, v117
	v_lshl_add_u64 v[114:115], v[106:107], 0, v[4:5]
	s_waitcnt vmcnt(0)
	s_barrier
	s_load_dwordx2 s[66:67], s[0:1], 0x90
	s_load_dwordx2 s[68:69], s[0:1], 0xf8
	v_and_b32_e32 v201, 0x3ff, v0
	v_readfirstlane_b32 s76, v0
	v_and_b32_e32 v200, 31, v201
	v_bfe_u32 v214, v201, 1, 3
	v_bfe_u32 v213, v201, 5, 1
	v_xor_b32_e32 v214, v214, v213
	v_lshlrev_b32_e32 v214, 4, v214
	s_and_b32 s76, s76, 0x3ff
	s_lshr_b32 s79, s76, 6
	s_lshl_b32 s76, s76, 4
	s_lshr_b32 s80, s79, 1
	s_and_b32 s79, s79, 1
	s_mul_i32 s80, s80, 0x3000
	s_lshl_b32 s79, s79, 13
	s_add_u32 s79, s79, 0xc000
	v_lshlrev_b32_e32 v200, 7, v200
	v_or_b32_e32 v200, v200, v214
	v_add_u32_e32 v215, s80, v200
	v_add_u32_e32 v211, s79, v200
	v_xor_b32_e32 v214, 0x20, v215
	v_xor_b32_e32 v210, 0x20, v211
	v_xor_b32_e32 v213, 0x40, v215
	v_xor_b32_e32 v209, 0x40, v211
	v_xor_b32_e32 v212, 0x60, v215
	v_xor_b32_e32 v208, 0x60, v211
	v_bfe_u32 v200, v201, 4, 3
	v_and_b32_e32 v206, 7, v201
	v_xor_b32_e32 v200, v200, v206
	v_lshlrev_b32_e32 v200, 4, v200
	v_lshrrev_b32_e32 v206, 3, v201
	v_lshl_or_b32 v207, v206, 11, v200
	v_add_u32_e32 v206, 0x10000, v207
	v_add_u32_e32 v205, 0x20000, v207
	v_add_u32_e32 v204, 0x30000, v207
	v_add_u32_e32 v203, 0x40000, v207
	v_add_u32_e32 v202, 0x50000, v207
	s_lshr_b32 s79, s64, 6
	s_and_b32 s80, s64, 63
	s_mov_b32 s75, 0
	s_mul_i32 s80, s80, 0x60000
	s_lshl_b32 s79, s79, 18
	s_waitcnt lgkmcnt(0)
	s_add_u32 s66, s66, s80
	s_addc_u32 s67, s67, 0
	s_add_u32 s68, s68, s79
	s_addc_u32 s69, s69, 0
	s_add_u32 s79, s75, 0
	s_and_b32 s79, s79, 15
	s_lshl_b32 s79, s79, 7
	s_add_u32 s70, s66, s79
	s_addc_u32 s71, s67, 0
	s_add_u32 s72, s68, s79
	s_addc_u32 s73, s69, 0
	s_add_u32 s77, s76, 0x0
	s_add_u32 s78, s76, 0xc000
	s_add_u32 m0, s77, 0x0
	s_nop 0
	global_load_lds_dwordx4 v207, s[70:71]
	s_add_u32 m0, s77, 0x1000
	s_nop 0
	global_load_lds_dwordx4 v206, s[70:71]
	s_add_u32 m0, s77, 0x2000
	s_nop 0
	global_load_lds_dwordx4 v205, s[70:71]
	s_add_u32 m0, s77, 0x3000
	s_nop 0
	global_load_lds_dwordx4 v204, s[70:71]
	s_add_u32 m0, s77, 0x4000
	s_nop 0
	global_load_lds_dwordx4 v203, s[70:71]
	s_add_u32 m0, s77, 0x5000
	s_nop 0
	global_load_lds_dwordx4 v202, s[70:71]
	s_add_u32 m0, s78, 0x0
	s_nop 0
	global_load_lds_dwordx4 v207, s[72:73]
	s_add_u32 m0, s78, 0x1000
	s_nop 0
	global_load_lds_dwordx4 v206, s[72:73]
	s_add_u32 m0, s78, 0x2000
	s_nop 0
	global_load_lds_dwordx4 v205, s[72:73]
	s_add_u32 m0, s78, 0x3000
	s_nop 0
	global_load_lds_dwordx4 v204, s[72:73]
	s_add_u32 s79, s75, 1
	s_and_b32 s79, s79, 15
	s_lshl_b32 s79, s79, 7
	s_add_u32 s70, s66, s79
	s_addc_u32 s71, s67, 0
	s_add_u32 s72, s68, s79
	s_addc_u32 s73, s69, 0
	s_add_u32 s77, s76, 0x6000
	s_add_u32 s78, s76, 0x10000
	s_add_u32 m0, s77, 0x0
	s_nop 0
	global_load_lds_dwordx4 v207, s[70:71]
	s_add_u32 m0, s77, 0x1000
	s_nop 0
	global_load_lds_dwordx4 v206, s[70:71]
	s_add_u32 m0, s77, 0x2000
	s_nop 0
	global_load_lds_dwordx4 v205, s[70:71]
	s_add_u32 m0, s77, 0x3000
	s_nop 0
	global_load_lds_dwordx4 v204, s[70:71]
	s_add_u32 m0, s77, 0x4000
	s_nop 0
	global_load_lds_dwordx4 v203, s[70:71]
	s_add_u32 m0, s77, 0x5000
	s_nop 0
	global_load_lds_dwordx4 v202, s[70:71]
	s_add_u32 m0, s78, 0x0
	s_nop 0
	global_load_lds_dwordx4 v207, s[72:73]
	s_add_u32 m0, s78, 0x1000
	s_nop 0
	global_load_lds_dwordx4 v206, s[72:73]
	s_add_u32 m0, s78, 0x2000
	s_nop 0
	global_load_lds_dwordx4 v205, s[72:73]
	s_add_u32 m0, s78, 0x3000
	s_nop 0
	global_load_lds_dwordx4 v204, s[72:73]
	v_mov_b32_e32 v2, 0
	v_mov_b32_e32 v3, 0
	v_mov_b32_e32 v4, 0
	v_mov_b32_e32 v5, 0
	v_mov_b32_e32 v6, 0
	v_mov_b32_e32 v7, 0
	v_mov_b32_e32 v8, 0
	v_mov_b32_e32 v9, 0
	v_mov_b32_e32 v10, 0
	v_mov_b32_e32 v11, 0
	v_mov_b32_e32 v12, 0
	v_mov_b32_e32 v13, 0
	v_mov_b32_e32 v14, 0
	v_mov_b32_e32 v15, 0
	v_mov_b32_e32 v16, 0
	v_mov_b32_e32 v17, 0
	v_mov_b32_e32 v18, 0
	v_mov_b32_e32 v19, 0
	v_mov_b32_e32 v20, 0
	v_mov_b32_e32 v21, 0
	v_mov_b32_e32 v22, 0
	v_mov_b32_e32 v23, 0
	v_mov_b32_e32 v24, 0
	v_mov_b32_e32 v25, 0
	v_mov_b32_e32 v26, 0
	v_mov_b32_e32 v27, 0
	v_mov_b32_e32 v28, 0
	v_mov_b32_e32 v29, 0
	v_mov_b32_e32 v30, 0
	v_mov_b32_e32 v31, 0
	v_mov_b32_e32 v32, 0
	v_mov_b32_e32 v33, 0
	v_mov_b32_e32 v34, 0
	v_mov_b32_e32 v35, 0
	v_mov_b32_e32 v36, 0
	v_mov_b32_e32 v37, 0
	v_mov_b32_e32 v38, 0
	v_mov_b32_e32 v39, 0
	v_mov_b32_e32 v40, 0
	v_mov_b32_e32 v41, 0
	v_mov_b32_e32 v42, 0
	v_mov_b32_e32 v43, 0
	v_mov_b32_e32 v44, 0
	v_mov_b32_e32 v45, 0
	v_mov_b32_e32 v46, 0
	v_mov_b32_e32 v47, 0
	v_mov_b32_e32 v48, 0
	v_mov_b32_e32 v49, 0
	v_mov_b32_e32 v50, 0
	v_mov_b32_e32 v51, 0
	v_mov_b32_e32 v52, 0
	v_mov_b32_e32 v53, 0
	v_mov_b32_e32 v54, 0
	v_mov_b32_e32 v55, 0
	v_mov_b32_e32 v56, 0
	v_mov_b32_e32 v57, 0
	v_mov_b32_e32 v58, 0
	v_mov_b32_e32 v59, 0
	v_mov_b32_e32 v60, 0
	v_mov_b32_e32 v61, 0
	v_mov_b32_e32 v62, 0
	v_mov_b32_e32 v63, 0
	v_mov_b32_e32 v64, 0
	v_mov_b32_e32 v65, 0
	v_mov_b32_e32 v66, 0
	v_mov_b32_e32 v67, 0
	v_mov_b32_e32 v68, 0
	v_mov_b32_e32 v69, 0
	v_mov_b32_e32 v70, 0
	v_mov_b32_e32 v71, 0
	v_mov_b32_e32 v72, 0
	v_mov_b32_e32 v73, 0
	v_mov_b32_e32 v74, 0
	v_mov_b32_e32 v75, 0
	v_mov_b32_e32 v76, 0
	v_mov_b32_e32 v77, 0
	v_mov_b32_e32 v78, 0
	v_mov_b32_e32 v79, 0
	v_mov_b32_e32 v80, 0
	v_mov_b32_e32 v81, 0
	v_mov_b32_e32 v82, 0
	v_mov_b32_e32 v83, 0
	v_mov_b32_e32 v84, 0
	v_mov_b32_e32 v85, 0
	v_mov_b32_e32 v86, 0
	v_mov_b32_e32 v87, 0
	v_mov_b32_e32 v88, 0
	v_mov_b32_e32 v89, 0
	v_mov_b32_e32 v90, 0
	v_mov_b32_e32 v91, 0
	v_mov_b32_e32 v92, 0
	v_mov_b32_e32 v93, 0
	v_mov_b32_e32 v94, 0
	v_mov_b32_e32 v95, 0
	v_mov_b32_e32 v96, 0
	v_mov_b32_e32 v97, 0
	s_waitcnt vmcnt(10)
	s_barrier
	ds_read_b128 v[240:243], v211 offset:0
	ds_read_b128 v[252:255], v215 offset:0
	ds_read_b128 v[236:239], v211 offset:4096
	ds_read_b128 v[248:251], v215 offset:4096
	ds_read_b128 v[244:247], v215 offset:8192
	s_mov_b32 s74, 0
.Lgm_ph13_loop:
	s_waitcnt lgkmcnt(1)
	v_mfma_f32_32x32x16_bf16 v[82:97], v[240:243], v[252:255], v[82:97]
	ds_read_b128 v[220:223], v210 offset:0
	v_mfma_f32_32x32x16_bf16 v[66:81], v[236:239], v[252:255], v[66:81]
	ds_read_b128 v[232:235], v214 offset:0
	v_mfma_f32_32x32x16_bf16 v[50:65], v[240:243], v[248:251], v[50:65]
	ds_read_b128 v[216:219], v210 offset:4096
	v_mfma_f32_32x32x16_bf16 v[34:49], v[236:239], v[248:251], v[34:49]
	ds_read_b128 v[228:231], v214 offset:4096
	s_waitcnt lgkmcnt(4)
	v_mfma_f32_32x32x16_bf16 v[18:33], v[240:243], v[244:247], v[18:33]
	ds_read_b128 v[224:227], v214 offset:8192
	v_mfma_f32_32x32x16_bf16 v[2:17], v[236:239], v[244:247], v[2:17]
	s_waitcnt lgkmcnt(1)
	v_mfma_f32_32x32x16_bf16 v[82:97], v[220:223], v[232:235], v[82:97]
	ds_read_b128 v[240:243], v209 offset:0
	v_mfma_f32_32x32x16_bf16 v[66:81], v[216:219], v[232:235], v[66:81]
	ds_read_b128 v[252:255], v213 offset:0
	v_mfma_f32_32x32x16_bf16 v[50:65], v[220:223], v[228:231], v[50:65]
	ds_read_b128 v[236:239], v209 offset:4096
	v_mfma_f32_32x32x16_bf16 v[34:49], v[216:219], v[228:231], v[34:49]
	ds_read_b128 v[248:251], v213 offset:4096
	s_waitcnt lgkmcnt(4)
	v_mfma_f32_32x32x16_bf16 v[18:33], v[220:223], v[224:227], v[18:33]
	ds_read_b128 v[244:247], v213 offset:8192
	v_mfma_f32_32x32x16_bf16 v[2:17], v[216:219], v[224:227], v[2:17]
	s_waitcnt lgkmcnt(1)
	v_mfma_f32_32x32x16_bf16 v[82:97], v[240:243], v[252:255], v[82:97]
	ds_read_b128 v[220:223], v208 offset:0
	s_add_u32 s79, s75, s74
	s_add_u32 s79, s79, 2
	s_and_b32 s79, s79, 15
	v_mfma_f32_32x32x16_bf16 v[66:81], v[236:239], v[252:255], v[66:81]
	ds_read_b128 v[232:235], v212 offset:0
	s_lshl_b32 s79, s79, 7
	s_add_u32 s70, s66, s79
	v_mfma_f32_32x32x16_bf16 v[50:65], v[240:243], v[248:251], v[50:65]
	ds_read_b128 v[216:219], v208 offset:4096
	s_addc_u32 s71, s67, 0
	s_add_u32 s72, s68, s79
	v_mfma_f32_32x32x16_bf16 v[34:49], v[236:239], v[248:251], v[34:49]
	ds_read_b128 v[228:231], v212 offset:4096
	s_addc_u32 s73, s69, 0
	s_add_u32 s77, s76, 0x0
	s_add_u32 s78, s76, 0xc000
	s_waitcnt lgkmcnt(4)
	v_mfma_f32_32x32x16_bf16 v[18:33], v[240:243], v[244:247], v[18:33]
	ds_read_b128 v[224:227], v212 offset:8192
	v_mfma_f32_32x32x16_bf16 v[2:17], v[236:239], v[244:247], v[2:17]
	s_waitcnt vmcnt(0) lgkmcnt(0)
	s_barrier
	v_mfma_f32_32x32x16_bf16 v[82:97], v[220:223], v[232:235], v[82:97]
	s_add_u32 m0, s77, 0x0
	ds_read_b128 v[240:243], v211 offset:16384
	global_load_lds_dwordx4 v207, s[70:71]
	s_add_u32 m0, s77, 0x1000
	s_nop 0
	global_load_lds_dwordx4 v206, s[70:71]
	v_mfma_f32_32x32x16_bf16 v[66:81], v[216:219], v[232:235], v[66:81]
	s_add_u32 m0, s77, 0x2000
	ds_read_b128 v[252:255], v215 offset:24576
	global_load_lds_dwordx4 v205, s[70:71]
	s_add_u32 m0, s77, 0x3000
	s_nop 0
	global_load_lds_dwordx4 v204, s[70:71]
	v_mfma_f32_32x32x16_bf16 v[50:65], v[220:223], v[228:231], v[50:65]
	s_add_u32 m0, s77, 0x4000
	ds_read_b128 v[236:239], v211 offset:20480
	global_load_lds_dwordx4 v203, s[70:71]
	s_add_u32 m0, s77, 0x5000
	s_nop 0
	global_load_lds_dwordx4 v202, s[70:71]
	v_mfma_f32_32x32x16_bf16 v[34:49], v[216:219], v[228:231], v[34:49]
	s_add_u32 m0, s78, 0x0
	ds_read_b128 v[248:251], v215 offset:28672
	global_load_lds_dwordx4 v207, s[72:73]
	s_add_u32 m0, s78, 0x1000
	s_nop 0
	global_load_lds_dwordx4 v206, s[72:73]
	v_mfma_f32_32x32x16_bf16 v[18:33], v[220:223], v[224:227], v[18:33]
	s_add_u32 m0, s78, 0x2000
	ds_read_b128 v[244:247], v215 offset:32768
	global_load_lds_dwordx4 v205, s[72:73]
	s_add_u32 m0, s78, 0x3000
	s_nop 0
	global_load_lds_dwordx4 v204, s[72:73]
	v_mfma_f32_32x32x16_bf16 v[2:17], v[216:219], v[224:227], v[2:17]
	s_waitcnt lgkmcnt(1)
	v_mfma_f32_32x32x16_bf16 v[82:97], v[240:243], v[252:255], v[82:97]
	ds_read_b128 v[220:223], v210 offset:16384
	v_mfma_f32_32x32x16_bf16 v[66:81], v[236:239], v[252:255], v[66:81]
	ds_read_b128 v[232:235], v214 offset:24576
	v_mfma_f32_32x32x16_bf16 v[50:65], v[240:243], v[248:251], v[50:65]
	ds_read_b128 v[216:219], v210 offset:20480
	v_mfma_f32_32x32x16_bf16 v[34:49], v[236:239], v[248:251], v[34:49]
	ds_read_b128 v[228:231], v214 offset:28672
	s_waitcnt lgkmcnt(4)
	v_mfma_f32_32x32x16_bf16 v[18:33], v[240:243], v[244:247], v[18:33]
	ds_read_b128 v[224:227], v214 offset:32768
	v_mfma_f32_32x32x16_bf16 v[2:17], v[236:239], v[244:247], v[2:17]
	s_waitcnt lgkmcnt(1)
	v_mfma_f32_32x32x16_bf16 v[82:97], v[220:223], v[232:235], v[82:97]
	ds_read_b128 v[240:243], v209 offset:16384
	v_mfma_f32_32x32x16_bf16 v[66:81], v[216:219], v[232:235], v[66:81]
	ds_read_b128 v[252:255], v213 offset:24576
	v_mfma_f32_32x32x16_bf16 v[50:65], v[220:223], v[228:231], v[50:65]
	ds_read_b128 v[236:239], v209 offset:20480
	v_mfma_f32_32x32x16_bf16 v[34:49], v[216:219], v[228:231], v[34:49]
	ds_read_b128 v[248:251], v213 offset:28672
	s_waitcnt lgkmcnt(4)
	v_mfma_f32_32x32x16_bf16 v[18:33], v[220:223], v[224:227], v[18:33]
	ds_read_b128 v[244:247], v213 offset:32768
	v_mfma_f32_32x32x16_bf16 v[2:17], v[216:219], v[224:227], v[2:17]
	s_waitcnt lgkmcnt(1)
	v_mfma_f32_32x32x16_bf16 v[82:97], v[240:243], v[252:255], v[82:97]
	ds_read_b128 v[220:223], v208 offset:16384
	s_add_u32 s79, s75, s74
	s_add_u32 s79, s79, 3
	s_and_b32 s79, s79, 15
	v_mfma_f32_32x32x16_bf16 v[66:81], v[236:239], v[252:255], v[66:81]
	ds_read_b128 v[232:235], v212 offset:24576
	s_lshl_b32 s79, s79, 7
	s_add_u32 s70, s66, s79
	v_mfma_f32_32x32x16_bf16 v[50:65], v[240:243], v[248:251], v[50:65]
	ds_read_b128 v[216:219], v208 offset:20480
	s_addc_u32 s71, s67, 0
	s_add_u32 s72, s68, s79
	v_mfma_f32_32x32x16_bf16 v[34:49], v[236:239], v[248:251], v[34:49]
	ds_read_b128 v[228:231], v212 offset:28672
	s_addc_u32 s73, s69, 0
	s_add_u32 s77, s76, 0x6000
	s_add_u32 s78, s76, 0x10000
	s_waitcnt lgkmcnt(4)
	v_mfma_f32_32x32x16_bf16 v[18:33], v[240:243], v[244:247], v[18:33]
	ds_read_b128 v[224:227], v212 offset:32768
	v_mfma_f32_32x32x16_bf16 v[2:17], v[236:239], v[244:247], v[2:17]
	s_waitcnt vmcnt(0) lgkmcnt(0)
	s_barrier
	v_mfma_f32_32x32x16_bf16 v[82:97], v[220:223], v[232:235], v[82:97]
	s_add_u32 m0, s77, 0x0
	ds_read_b128 v[240:243], v211 offset:0
	global_load_lds_dwordx4 v207, s[70:71]
	s_add_u32 m0, s77, 0x1000
	s_nop 0
	global_load_lds_dwordx4 v206, s[70:71]
	v_mfma_f32_32x32x16_bf16 v[66:81], v[216:219], v[232:235], v[66:81]
	s_add_u32 m0, s77, 0x2000
	ds_read_b128 v[252:255], v215 offset:0
	global_load_lds_dwordx4 v205, s[70:71]
	s_add_u32 m0, s77, 0x3000
	s_nop 0
	global_load_lds_dwordx4 v204, s[70:71]
	v_mfma_f32_32x32x16_bf16 v[50:65], v[220:223], v[228:231], v[50:65]
	s_add_u32 m0, s77, 0x4000
	ds_read_b128 v[236:239], v211 offset:4096
	global_load_lds_dwordx4 v203, s[70:71]
	s_add_u32 m0, s77, 0x5000
	s_nop 0
	global_load_lds_dwordx4 v202, s[70:71]
	v_mfma_f32_32x32x16_bf16 v[34:49], v[216:219], v[228:231], v[34:49]
	s_add_u32 m0, s78, 0x0
	ds_read_b128 v[248:251], v215 offset:4096
	global_load_lds_dwordx4 v207, s[72:73]
	s_add_u32 m0, s78, 0x1000
	s_nop 0
	global_load_lds_dwordx4 v206, s[72:73]
	v_mfma_f32_32x32x16_bf16 v[18:33], v[220:223], v[224:227], v[18:33]
	s_add_u32 m0, s78, 0x2000
	ds_read_b128 v[244:247], v215 offset:8192
	global_load_lds_dwordx4 v205, s[72:73]
	s_add_u32 m0, s78, 0x3000
	s_nop 0
	global_load_lds_dwordx4 v204, s[72:73]
	v_mfma_f32_32x32x16_bf16 v[2:17], v[216:219], v[224:227], v[2:17]
	s_add_u32 s74, s74, 2
	s_cmp_lt_u32 s74, 14
	s_cbranch_scc1 .Lgm_ph13_loop
	s_waitcnt lgkmcnt(1)
	v_mfma_f32_32x32x16_bf16 v[82:97], v[240:243], v[252:255], v[82:97]
	ds_read_b128 v[220:223], v210 offset:0
	v_mfma_f32_32x32x16_bf16 v[66:81], v[236:239], v[252:255], v[66:81]
	ds_read_b128 v[232:235], v214 offset:0
	v_mfma_f32_32x32x16_bf16 v[50:65], v[240:243], v[248:251], v[50:65]
	ds_read_b128 v[216:219], v210 offset:4096
	v_mfma_f32_32x32x16_bf16 v[34:49], v[236:239], v[248:251], v[34:49]
	ds_read_b128 v[228:231], v214 offset:4096
	s_waitcnt lgkmcnt(4)
	v_mfma_f32_32x32x16_bf16 v[18:33], v[240:243], v[244:247], v[18:33]
	ds_read_b128 v[224:227], v214 offset:8192
	v_mfma_f32_32x32x16_bf16 v[2:17], v[236:239], v[244:247], v[2:17]
	s_waitcnt lgkmcnt(1)
	v_mfma_f32_32x32x16_bf16 v[82:97], v[220:223], v[232:235], v[82:97]
	ds_read_b128 v[240:243], v209 offset:0
	v_mfma_f32_32x32x16_bf16 v[66:81], v[216:219], v[232:235], v[66:81]
	ds_read_b128 v[252:255], v213 offset:0
	v_mfma_f32_32x32x16_bf16 v[50:65], v[220:223], v[228:231], v[50:65]
	ds_read_b128 v[236:239], v209 offset:4096
	v_mfma_f32_32x32x16_bf16 v[34:49], v[216:219], v[228:231], v[34:49]
	ds_read_b128 v[248:251], v213 offset:4096
	s_waitcnt lgkmcnt(4)
	v_mfma_f32_32x32x16_bf16 v[18:33], v[220:223], v[224:227], v[18:33]
	ds_read_b128 v[244:247], v213 offset:8192
	v_mfma_f32_32x32x16_bf16 v[2:17], v[216:219], v[224:227], v[2:17]
	s_waitcnt lgkmcnt(1)
	v_mfma_f32_32x32x16_bf16 v[82:97], v[240:243], v[252:255], v[82:97]
	ds_read_b128 v[220:223], v208 offset:0
	v_mfma_f32_32x32x16_bf16 v[66:81], v[236:239], v[252:255], v[66:81]
	ds_read_b128 v[232:235], v212 offset:0
	v_mfma_f32_32x32x16_bf16 v[50:65], v[240:243], v[248:251], v[50:65]
	ds_read_b128 v[216:219], v208 offset:4096
	v_mfma_f32_32x32x16_bf16 v[34:49], v[236:239], v[248:251], v[34:49]
	ds_read_b128 v[228:231], v212 offset:4096
	s_waitcnt lgkmcnt(4)
	v_mfma_f32_32x32x16_bf16 v[18:33], v[240:243], v[244:247], v[18:33]
	ds_read_b128 v[224:227], v212 offset:8192
	v_mfma_f32_32x32x16_bf16 v[2:17], v[236:239], v[244:247], v[2:17]
	s_waitcnt vmcnt(0) lgkmcnt(0)
	s_barrier
	v_mfma_f32_32x32x16_bf16 v[82:97], v[220:223], v[232:235], v[82:97]
	ds_read_b128 v[240:243], v211 offset:16384
	v_mfma_f32_32x32x16_bf16 v[66:81], v[216:219], v[232:235], v[66:81]
	ds_read_b128 v[252:255], v215 offset:24576
	v_mfma_f32_32x32x16_bf16 v[50:65], v[220:223], v[228:231], v[50:65]
	ds_read_b128 v[236:239], v211 offset:20480
	v_mfma_f32_32x32x16_bf16 v[34:49], v[216:219], v[228:231], v[34:49]
	ds_read_b128 v[248:251], v215 offset:28672
	v_mfma_f32_32x32x16_bf16 v[18:33], v[220:223], v[224:227], v[18:33]
	ds_read_b128 v[244:247], v215 offset:32768
	v_mfma_f32_32x32x16_bf16 v[2:17], v[216:219], v[224:227], v[2:17]
	s_waitcnt lgkmcnt(1)
	v_mfma_f32_32x32x16_bf16 v[82:97], v[240:243], v[252:255], v[82:97]
	ds_read_b128 v[220:223], v210 offset:16384
	v_mfma_f32_32x32x16_bf16 v[66:81], v[236:239], v[252:255], v[66:81]
	ds_read_b128 v[232:235], v214 offset:24576
	v_mfma_f32_32x32x16_bf16 v[50:65], v[240:243], v[248:251], v[50:65]
	ds_read_b128 v[216:219], v210 offset:20480
	v_mfma_f32_32x32x16_bf16 v[34:49], v[236:239], v[248:251], v[34:49]
	ds_read_b128 v[228:231], v214 offset:28672
	s_waitcnt lgkmcnt(4)
	v_mfma_f32_32x32x16_bf16 v[18:33], v[240:243], v[244:247], v[18:33]
	ds_read_b128 v[224:227], v214 offset:32768
	v_mfma_f32_32x32x16_bf16 v[2:17], v[236:239], v[244:247], v[2:17]
	s_waitcnt lgkmcnt(1)
	v_mfma_f32_32x32x16_bf16 v[82:97], v[220:223], v[232:235], v[82:97]
	ds_read_b128 v[240:243], v209 offset:16384
	v_mfma_f32_32x32x16_bf16 v[66:81], v[216:219], v[232:235], v[66:81]
	ds_read_b128 v[252:255], v213 offset:24576
	v_mfma_f32_32x32x16_bf16 v[50:65], v[220:223], v[228:231], v[50:65]
	ds_read_b128 v[236:239], v209 offset:20480
	v_mfma_f32_32x32x16_bf16 v[34:49], v[216:219], v[228:231], v[34:49]
	ds_read_b128 v[248:251], v213 offset:28672
	s_waitcnt lgkmcnt(4)
	v_mfma_f32_32x32x16_bf16 v[18:33], v[220:223], v[224:227], v[18:33]
	ds_read_b128 v[244:247], v213 offset:32768
	v_mfma_f32_32x32x16_bf16 v[2:17], v[216:219], v[224:227], v[2:17]
	s_waitcnt lgkmcnt(1)
	v_mfma_f32_32x32x16_bf16 v[82:97], v[240:243], v[252:255], v[82:97]
	ds_read_b128 v[220:223], v208 offset:16384
	v_mfma_f32_32x32x16_bf16 v[66:81], v[236:239], v[252:255], v[66:81]
	ds_read_b128 v[232:235], v212 offset:24576
	v_mfma_f32_32x32x16_bf16 v[50:65], v[240:243], v[248:251], v[50:65]
	ds_read_b128 v[216:219], v208 offset:20480
	v_mfma_f32_32x32x16_bf16 v[34:49], v[236:239], v[248:251], v[34:49]
	ds_read_b128 v[228:231], v212 offset:28672
	s_waitcnt lgkmcnt(4)
	v_mfma_f32_32x32x16_bf16 v[18:33], v[240:243], v[244:247], v[18:33]
	ds_read_b128 v[224:227], v212 offset:32768
	v_mfma_f32_32x32x16_bf16 v[2:17], v[236:239], v[244:247], v[2:17]
	s_waitcnt vmcnt(0) lgkmcnt(0)
	s_barrier
	v_mfma_f32_32x32x16_bf16 v[82:97], v[220:223], v[232:235], v[82:97]
	v_mfma_f32_32x32x16_bf16 v[66:81], v[216:219], v[232:235], v[66:81]
	v_mfma_f32_32x32x16_bf16 v[50:65], v[220:223], v[228:231], v[50:65]
	v_mfma_f32_32x32x16_bf16 v[34:49], v[216:219], v[228:231], v[34:49]
	v_mfma_f32_32x32x16_bf16 v[18:33], v[220:223], v[224:227], v[18:33]
	v_mfma_f32_32x32x16_bf16 v[2:17], v[216:219], v[224:227], v[2:17]
	s_nop 7
	s_nop 7
	s_and_b32 s5, s5, 0x1fffff8
	s_nop 4
	s_cmp_eq_u32 s5, 16
	s_nop 4
	s_cselect_b64 s[50:51], -1, 0
	s_nop 4
	s_cmpk_gt_u32 s4, 0x7ff
	s_nop 4
	s_cselect_b64 s[48:49], -1, 0
	s_nop 4
	s_cmpk_gt_u32 s4, 0xbff
	s_nop 4
	s_cselect_b64 s[46:47], -1, 0
	s_nop 4
	s_mov_b64 s[52:53], -1
	s_nop 4
	s_and_b64 vcc, exec, s[50:51]
	s_nop 4
	v_add_u32_e32 v109, s6, v119
	s_nop 4
	v_or_b32_e32 v100, s4, v127
	s_waitcnt lgkmcnt(0)
	s_nop 11
	ds_write_b128 v140, v[82:85]
	ds_write_b128 v140, v[86:89] offset:32
	ds_write_b128 v140, v[90:93] offset:64
	ds_write_b128 v140, v[94:97] offset:96
	s_nop 11
	ds_write_b128 v140, v[66:69] offset:128
	ds_write_b128 v140, v[70:73] offset:160
	ds_write_b128 v140, v[74:77] offset:192
	ds_write_b128 v140, v[78:81] offset:224
	s_waitcnt lgkmcnt(0)
	v_add_u32_e32 v112, v128, v100
	v_or_b32_e32 v100, v100, v131
	v_cmp_lt_i32_e64 s[6:7], s3, v100
	s_cbranch_vccz .LBB0_1278
	v_mov_b32_e32 v80, 0x880
	v_cmp_gt_i32_e64 s[52:53], s57, v109
	v_mov_b32_e32 v81, 0x990
	v_mov_b32_e32 v79, 0xaa0
	v_mov_b32_e32 v78, 0xbb0
	ds_read2_b32 v[70:71], v129 offset1:68
	ds_read2_b32 v[72:73], v129 offset0:136 offset1:204
	v_cndmask_b32_e64 v82, v141, v80, s[52:53]
	v_cndmask_b32_e64 v83, v142, v81, s[52:53]
	v_cndmask_b32_e64 v84, v143, v79, s[52:53]
	v_cndmask_b32_e64 v85, v144, v78, s[52:53]
	v_add_u32_e32 v66, 0xfffff000, v109
	v_ashrrev_i32_e32 v68, 8, v109
	v_add_u32_e32 v82, v129, v82
	v_add_u32_e32 v83, v129, v83
	v_add_u32_e32 v84, v129, v84
	v_add_u32_e32 v85, v129, v85
	v_lshrrev_b32_e32 v66, 11, v66
	v_and_b32_e32 v67, 0x7e0, v109
	v_ashrrev_i32_e32 v69, 31, v68
	ds_read_b32 v82, v82
	ds_read_b32 v83, v83
	ds_read_b32 v84, v84
	ds_read_b32 v85, v85
	v_add_u32_e32 v76, 0x100, v67
	v_mad_u64_u32 v[66:67], s[4:5], v66, s59, v[110:111]
	v_lshlrev_b64 v[68:69], 18, v[68:69]
	v_and_b32_e32 v77, 0xe0, v109
	v_cndmask_b32_e64 v75, v67, v69, s[52:53]
	v_cndmask_b32_e64 v74, v66, v68, s[52:53]
	v_cndmask_b32_e64 v86, v145, v147, s[52:53]
	v_cndmask_b32_e64 v87, v76, v77, s[52:53]
	s_waitcnt lgkmcnt(0)
	v_cvt_pk_bf16_f32 v70, v70, v71
	v_cvt_pk_bf16_f32 v71, v72, v73
	v_cvt_pk_bf16_f32 v72, v82, v83
	v_lshl_add_u64 v[74:75], v[74:75], 1, s[24:25]
	v_mad_u64_u32 v[82:83], s[4:5], v86, v112, 0
	v_lshl_add_u64 v[74:75], v[82:83], 1, v[74:75]
	v_lshlrev_b32_e32 v82, 1, v87
	v_mov_b32_e32 v83, v101
	v_cvt_pk_bf16_f32 v73, v84, v85
	v_lshl_add_u64 v[74:75], v[74:75], 0, v[82:83]
	global_store_dwordx4 v[74:75], v[70:73], off
	v_mov_b32_e32 v84, 0x1540
	v_mov_b32_e32 v83, 0x1650
	v_mov_b64_e32 v[70:71], 0x900
	v_mov_b64_e32 v[72:73], 0x900
	v_mov_b32_e32 v82, 0x1760
	v_mov_b32_e32 v71, 0x1870
	v_mov_b64_e32 v[74:75], v[66:67]
	v_mov_b32_e32 v73, v76
	s_and_saveexec_b64 s[4:5], s[52:53]
	s_cbranch_execz .LBB0_1275
	v_mov_b64_e32 v[72:73], 0x100
	v_mov_b32_e32 v78, 0x770
	v_mov_b32_e32 v79, 0x660
	v_mov_b32_e32 v81, 0x550
	v_mov_b32_e32 v80, 0x440
	v_mov_b32_e32 v84, 0x1980
	v_mov_b32_e32 v83, 0x1a90
	v_mov_b32_e32 v82, 0x1ba0
	v_mov_b32_e32 v71, 0x1cb0
	v_mov_b64_e32 v[74:75], v[68:69]
	v_mov_b32_e32 v73, v77

.LBB0_1859:
	s_ashr_i32 s10, s28, 31
	s_lshr_b32 s10, s10, 26
	s_add_i32 s10, s28, s10
	s_ashr_i32 s31, s10, 6
	s_and_b32 s10, s10, 0x3ffffc0
	s_sub_i32 s29, s28, s10
	s_mulk_i32 s29, 0xc0
	v_add_u32_e32 v2, s29, v108
	s_lshr_b32 s10, s29, 6
	s_lshl_b32 s30, s31, 7
	v_ashrrev_i32_e32 v3, 31, v2
	s_add_i32 s10, s10, s31
	v_lshlrev_b64 v[2:3], 11, v[2:3]
	v_or_b32_e32 v4, s30, v108
	s_lshl_b32 s31, s10, 6
	s_lshl_b32 s10, s10, 7
	v_ashrrev_i32_e32 v5, 31, v4
	v_lshl_add_u64 v[104:105], v[100:101], 0, v[2:3]
	s_and_b32 s10, s10, 0x780
	v_readfirstlane_b32 s34, v109
	v_lshlrev_b64 v[4:5], 11, v[4:5]
	v_lshl_add_u64 v[2:3], v[104:105], 0, s[10:11]
	s_mov_b32 m0, s34
	v_readfirstlane_b32 s34, v128
	v_lshl_add_u64 v[106:107], v[102:103], 0, v[4:5]
	s_waitcnt vmcnt(0)
	s_barrier
	s_load_dwordx2 s[66:67], s[0:1], 0x178
	s_load_dwordx2 s[68:69], s[0:1], 0x100
	v_and_b32_e32 v201, 0x3ff, v0
	v_readfirstlane_b32 s76, v0
	v_and_b32_e32 v200, 31, v201
	v_bfe_u32 v214, v201, 1, 3
	v_bfe_u32 v213, v201, 5, 1
	v_xor_b32_e32 v214, v214, v213
	v_lshlrev_b32_e32 v214, 4, v214
	s_and_b32 s76, s76, 0x3ff
	s_lshr_b32 s79, s76, 6
	s_lshl_b32 s76, s76, 4
	s_lshr_b32 s80, s79, 1
	s_and_b32 s79, s79, 1
	s_mul_i32 s80, s80, 0x3000
	s_lshl_b32 s79, s79, 13
	s_add_u32 s79, s79, 0xc000
	v_lshlrev_b32_e32 v200, 7, v200
	v_or_b32_e32 v200, v200, v214
	v_add_u32_e32 v215, s80, v200
	v_add_u32_e32 v211, s79, v200
	v_xor_b32_e32 v214, 0x20, v215
	v_xor_b32_e32 v210, 0x20, v211
	v_xor_b32_e32 v213, 0x40, v215
	v_xor_b32_e32 v209, 0x40, v211
	v_xor_b32_e32 v212, 0x60, v215
	v_xor_b32_e32 v208, 0x60, v211
	v_bfe_u32 v200, v201, 4, 3
	v_and_b32_e32 v206, 7, v201
	v_xor_b32_e32 v200, v200, v206
	v_lshlrev_b32_e32 v200, 4, v200
	v_lshrrev_b32_e32 v206, 3, v201
	v_lshl_or_b32 v207, v206, 11, v200
	v_add_u32_e32 v206, 0x10000, v207
	v_add_u32_e32 v205, 0x20000, v207
	v_add_u32_e32 v204, 0x30000, v207
	v_add_u32_e32 v203, 0x40000, v207
	v_add_u32_e32 v202, 0x50000, v207
	s_lshr_b32 s79, s28, 6
	s_and_b32 s80, s28, 63
	s_mov_b32 s75, 0
	s_mul_i32 s80, s80, 0x60000
	s_lshl_b32 s79, s79, 18
	s_waitcnt lgkmcnt(0)
	s_add_u32 s66, s66, s80
	s_addc_u32 s67, s67, 0
	s_add_u32 s68, s68, s79
	s_addc_u32 s69, s69, 0
	s_add_u32 s79, s75, 0
	s_and_b32 s79, s79, 15
	s_lshl_b32 s79, s79, 7
	s_add_u32 s70, s66, s79
	s_addc_u32 s71, s67, 0
	s_add_u32 s72, s68, s79
	s_addc_u32 s73, s69, 0
	s_add_u32 s77, s76, 0x0
	s_add_u32 s78, s76, 0xc000
	s_add_u32 m0, s77, 0x0
	s_nop 0
	global_load_lds_dwordx4 v207, s[70:71]
	s_add_u32 m0, s77, 0x1000
	s_nop 0
	global_load_lds_dwordx4 v206, s[70:71]
	s_add_u32 m0, s77, 0x2000
	s_nop 0
	global_load_lds_dwordx4 v205, s[70:71]
	s_add_u32 m0, s77, 0x3000
	s_nop 0
	global_load_lds_dwordx4 v204, s[70:71]
	s_add_u32 m0, s77, 0x4000
	s_nop 0
	global_load_lds_dwordx4 v203, s[70:71]
	s_add_u32 m0, s77, 0x5000
	s_nop 0
	global_load_lds_dwordx4 v202, s[70:71]
	s_add_u32 m0, s78, 0x0
	s_nop 0
	global_load_lds_dwordx4 v207, s[72:73]
	s_add_u32 m0, s78, 0x1000
	s_nop 0
	global_load_lds_dwordx4 v206, s[72:73]
	s_add_u32 m0, s78, 0x2000
	s_nop 0
	global_load_lds_dwordx4 v205, s[72:73]
	s_add_u32 m0, s78, 0x3000
	s_nop 0
	global_load_lds_dwordx4 v204, s[72:73]
	s_add_u32 s79, s75, 1
	s_and_b32 s79, s79, 15
	s_lshl_b32 s79, s79, 7
	s_add_u32 s70, s66, s79
	s_addc_u32 s71, s67, 0
	s_add_u32 s72, s68, s79
	s_addc_u32 s73, s69, 0
	s_add_u32 s77, s76, 0x6000
	s_add_u32 s78, s76, 0x10000
	s_add_u32 m0, s77, 0x0
	s_nop 0
	global_load_lds_dwordx4 v207, s[70:71]
	s_add_u32 m0, s77, 0x1000
	s_nop 0
	global_load_lds_dwordx4 v206, s[70:71]
	s_add_u32 m0, s77, 0x2000
	s_nop 0
	global_load_lds_dwordx4 v205, s[70:71]
	s_add_u32 m0, s77, 0x3000
	s_nop 0
	global_load_lds_dwordx4 v204, s[70:71]
	s_add_u32 m0, s77, 0x4000
	s_nop 0
	global_load_lds_dwordx4 v203, s[70:71]
	s_add_u32 m0, s77, 0x5000
	s_nop 0
	global_load_lds_dwordx4 v202, s[70:71]
	s_add_u32 m0, s78, 0x0
	s_nop 0
	global_load_lds_dwordx4 v207, s[72:73]
	s_add_u32 m0, s78, 0x1000
	s_nop 0
	global_load_lds_dwordx4 v206, s[72:73]
	s_add_u32 m0, s78, 0x2000
	s_nop 0
	global_load_lds_dwordx4 v205, s[72:73]
	s_add_u32 m0, s78, 0x3000
	s_nop 0
	global_load_lds_dwordx4 v204, s[72:73]
	v_mov_b32_e32 v2, 0
	v_mov_b32_e32 v3, 0
	v_mov_b32_e32 v4, 0
	v_mov_b32_e32 v5, 0
	v_mov_b32_e32 v6, 0
	v_mov_b32_e32 v7, 0
	v_mov_b32_e32 v8, 0
	v_mov_b32_e32 v9, 0
	v_mov_b32_e32 v10, 0
	v_mov_b32_e32 v11, 0
	v_mov_b32_e32 v12, 0
	v_mov_b32_e32 v13, 0
	v_mov_b32_e32 v14, 0
	v_mov_b32_e32 v15, 0
	v_mov_b32_e32 v16, 0
	v_mov_b32_e32 v17, 0
	v_mov_b32_e32 v18, 0
	v_mov_b32_e32 v19, 0
	v_mov_b32_e32 v20, 0
	v_mov_b32_e32 v21, 0
	v_mov_b32_e32 v22, 0
	v_mov_b32_e32 v23, 0
	v_mov_b32_e32 v24, 0
	v_mov_b32_e32 v25, 0
	v_mov_b32_e32 v26, 0
	v_mov_b32_e32 v27, 0
	v_mov_b32_e32 v28, 0
	v_mov_b32_e32 v29, 0
	v_mov_b32_e32 v30, 0
	v_mov_b32_e32 v31, 0
	v_mov_b32_e32 v32, 0
	v_mov_b32_e32 v33, 0
	v_mov_b32_e32 v34, 0
	v_mov_b32_e32 v35, 0
	v_mov_b32_e32 v36, 0
	v_mov_b32_e32 v37, 0
	v_mov_b32_e32 v38, 0
	v_mov_b32_e32 v39, 0
	v_mov_b32_e32 v40, 0
	v_mov_b32_e32 v41, 0
	v_mov_b32_e32 v42, 0
	v_mov_b32_e32 v43, 0
	v_mov_b32_e32 v44, 0
	v_mov_b32_e32 v45, 0
	v_mov_b32_e32 v46, 0
	v_mov_b32_e32 v47, 0
	v_mov_b32_e32 v48, 0
	v_mov_b32_e32 v49, 0
	v_mov_b32_e32 v50, 0
	v_mov_b32_e32 v51, 0
	v_mov_b32_e32 v52, 0
	v_mov_b32_e32 v53, 0
	v_mov_b32_e32 v54, 0
	v_mov_b32_e32 v55, 0
	v_mov_b32_e32 v56, 0
	v_mov_b32_e32 v57, 0
	v_mov_b32_e32 v58, 0
	v_mov_b32_e32 v59, 0
	v_mov_b32_e32 v60, 0
	v_mov_b32_e32 v61, 0
	v_mov_b32_e32 v62, 0
	v_mov_b32_e32 v63, 0
	v_mov_b32_e32 v64, 0
	v_mov_b32_e32 v65, 0
	v_mov_b32_e32 v66, 0
	v_mov_b32_e32 v67, 0
	v_mov_b32_e32 v68, 0
	v_mov_b32_e32 v69, 0
	v_mov_b32_e32 v70, 0
	v_mov_b32_e32 v71, 0
	v_mov_b32_e32 v72, 0
	v_mov_b32_e32 v73, 0
	v_mov_b32_e32 v74, 0
	v_mov_b32_e32 v75, 0
	v_mov_b32_e32 v76, 0
	v_mov_b32_e32 v77, 0
	v_mov_b32_e32 v78, 0
	v_mov_b32_e32 v79, 0
	v_mov_b32_e32 v80, 0
	v_mov_b32_e32 v81, 0
	v_mov_b32_e32 v82, 0
	v_mov_b32_e32 v83, 0
	v_mov_b32_e32 v84, 0
	v_mov_b32_e32 v85, 0
	v_mov_b32_e32 v86, 0
	v_mov_b32_e32 v87, 0
	v_mov_b32_e32 v88, 0
	v_mov_b32_e32 v89, 0
	v_mov_b32_e32 v90, 0
	v_mov_b32_e32 v91, 0
	v_mov_b32_e32 v92, 0
	v_mov_b32_e32 v93, 0
	v_mov_b32_e32 v94, 0
	v_mov_b32_e32 v95, 0
	v_mov_b32_e32 v96, 0
	v_mov_b32_e32 v97, 0
	s_waitcnt vmcnt(10)
	s_barrier
	ds_read_b128 v[240:243], v211 offset:0
	ds_read_b128 v[252:255], v215 offset:0
	ds_read_b128 v[236:239], v211 offset:4096
	ds_read_b128 v[248:251], v215 offset:4096
	ds_read_b128 v[244:247], v215 offset:8192
	s_mov_b32 s74, 0

.LBB0_1992:
	s_ashr_i32 s4, s35, 31
	s_lshr_b32 s4, s4, 26
	s_add_i32 s4, s35, s4
	s_ashr_i32 s6, s4, 6
	s_and_b32 s4, s4, 0x3ffffc0
	s_sub_i32 s4, s35, s4
	s_mulk_i32 s4, 0xc0
	v_add_u32_e32 v2, s4, v112
	s_lshr_b32 s7, s4, 6
	s_lshl_b32 s5, s6, 7
	v_ashrrev_i32_e32 v3, 31, v2
	s_add_i32 s7, s7, s6
	v_lshlrev_b64 v[2:3], 11, v[2:3]
	v_or_b32_e32 v4, s5, v112
	s_lshl_b32 s6, s7, 6
	s_lshl_b32 s7, s7, 7
	v_ashrrev_i32_e32 v5, 31, v4
	v_lshl_add_u64 v[104:105], v[100:101], 0, v[2:3]
	s_and_b32 s14, s7, 0x780
	v_readfirstlane_b32 s7, v113
	v_lshlrev_b64 v[4:5], 11, v[4:5]
	v_lshl_add_u64 v[2:3], v[104:105], 0, s[14:15]
	s_mov_b32 m0, s7
	v_readfirstlane_b32 s7, v125
	v_lshl_add_u64 v[106:107], v[102:103], 0, v[4:5]
	s_waitcnt vmcnt(0)
	s_barrier
	s_load_dwordx2 s[66:67], s[0:1], 0x90
	s_load_dwordx2 s[68:69], s[0:1], 0xc0
	v_and_b32_e32 v201, 0x3ff, v0
	v_readfirstlane_b32 s76, v0
	v_and_b32_e32 v200, 31, v201
	v_bfe_u32 v214, v201, 1, 3
	v_bfe_u32 v213, v201, 5, 1
	v_xor_b32_e32 v214, v214, v213
	v_lshlrev_b32_e32 v214, 4, v214
	s_and_b32 s76, s76, 0x3ff
	s_lshr_b32 s79, s76, 6
	s_lshl_b32 s76, s76, 4
	s_lshr_b32 s80, s79, 1
	s_and_b32 s79, s79, 1
	s_mul_i32 s80, s80, 0x3000
	s_lshl_b32 s79, s79, 13
	s_add_u32 s79, s79, 0xc000
	v_lshlrev_b32_e32 v200, 7, v200
	v_or_b32_e32 v200, v200, v214
	v_add_u32_e32 v215, s80, v200
	v_add_u32_e32 v211, s79, v200
	v_xor_b32_e32 v214, 0x20, v215
	v_xor_b32_e32 v210, 0x20, v211
	v_xor_b32_e32 v213, 0x40, v215
	v_xor_b32_e32 v209, 0x40, v211
	v_xor_b32_e32 v212, 0x60, v215
	v_xor_b32_e32 v208, 0x60, v211
	v_bfe_u32 v200, v201, 4, 3
	v_and_b32_e32 v206, 7, v201
	v_xor_b32_e32 v200, v200, v206
	v_lshlrev_b32_e32 v200, 4, v200
	v_lshrrev_b32_e32 v206, 3, v201
	v_lshl_or_b32 v207, v206, 11, v200
	v_add_u32_e32 v206, 0x10000, v207
	v_add_u32_e32 v205, 0x20000, v207
	v_add_u32_e32 v204, 0x30000, v207
	v_add_u32_e32 v203, 0x40000, v207
	v_add_u32_e32 v202, 0x50000, v207
	s_lshr_b32 s79, s35, 6
	s_and_b32 s80, s35, 63
	s_mov_b32 s75, 0
	s_mul_i32 s80, s80, 0x60000
	s_lshl_b32 s79, s79, 18
	s_add_u32 s79, s79, 0x400000
	s_waitcnt lgkmcnt(0)
	s_add_u32 s66, s66, s80
	s_addc_u32 s67, s67, 0
	s_add_u32 s68, s68, s79
	s_addc_u32 s69, s69, 0
	s_add_u32 s79, s75, 0
	s_and_b32 s79, s79, 15
	s_lshl_b32 s79, s79, 7
	s_add_u32 s70, s66, s79
	s_addc_u32 s71, s67, 0
	s_add_u32 s72, s68, s79
	s_addc_u32 s73, s69, 0
	s_add_u32 s77, s76, 0x0
	s_add_u32 s78, s76, 0xc000
	s_add_u32 m0, s77, 0x0
	s_nop 0
	global_load_lds_dwordx4 v207, s[70:71]
	s_add_u32 m0, s77, 0x1000
	s_nop 0
	global_load_lds_dwordx4 v206, s[70:71]
	s_add_u32 m0, s77, 0x2000
	s_nop 0
	global_load_lds_dwordx4 v205, s[70:71]
	s_add_u32 m0, s77, 0x3000
	s_nop 0
	global_load_lds_dwordx4 v204, s[70:71]
	s_add_u32 m0, s77, 0x4000
	s_nop 0
	global_load_lds_dwordx4 v203, s[70:71]
	s_add_u32 m0, s77, 0x5000
	s_nop 0
	global_load_lds_dwordx4 v202, s[70:71]
	s_add_u32 m0, s78, 0x0
	s_nop 0
	global_load_lds_dwordx4 v207, s[72:73]
	s_add_u32 m0, s78, 0x1000
	s_nop 0
	global_load_lds_dwordx4 v206, s[72:73]
	s_add_u32 m0, s78, 0x2000
	s_nop 0
	global_load_lds_dwordx4 v205, s[72:73]
	s_add_u32 m0, s78, 0x3000
	s_nop 0
	global_load_lds_dwordx4 v204, s[72:73]
	s_add_u32 s79, s75, 1
	s_and_b32 s79, s79, 15
	s_lshl_b32 s79, s79, 7
	s_add_u32 s70, s66, s79
	s_addc_u32 s71, s67, 0
	s_add_u32 s72, s68, s79
	s_addc_u32 s73, s69, 0
	s_add_u32 s77, s76, 0x6000
	s_add_u32 s78, s76, 0x10000
	s_add_u32 m0, s77, 0x0
	s_nop 0
	global_load_lds_dwordx4 v207, s[70:71]
	s_add_u32 m0, s77, 0x1000
	s_nop 0
	global_load_lds_dwordx4 v206, s[70:71]
	s_add_u32 m0, s77, 0x2000
	s_nop 0
	global_load_lds_dwordx4 v205, s[70:71]
	s_add_u32 m0, s77, 0x3000
	s_nop 0
	global_load_lds_dwordx4 v204, s[70:71]
	s_add_u32 m0, s77, 0x4000
	s_nop 0
	global_load_lds_dwordx4 v203, s[70:71]
	s_add_u32 m0, s77, 0x5000
	s_nop 0
	global_load_lds_dwordx4 v202, s[70:71]
	s_add_u32 m0, s78, 0x0
	s_nop 0
	global_load_lds_dwordx4 v207, s[72:73]
	s_add_u32 m0, s78, 0x1000
	s_nop 0
	global_load_lds_dwordx4 v206, s[72:73]
	s_add_u32 m0, s78, 0x2000
	s_nop 0
	global_load_lds_dwordx4 v205, s[72:73]
	s_add_u32 m0, s78, 0x3000
	s_nop 0
	global_load_lds_dwordx4 v204, s[72:73]
	v_mov_b32_e32 v2, 0
	v_mov_b32_e32 v3, 0
	v_mov_b32_e32 v4, 0
	v_mov_b32_e32 v5, 0
	v_mov_b32_e32 v6, 0
	v_mov_b32_e32 v7, 0
	v_mov_b32_e32 v8, 0
	v_mov_b32_e32 v9, 0
	v_mov_b32_e32 v10, 0
	v_mov_b32_e32 v11, 0
	v_mov_b32_e32 v12, 0
	v_mov_b32_e32 v13, 0
	v_mov_b32_e32 v14, 0
	v_mov_b32_e32 v15, 0
	v_mov_b32_e32 v16, 0
	v_mov_b32_e32 v17, 0
	v_mov_b32_e32 v18, 0
	v_mov_b32_e32 v19, 0
	v_mov_b32_e32 v20, 0
	v_mov_b32_e32 v21, 0
	v_mov_b32_e32 v22, 0
	v_mov_b32_e32 v23, 0
	v_mov_b32_e32 v24, 0
	v_mov_b32_e32 v25, 0
	v_mov_b32_e32 v26, 0
	v_mov_b32_e32 v27, 0
	v_mov_b32_e32 v28, 0
	v_mov_b32_e32 v29, 0
	v_mov_b32_e32 v30, 0
	v_mov_b32_e32 v31, 0
	v_mov_b32_e32 v32, 0
	v_mov_b32_e32 v33, 0
	v_mov_b32_e32 v34, 0
	v_mov_b32_e32 v35, 0
	v_mov_b32_e32 v36, 0
	v_mov_b32_e32 v37, 0
	v_mov_b32_e32 v38, 0
	v_mov_b32_e32 v39, 0
	v_mov_b32_e32 v40, 0
	v_mov_b32_e32 v41, 0
	v_mov_b32_e32 v42, 0
	v_mov_b32_e32 v43, 0
	v_mov_b32_e32 v44, 0
	v_mov_b32_e32 v45, 0
	v_mov_b32_e32 v46, 0
	v_mov_b32_e32 v47, 0
	v_mov_b32_e32 v48, 0
	v_mov_b32_e32 v49, 0
	v_mov_b32_e32 v50, 0
	v_mov_b32_e32 v51, 0
	v_mov_b32_e32 v52, 0
	v_mov_b32_e32 v53, 0
	v_mov_b32_e32 v54, 0
	v_mov_b32_e32 v55, 0
	v_mov_b32_e32 v56, 0
	v_mov_b32_e32 v57, 0
	v_mov_b32_e32 v58, 0
	v_mov_b32_e32 v59, 0
	v_mov_b32_e32 v60, 0
	v_mov_b32_e32 v61, 0
	v_mov_b32_e32 v62, 0
	v_mov_b32_e32 v63, 0
	v_mov_b32_e32 v64, 0
	v_mov_b32_e32 v65, 0
	v_mov_b32_e32 v66, 0
	v_mov_b32_e32 v67, 0
	v_mov_b32_e32 v68, 0
	v_mov_b32_e32 v69, 0
	v_mov_b32_e32 v70, 0
	v_mov_b32_e32 v71, 0
	v_mov_b32_e32 v72, 0
	v_mov_b32_e32 v73, 0
	v_mov_b32_e32 v74, 0
	v_mov_b32_e32 v75, 0
	v_mov_b32_e32 v76, 0
	v_mov_b32_e32 v77, 0
	v_mov_b32_e32 v78, 0
	v_mov_b32_e32 v79, 0
	v_mov_b32_e32 v80, 0
	v_mov_b32_e32 v81, 0
	v_mov_b32_e32 v82, 0
	v_mov_b32_e32 v83, 0
	v_mov_b32_e32 v84, 0
	v_mov_b32_e32 v85, 0
	v_mov_b32_e32 v86, 0
	v_mov_b32_e32 v87, 0
	v_mov_b32_e32 v88, 0
	v_mov_b32_e32 v89, 0
	v_mov_b32_e32 v90, 0
	v_mov_b32_e32 v91, 0
	v_mov_b32_e32 v92, 0
	v_mov_b32_e32 v93, 0
	v_mov_b32_e32 v94, 0
	v_mov_b32_e32 v95, 0
	v_mov_b32_e32 v96, 0
	v_mov_b32_e32 v97, 0
	s_waitcnt vmcnt(10)
	s_barrier
	ds_read_b128 v[240:243], v211 offset:0
	ds_read_b128 v[252:255], v215 offset:0
	ds_read_b128 v[236:239], v211 offset:4096
	ds_read_b128 v[248:251], v215 offset:4096
	ds_read_b128 v[244:247], v215 offset:8192
	s_mov_b32 s74, 0
.Lgm_ph17_loop:
	s_waitcnt lgkmcnt(1)
	v_mfma_f32_32x32x16_bf16 v[82:97], v[240:243], v[252:255], v[82:97]
	ds_read_b128 v[220:223], v210 offset:0
	v_mfma_f32_32x32x16_bf16 v[66:81], v[236:239], v[252:255], v[66:81]
	ds_read_b128 v[232:235], v214 offset:0
	v_mfma_f32_32x32x16_bf16 v[50:65], v[240:243], v[248:251], v[50:65]
	ds_read_b128 v[216:219], v210 offset:4096
	v_mfma_f32_32x32x16_bf16 v[34:49], v[236:239], v[248:251], v[34:49]
	ds_read_b128 v[228:231], v214 offset:4096
	s_waitcnt lgkmcnt(4)
	v_mfma_f32_32x32x16_bf16 v[18:33], v[240:243], v[244:247], v[18:33]
	ds_read_b128 v[224:227], v214 offset:8192
	v_mfma_f32_32x32x16_bf16 v[2:17], v[236:239], v[244:247], v[2:17]
	s_waitcnt lgkmcnt(1)
	v_mfma_f32_32x32x16_bf16 v[82:97], v[220:223], v[232:235], v[82:97]
	ds_read_b128 v[240:243], v209 offset:0
	v_mfma_f32_32x32x16_bf16 v[66:81], v[216:219], v[232:235], v[66:81]
	ds_read_b128 v[252:255], v213 offset:0
	v_mfma_f32_32x32x16_bf16 v[50:65], v[220:223], v[228:231], v[50:65]
	ds_read_b128 v[236:239], v209 offset:4096
	v_mfma_f32_32x32x16_bf16 v[34:49], v[216:219], v[228:231], v[34:49]
	ds_read_b128 v[248:251], v213 offset:4096
	s_waitcnt lgkmcnt(4)
	v_mfma_f32_32x32x16_bf16 v[18:33], v[220:223], v[224:227], v[18:33]
	ds_read_b128 v[244:247], v213 offset:8192
	v_mfma_f32_32x32x16_bf16 v[2:17], v[216:219], v[224:227], v[2:17]
	s_waitcnt lgkmcnt(1)
	v_mfma_f32_32x32x16_bf16 v[82:97], v[240:243], v[252:255], v[82:97]
	ds_read_b128 v[220:223], v208 offset:0
	s_add_u32 s79, s75, s74
	s_add_u32 s79, s79, 2
	s_and_b32 s79, s79, 15
	v_mfma_f32_32x32x16_bf16 v[66:81], v[236:239], v[252:255], v[66:81]
	ds_read_b128 v[232:235], v212 offset:0
	s_lshl_b32 s79, s79, 7
	s_add_u32 s70, s66, s79
	v_mfma_f32_32x32x16_bf16 v[50:65], v[240:243], v[248:251], v[50:65]
	ds_read_b128 v[216:219], v208 offset:4096
	s_addc_u32 s71, s67, 0
	s_add_u32 s72, s68, s79
	v_mfma_f32_32x32x16_bf16 v[34:49], v[236:239], v[248:251], v[34:49]
	ds_read_b128 v[228:231], v212 offset:4096
	s_addc_u32 s73, s69, 0
	s_add_u32 s77, s76, 0x0
	s_add_u32 s78, s76, 0xc000
	s_waitcnt lgkmcnt(4)
	v_mfma_f32_32x32x16_bf16 v[18:33], v[240:243], v[244:247], v[18:33]
	ds_read_b128 v[224:227], v212 offset:8192
	v_mfma_f32_32x32x16_bf16 v[2:17], v[236:239], v[244:247], v[2:17]
	s_waitcnt vmcnt(0) lgkmcnt(0)
	s_barrier
	v_mfma_f32_32x32x16_bf16 v[82:97], v[220:223], v[232:235], v[82:97]
	s_add_u32 m0, s77, 0x0
	ds_read_b128 v[240:243], v211 offset:16384
	global_load_lds_dwordx4 v207, s[70:71]
	s_add_u32 m0, s77, 0x1000
	s_nop 0
	global_load_lds_dwordx4 v206, s[70:71]
	v_mfma_f32_32x32x16_bf16 v[66:81], v[216:219], v[232:235], v[66:81]
	s_add_u32 m0, s77, 0x2000
	ds_read_b128 v[252:255], v215 offset:24576
	global_load_lds_dwordx4 v205, s[70:71]
	s_add_u32 m0, s77, 0x3000
	s_nop 0
	global_load_lds_dwordx4 v204, s[70:71]
	v_mfma_f32_32x32x16_bf16 v[50:65], v[220:223], v[228:231], v[50:65]
	s_add_u32 m0, s77, 0x4000
	ds_read_b128 v[236:239], v211 offset:20480
	global_load_lds_dwordx4 v203, s[70:71]
	s_add_u32 m0, s77, 0x5000
	s_nop 0
	global_load_lds_dwordx4 v202, s[70:71]
	v_mfma_f32_32x32x16_bf16 v[34:49], v[216:219], v[228:231], v[34:49]
	s_add_u32 m0, s78, 0x0
	ds_read_b128 v[248:251], v215 offset:28672
	global_load_lds_dwordx4 v207, s[72:73]
	s_add_u32 m0, s78, 0x1000
	s_nop 0
	global_load_lds_dwordx4 v206, s[72:73]
	v_mfma_f32_32x32x16_bf16 v[18:33], v[220:223], v[224:227], v[18:33]
	s_add_u32 m0, s78, 0x2000
	ds_read_b128 v[244:247], v215 offset:32768
	global_load_lds_dwordx4 v205, s[72:73]
	s_add_u32 m0, s78, 0x3000
	s_nop 0
	global_load_lds_dwordx4 v204, s[72:73]
	v_mfma_f32_32x32x16_bf16 v[2:17], v[216:219], v[224:227], v[2:17]
	s_waitcnt lgkmcnt(1)
	v_mfma_f32_32x32x16_bf16 v[82:97], v[240:243], v[252:255], v[82:97]
	ds_read_b128 v[220:223], v210 offset:16384
	v_mfma_f32_32x32x16_bf16 v[66:81], v[236:239], v[252:255], v[66:81]
	ds_read_b128 v[232:235], v214 offset:24576
	v_mfma_f32_32x32x16_bf16 v[50:65], v[240:243], v[248:251], v[50:65]
	ds_read_b128 v[216:219], v210 offset:20480
	v_mfma_f32_32x32x16_bf16 v[34:49], v[236:239], v[248:251], v[34:49]
	ds_read_b128 v[228:231], v214 offset:28672
	s_waitcnt lgkmcnt(4)
	v_mfma_f32_32x32x16_bf16 v[18:33], v[240:243], v[244:247], v[18:33]
	ds_read_b128 v[224:227], v214 offset:32768
	v_mfma_f32_32x32x16_bf16 v[2:17], v[236:239], v[244:247], v[2:17]
	s_waitcnt lgkmcnt(1)
	v_mfma_f32_32x32x16_bf16 v[82:97], v[220:223], v[232:235], v[82:97]
	ds_read_b128 v[240:243], v209 offset:16384
	v_mfma_f32_32x32x16_bf16 v[66:81], v[216:219], v[232:235], v[66:81]
	ds_read_b128 v[252:255], v213 offset:24576
	v_mfma_f32_32x32x16_bf16 v[50:65], v[220:223], v[228:231], v[50:65]
	ds_read_b128 v[236:239], v209 offset:20480
	v_mfma_f32_32x32x16_bf16 v[34:49], v[216:219], v[228:231], v[34:49]
	ds_read_b128 v[248:251], v213 offset:28672
	s_waitcnt lgkmcnt(4)
	v_mfma_f32_32x32x16_bf16 v[18:33], v[220:223], v[224:227], v[18:33]
	ds_read_b128 v[244:247], v213 offset:32768
	v_mfma_f32_32x32x16_bf16 v[2:17], v[216:219], v[224:227], v[2:17]
	s_waitcnt lgkmcnt(1)
	v_mfma_f32_32x32x16_bf16 v[82:97], v[240:243], v[252:255], v[82:97]
	ds_read_b128 v[220:223], v208 offset:16384
	s_add_u32 s79, s75, s74
	s_add_u32 s79, s79, 3
	s_and_b32 s79, s79, 15
	v_mfma_f32_32x32x16_bf16 v[66:81], v[236:239], v[252:255], v[66:81]
	ds_read_b128 v[232:235], v212 offset:24576
	s_lshl_b32 s79, s79, 7
	s_add_u32 s70, s66, s79
	v_mfma_f32_32x32x16_bf16 v[50:65], v[240:243], v[248:251], v[50:65]
	ds_read_b128 v[216:219], v208 offset:20480
	s_addc_u32 s71, s67, 0
	s_add_u32 s72, s68, s79
	v_mfma_f32_32x32x16_bf16 v[34:49], v[236:239], v[248:251], v[34:49]
	ds_read_b128 v[228:231], v212 offset:28672
	s_addc_u32 s73, s69, 0
	s_add_u32 s77, s76, 0x6000
	s_add_u32 s78, s76, 0x10000
	s_waitcnt lgkmcnt(4)
	v_mfma_f32_32x32x16_bf16 v[18:33], v[240:243], v[244:247], v[18:33]
	ds_read_b128 v[224:227], v212 offset:32768
	v_mfma_f32_32x32x16_bf16 v[2:17], v[236:239], v[244:247], v[2:17]
	s_waitcnt vmcnt(0) lgkmcnt(0)
	s_barrier
	v_mfma_f32_32x32x16_bf16 v[82:97], v[220:223], v[232:235], v[82:97]
	s_add_u32 m0, s77, 0x0
	ds_read_b128 v[240:243], v211 offset:0
	global_load_lds_dwordx4 v207, s[70:71]
	s_add_u32 m0, s77, 0x1000
	s_nop 0
	global_load_lds_dwordx4 v206, s[70:71]
	v_mfma_f32_32x32x16_bf16 v[66:81], v[216:219], v[232:235], v[66:81]
	s_add_u32 m0, s77, 0x2000
	ds_read_b128 v[252:255], v215 offset:0
	global_load_lds_dwordx4 v205, s[70:71]
	s_add_u32 m0, s77, 0x3000
	s_nop 0
	global_load_lds_dwordx4 v204, s[70:71]
	v_mfma_f32_32x32x16_bf16 v[50:65], v[220:223], v[228:231], v[50:65]
	s_add_u32 m0, s77, 0x4000
	ds_read_b128 v[236:239], v211 offset:4096
	global_load_lds_dwordx4 v203, s[70:71]
	s_add_u32 m0, s77, 0x5000
	s_nop 0
	global_load_lds_dwordx4 v202, s[70:71]
	v_mfma_f32_32x32x16_bf16 v[34:49], v[216:219], v[228:231], v[34:49]
	s_add_u32 m0, s78, 0x0
	ds_read_b128 v[248:251], v215 offset:4096
	global_load_lds_dwordx4 v207, s[72:73]
	s_add_u32 m0, s78, 0x1000
	s_nop 0
	global_load_lds_dwordx4 v206, s[72:73]
	v_mfma_f32_32x32x16_bf16 v[18:33], v[220:223], v[224:227], v[18:33]
	s_add_u32 m0, s78, 0x2000
	ds_read_b128 v[244:247], v215 offset:8192
	global_load_lds_dwordx4 v205, s[72:73]
	s_add_u32 m0, s78, 0x3000
	s_nop 0
	global_load_lds_dwordx4 v204, s[72:73]
	v_mfma_f32_32x32x16_bf16 v[2:17], v[216:219], v[224:227], v[2:17]
	s_add_u32 s74, s74, 2
	s_cmp_lt_u32 s74, 14
	s_cbranch_scc1 .Lgm_ph17_loop
	s_waitcnt lgkmcnt(1)
	v_mfma_f32_32x32x16_bf16 v[82:97], v[240:243], v[252:255], v[82:97]
	ds_read_b128 v[220:223], v210 offset:0
	v_mfma_f32_32x32x16_bf16 v[66:81], v[236:239], v[252:255], v[66:81]
	ds_read_b128 v[232:235], v214 offset:0
	v_mfma_f32_32x32x16_bf16 v[50:65], v[240:243], v[248:251], v[50:65]
	ds_read_b128 v[216:219], v210 offset:4096
	v_mfma_f32_32x32x16_bf16 v[34:49], v[236:239], v[248:251], v[34:49]
	ds_read_b128 v[228:231], v214 offset:4096
	s_waitcnt lgkmcnt(4)
	v_mfma_f32_32x32x16_bf16 v[18:33], v[240:243], v[244:247], v[18:33]
	ds_read_b128 v[224:227], v214 offset:8192
	v_mfma_f32_32x32x16_bf16 v[2:17], v[236:239], v[244:247], v[2:17]
	s_waitcnt lgkmcnt(1)
	v_mfma_f32_32x32x16_bf16 v[82:97], v[220:223], v[232:235], v[82:97]
	ds_read_b128 v[240:243], v209 offset:0
	v_mfma_f32_32x32x16_bf16 v[66:81], v[216:219], v[232:235], v[66:81]
	ds_read_b128 v[252:255], v213 offset:0
	v_mfma_f32_32x32x16_bf16 v[50:65], v[220:223], v[228:231], v[50:65]
	ds_read_b128 v[236:239], v209 offset:4096
	v_mfma_f32_32x32x16_bf16 v[34:49], v[216:219], v[228:231], v[34:49]
	ds_read_b128 v[248:251], v213 offset:4096
	s_waitcnt lgkmcnt(4)
	v_mfma_f32_32x32x16_bf16 v[18:33], v[220:223], v[224:227], v[18:33]
	ds_read_b128 v[244:247], v213 offset:8192
	v_mfma_f32_32x32x16_bf16 v[2:17], v[216:219], v[224:227], v[2:17]
	s_waitcnt lgkmcnt(1)
	v_mfma_f32_32x32x16_bf16 v[82:97], v[240:243], v[252:255], v[82:97]
	ds_read_b128 v[220:223], v208 offset:0
	v_mfma_f32_32x32x16_bf16 v[66:81], v[236:239], v[252:255], v[66:81]
	ds_read_b128 v[232:235], v212 offset:0
	v_mfma_f32_32x32x16_bf16 v[50:65], v[240:243], v[248:251], v[50:65]
	ds_read_b128 v[216:219], v208 offset:4096
	v_mfma_f32_32x32x16_bf16 v[34:49], v[236:239], v[248:251], v[34:49]
	ds_read_b128 v[228:231], v212 offset:4096
	s_waitcnt lgkmcnt(4)
	v_mfma_f32_32x32x16_bf16 v[18:33], v[240:243], v[244:247], v[18:33]
	ds_read_b128 v[224:227], v212 offset:8192
	v_mfma_f32_32x32x16_bf16 v[2:17], v[236:239], v[244:247], v[2:17]
	s_waitcnt vmcnt(0) lgkmcnt(0)
	s_barrier
	v_mfma_f32_32x32x16_bf16 v[82:97], v[220:223], v[232:235], v[82:97]
	ds_read_b128 v[240:243], v211 offset:16384
	v_mfma_f32_32x32x16_bf16 v[66:81], v[216:219], v[232:235], v[66:81]
	ds_read_b128 v[252:255], v215 offset:24576
	v_mfma_f32_32x32x16_bf16 v[50:65], v[220:223], v[228:231], v[50:65]
	ds_read_b128 v[236:239], v211 offset:20480
	v_mfma_f32_32x32x16_bf16 v[34:49], v[216:219], v[228:231], v[34:49]
	ds_read_b128 v[248:251], v215 offset:28672
	v_mfma_f32_32x32x16_bf16 v[18:33], v[220:223], v[224:227], v[18:33]
	ds_read_b128 v[244:247], v215 offset:32768
	v_mfma_f32_32x32x16_bf16 v[2:17], v[216:219], v[224:227], v[2:17]
	s_waitcnt lgkmcnt(1)
	v_mfma_f32_32x32x16_bf16 v[82:97], v[240:243], v[252:255], v[82:97]
	ds_read_b128 v[220:223], v210 offset:16384
	v_mfma_f32_32x32x16_bf16 v[66:81], v[236:239], v[252:255], v[66:81]
	ds_read_b128 v[232:235], v214 offset:24576
	v_mfma_f32_32x32x16_bf16 v[50:65], v[240:243], v[248:251], v[50:65]
	ds_read_b128 v[216:219], v210 offset:20480
	v_mfma_f32_32x32x16_bf16 v[34:49], v[236:239], v[248:251], v[34:49]
	ds_read_b128 v[228:231], v214 offset:28672
	s_waitcnt lgkmcnt(4)
	v_mfma_f32_32x32x16_bf16 v[18:33], v[240:243], v[244:247], v[18:33]
	ds_read_b128 v[224:227], v214 offset:32768
	v_mfma_f32_32x32x16_bf16 v[2:17], v[236:239], v[244:247], v[2:17]
	s_waitcnt lgkmcnt(1)
	v_mfma_f32_32x32x16_bf16 v[82:97], v[220:223], v[232:235], v[82:97]
	ds_read_b128 v[240:243], v209 offset:16384
	v_mfma_f32_32x32x16_bf16 v[66:81], v[216:219], v[232:235], v[66:81]
	ds_read_b128 v[252:255], v213 offset:24576
	v_mfma_f32_32x32x16_bf16 v[50:65], v[220:223], v[228:231], v[50:65]
	ds_read_b128 v[236:239], v209 offset:20480
	v_mfma_f32_32x32x16_bf16 v[34:49], v[216:219], v[228:231], v[34:49]
	ds_read_b128 v[248:251], v213 offset:28672
	s_waitcnt lgkmcnt(4)
	v_mfma_f32_32x32x16_bf16 v[18:33], v[220:223], v[224:227], v[18:33]
	ds_read_b128 v[244:247], v213 offset:32768
	v_mfma_f32_32x32x16_bf16 v[2:17], v[216:219], v[224:227], v[2:17]
	s_waitcnt lgkmcnt(1)
	v_mfma_f32_32x32x16_bf16 v[82:97], v[240:243], v[252:255], v[82:97]
	ds_read_b128 v[220:223], v208 offset:16384
	v_mfma_f32_32x32x16_bf16 v[66:81], v[236:239], v[252:255], v[66:81]
	ds_read_b128 v[232:235], v212 offset:24576
	v_mfma_f32_32x32x16_bf16 v[50:65], v[240:243], v[248:251], v[50:65]
	ds_read_b128 v[216:219], v208 offset:20480
	v_mfma_f32_32x32x16_bf16 v[34:49], v[236:239], v[248:251], v[34:49]
	ds_read_b128 v[228:231], v212 offset:28672
	s_waitcnt lgkmcnt(4)
	v_mfma_f32_32x32x16_bf16 v[18:33], v[240:243], v[244:247], v[18:33]
	ds_read_b128 v[224:227], v212 offset:32768
	v_mfma_f32_32x32x16_bf16 v[2:17], v[236:239], v[244:247], v[2:17]
	s_waitcnt vmcnt(0) lgkmcnt(0)
	s_barrier
	v_mfma_f32_32x32x16_bf16 v[82:97], v[220:223], v[232:235], v[82:97]
	v_mfma_f32_32x32x16_bf16 v[66:81], v[216:219], v[232:235], v[66:81]
	v_mfma_f32_32x32x16_bf16 v[50:65], v[220:223], v[228:231], v[50:65]
	v_mfma_f32_32x32x16_bf16 v[34:49], v[216:219], v[228:231], v[34:49]
	v_mfma_f32_32x32x16_bf16 v[18:33], v[220:223], v[224:227], v[18:33]
	v_mfma_f32_32x32x16_bf16 v[2:17], v[216:219], v[224:227], v[2:17]
	s_nop 7
	s_nop 7
	v_add_u32_e32 v144, v116, v120
	s_nop 4
	v_add_u32_e32 v145, v116, v121
	s_nop 4
	v_add_u32_e32 v147, v116, v122
	s_nop 4
	v_or_b32_e32 v143, s5, v123
	s_nop 4
	v_cmp_lt_i32_e64 s[6:7], s3, v143
	s_nop 4
	v_add_u32_e32 v98, v118, v122
	s_nop 4
	s_waitcnt lgkmcnt(0)
	v_add_u32_e32 v106, s4, v115
	v_ashrrev_i32_e32 v107, 31, v106
	v_lshlrev_b64 v[110:111], 11, v[106:107]
	v_or_b32_e32 v104, v143, v124
	v_lshl_add_u64 v[108:109], s[10:11], 0, v[110:111]
	s_and_saveexec_b64 s[4:5], s[6:7]
	s_xor_b64 s[4:5], exec, s[4:5]
	s_cbranch_execz .LBB0_1996
	v_mul_f32_e32 v98, 0xbfb8aa3b, v82
	v_exp_f32_e32 v144, v98
	v_mul_f32_e32 v98, 0xbfb8aa3b, v83
	v_exp_f32_e32 v145, v98
	s_nop 0
	v_pk_add_f32 v[144:145], v[144:145], 1.0 op_sel_hi:[1,0]
	s_nop 0
	v_div_scale_f32 v98, s[30:31], v145, v145, v83
	v_rcp_f32_e32 v105, v98
	v_div_scale_f32 v107, vcc, v83, v145, v83
	v_fma_f32 v147, -v98, v105, 1.0
	v_fmac_f32_e32 v105, v147, v105
	v_mul_f32_e32 v147, v107, v105
	v_fma_f32 v149, -v98, v147, v107
	v_fmac_f32_e32 v147, v149, v105
	v_fma_f32 v98, -v98, v147, v107
	v_div_scale_f32 v107, s[30:31], v144, v144, v82
	v_rcp_f32_e32 v149, v107
	v_div_fmas_f32 v98, v98, v105, v147
	v_mul_f32_e32 v147, 0xbfb8aa3b, v84
	v_exp_f32_e32 v152, v147
	v_mul_f32_e32 v147, 0xbfb8aa3b, v85
	v_fma_f32 v105, -v107, v149, 1.0
	v_exp_f32_e32 v153, v147
	v_fmac_f32_e32 v149, v105, v149
	v_div_scale_f32 v105, vcc, v82, v144, v82
	v_div_fixup_f32 v98, v98, v145, v83
	v_mul_f32_e32 v145, v105, v149
	v_fma_f32 v147, -v107, v145, v105
	v_fmac_f32_e32 v145, v147, v149
	v_pk_add_f32 v[152:153], v[152:153], 1.0 op_sel_hi:[1,0]
	v_fma_f32 v105, -v107, v145, v105
	v_div_scale_f32 v107, s[30:31], v153, v153, v85
	v_rcp_f32_e32 v147, v107
	v_div_fmas_f32 v105, v105, v149, v145
	v_div_fixup_f32 v105, v105, v144, v82
	v_cvt_pk_bf16_f32 v144, v105, v98
	v_fma_f32 v98, -v107, v147, 1.0
	v_fmac_f32_e32 v147, v98, v147
	v_div_scale_f32 v98, vcc, v85, v153, v85
	v_mul_f32_e32 v105, v98, v147
	v_fma_f32 v145, -v107, v105, v98
	v_fmac_f32_e32 v105, v145, v147
	v_fma_f32 v98, -v107, v105, v98
	v_div_scale_f32 v107, s[30:31], v152, v152, v84
	v_rcp_f32_e32 v145, v107
	v_div_fmas_f32 v98, v98, v147, v105
	v_div_fixup_f32 v98, v98, v153, v85
	v_fma_f32 v105, -v107, v145, 1.0
	v_fmac_f32_e32 v145, v105, v145
	v_div_scale_f32 v105, vcc, v84, v152, v84
	v_mul_f32_e32 v147, v105, v145
	v_fma_f32 v149, -v107, v147, v105
	v_fmac_f32_e32 v147, v149, v145
	v_fma_f32 v105, -v107, v147, v105
	v_div_fmas_f32 v105, v105, v145, v147
	v_div_fixup_f32 v105, v105, v152, v84
	v_cvt_pk_bf16_f32 v145, v105, v98
	v_mov_b32_e32 v105, v99
	v_lshl_add_u64 v[152:153], v[104:105], 1, v[108:109]
	global_store_dwordx2 v[152:153], v[144:145], off offset:-2048

.LBB0_2331:
	s_ashr_i32 s10, s2, 31
	s_lshr_b32 s10, s10, 26
	s_add_i32 s10, s2, s10
	s_ashr_i32 s30, s10, 6
	s_and_b32 s10, s10, 0x3ffffc0
	s_sub_i32 s28, s2, s10
	s_mulk_i32 s28, 0xc0
	v_add_u32_e32 v2, s28, v108
	s_lshr_b32 s10, s28, 6
	s_lshl_b32 s29, s30, 7
	v_ashrrev_i32_e32 v3, 31, v2
	s_add_i32 s10, s10, s30
	v_lshlrev_b64 v[2:3], 11, v[2:3]
	v_or_b32_e32 v4, s29, v108
	s_lshl_b32 s30, s10, 6
	s_lshl_b32 s10, s10, 7
	v_ashrrev_i32_e32 v5, 31, v4
	v_lshl_add_u64 v[104:105], v[100:101], 0, v[2:3]
	s_and_b32 s10, s10, 0x780
	v_readfirstlane_b32 s31, v109
	v_lshlrev_b64 v[4:5], 11, v[4:5]
	v_lshl_add_u64 v[2:3], v[104:105], 0, s[10:11]
	s_mov_b32 m0, s31
	v_readfirstlane_b32 s31, v127
	v_lshl_add_u64 v[106:107], v[102:103], 0, v[4:5]
	s_waitcnt vmcnt(0)
	s_barrier
	s_load_dwordx2 s[66:67], s[0:1], 0x118
	s_load_dwordx2 s[68:69], s[0:1], 0xd0
	v_and_b32_e32 v201, 0x3ff, v0
	v_readfirstlane_b32 s76, v0
	v_and_b32_e32 v200, 31, v201
	v_bfe_u32 v214, v201, 1, 3
	v_bfe_u32 v213, v201, 5, 1
	v_xor_b32_e32 v214, v214, v213
	v_lshlrev_b32_e32 v214, 4, v214
	s_and_b32 s76, s76, 0x3ff
	s_lshr_b32 s79, s76, 6
	s_lshl_b32 s76, s76, 4
	s_lshr_b32 s80, s79, 1
	s_and_b32 s79, s79, 1
	s_mul_i32 s80, s80, 0x3000
	s_lshl_b32 s79, s79, 13
	s_add_u32 s79, s79, 0xc000
	v_lshlrev_b32_e32 v200, 7, v200
	v_or_b32_e32 v200, v200, v214
	v_add_u32_e32 v215, s80, v200
	v_add_u32_e32 v211, s79, v200
	v_xor_b32_e32 v214, 0x20, v215
	v_xor_b32_e32 v210, 0x20, v211
	v_xor_b32_e32 v213, 0x40, v215
	v_xor_b32_e32 v209, 0x40, v211
	v_xor_b32_e32 v212, 0x60, v215
	v_xor_b32_e32 v208, 0x60, v211
	v_bfe_u32 v200, v201, 4, 3
	v_and_b32_e32 v206, 7, v201
	v_xor_b32_e32 v200, v200, v206
	v_lshlrev_b32_e32 v200, 4, v200
	v_lshrrev_b32_e32 v206, 3, v201
	v_lshl_or_b32 v207, v206, 11, v200
	v_add_u32_e32 v206, 0x10000, v207
	v_add_u32_e32 v205, 0x20000, v207
	v_add_u32_e32 v204, 0x30000, v207
	v_add_u32_e32 v203, 0x40000, v207
	v_add_u32_e32 v202, 0x50000, v207
	s_lshr_b32 s79, s2, 6
	s_and_b32 s80, s2, 63
	s_mov_b32 s75, 0
	s_mul_i32 s80, s80, 0x60000
	s_lshl_b32 s79, s79, 18
	s_add_u32 s79, s79, 0x200000
	s_waitcnt lgkmcnt(0)
	s_add_u32 s66, s66, s80
	s_addc_u32 s67, s67, 0
	s_add_u32 s68, s68, s79
	s_addc_u32 s69, s69, 0
	s_add_u32 s79, s75, 0
	s_and_b32 s79, s79, 15
	s_lshl_b32 s79, s79, 7
	s_add_u32 s70, s66, s79
	s_addc_u32 s71, s67, 0
	s_add_u32 s72, s68, s79
	s_addc_u32 s73, s69, 0
	s_add_u32 s77, s76, 0x0
	s_add_u32 s78, s76, 0xc000
	s_add_u32 m0, s77, 0x0
	s_nop 0
	global_load_lds_dwordx4 v207, s[70:71]
	s_add_u32 m0, s77, 0x1000
	s_nop 0
	global_load_lds_dwordx4 v206, s[70:71]
	s_add_u32 m0, s77, 0x2000
	s_nop 0
	global_load_lds_dwordx4 v205, s[70:71]
	s_add_u32 m0, s77, 0x3000
	s_nop 0
	global_load_lds_dwordx4 v204, s[70:71]
	s_add_u32 m0, s77, 0x4000
	s_nop 0
	global_load_lds_dwordx4 v203, s[70:71]
	s_add_u32 m0, s77, 0x5000
	s_nop 0
	global_load_lds_dwordx4 v202, s[70:71]
	s_add_u32 m0, s78, 0x0
	s_nop 0
	global_load_lds_dwordx4 v207, s[72:73]
	s_add_u32 m0, s78, 0x1000
	s_nop 0
	global_load_lds_dwordx4 v206, s[72:73]
	s_add_u32 m0, s78, 0x2000
	s_nop 0
	global_load_lds_dwordx4 v205, s[72:73]
	s_add_u32 m0, s78, 0x3000
	s_nop 0
	global_load_lds_dwordx4 v204, s[72:73]
	s_add_u32 s79, s75, 1
	s_and_b32 s79, s79, 15
	s_lshl_b32 s79, s79, 7
	s_add_u32 s70, s66, s79
	s_addc_u32 s71, s67, 0
	s_add_u32 s72, s68, s79
	s_addc_u32 s73, s69, 0
	s_add_u32 s77, s76, 0x6000
	s_add_u32 s78, s76, 0x10000
	s_add_u32 m0, s77, 0x0
	s_nop 0
	global_load_lds_dwordx4 v207, s[70:71]
	s_add_u32 m0, s77, 0x1000
	s_nop 0
	global_load_lds_dwordx4 v206, s[70:71]
	s_add_u32 m0, s77, 0x2000
	s_nop 0
	global_load_lds_dwordx4 v205, s[70:71]
	s_add_u32 m0, s77, 0x3000
	s_nop 0
	global_load_lds_dwordx4 v204, s[70:71]
	s_add_u32 m0, s77, 0x4000
	s_nop 0
	global_load_lds_dwordx4 v203, s[70:71]
	s_add_u32 m0, s77, 0x5000
	s_nop 0
	global_load_lds_dwordx4 v202, s[70:71]
	s_add_u32 m0, s78, 0x0
	s_nop 0
	global_load_lds_dwordx4 v207, s[72:73]
	s_add_u32 m0, s78, 0x1000
	s_nop 0
	global_load_lds_dwordx4 v206, s[72:73]
	s_add_u32 m0, s78, 0x2000
	s_nop 0
	global_load_lds_dwordx4 v205, s[72:73]
	s_add_u32 m0, s78, 0x3000
	s_nop 0
	global_load_lds_dwordx4 v204, s[72:73]
	v_mov_b32_e32 v2, 0
	v_mov_b32_e32 v3, 0
	v_mov_b32_e32 v4, 0
	v_mov_b32_e32 v5, 0
	v_mov_b32_e32 v6, 0
	v_mov_b32_e32 v7, 0
	v_mov_b32_e32 v8, 0
	v_mov_b32_e32 v9, 0
	v_mov_b32_e32 v10, 0
	v_mov_b32_e32 v11, 0
	v_mov_b32_e32 v12, 0
	v_mov_b32_e32 v13, 0
	v_mov_b32_e32 v14, 0
	v_mov_b32_e32 v15, 0
	v_mov_b32_e32 v16, 0
	v_mov_b32_e32 v17, 0
	v_mov_b32_e32 v18, 0
	v_mov_b32_e32 v19, 0
	v_mov_b32_e32 v20, 0
	v_mov_b32_e32 v21, 0
	v_mov_b32_e32 v22, 0
	v_mov_b32_e32 v23, 0
	v_mov_b32_e32 v24, 0
	v_mov_b32_e32 v25, 0
	v_mov_b32_e32 v26, 0
	v_mov_b32_e32 v27, 0
	v_mov_b32_e32 v28, 0
	v_mov_b32_e32 v29, 0
	v_mov_b32_e32 v30, 0
	v_mov_b32_e32 v31, 0
	v_mov_b32_e32 v32, 0
	v_mov_b32_e32 v33, 0
	v_mov_b32_e32 v34, 0
	v_mov_b32_e32 v35, 0
	v_mov_b32_e32 v36, 0
	v_mov_b32_e32 v37, 0
	v_mov_b32_e32 v38, 0
	v_mov_b32_e32 v39, 0
	v_mov_b32_e32 v40, 0
	v_mov_b32_e32 v41, 0
	v_mov_b32_e32 v42, 0
	v_mov_b32_e32 v43, 0
	v_mov_b32_e32 v44, 0
	v_mov_b32_e32 v45, 0
	v_mov_b32_e32 v46, 0
	v_mov_b32_e32 v47, 0
	v_mov_b32_e32 v48, 0
	v_mov_b32_e32 v49, 0
	v_mov_b32_e32 v50, 0
	v_mov_b32_e32 v51, 0
	v_mov_b32_e32 v52, 0
	v_mov_b32_e32 v53, 0
	v_mov_b32_e32 v54, 0
	v_mov_b32_e32 v55, 0
	v_mov_b32_e32 v56, 0
	v_mov_b32_e32 v57, 0
	v_mov_b32_e32 v58, 0
	v_mov_b32_e32 v59, 0
	v_mov_b32_e32 v60, 0
	v_mov_b32_e32 v61, 0
	v_mov_b32_e32 v62, 0
	v_mov_b32_e32 v63, 0
	v_mov_b32_e32 v64, 0
	v_mov_b32_e32 v65, 0
	v_mov_b32_e32 v66, 0
	v_mov_b32_e32 v67, 0
	v_mov_b32_e32 v68, 0
	v_mov_b32_e32 v69, 0
	v_mov_b32_e32 v70, 0
	v_mov_b32_e32 v71, 0
	v_mov_b32_e32 v72, 0
	v_mov_b32_e32 v73, 0
	v_mov_b32_e32 v74, 0
	v_mov_b32_e32 v75, 0
	v_mov_b32_e32 v76, 0
	v_mov_b32_e32 v77, 0
	v_mov_b32_e32 v78, 0
	v_mov_b32_e32 v79, 0
	v_mov_b32_e32 v80, 0
	v_mov_b32_e32 v81, 0
	v_mov_b32_e32 v82, 0
	v_mov_b32_e32 v83, 0
	v_mov_b32_e32 v84, 0
	v_mov_b32_e32 v85, 0
	v_mov_b32_e32 v86, 0
	v_mov_b32_e32 v87, 0
	v_mov_b32_e32 v88, 0
	v_mov_b32_e32 v89, 0
	v_mov_b32_e32 v90, 0
	v_mov_b32_e32 v91, 0
	v_mov_b32_e32 v92, 0
	v_mov_b32_e32 v93, 0
	v_mov_b32_e32 v94, 0
	v_mov_b32_e32 v95, 0
	v_mov_b32_e32 v96, 0
	v_mov_b32_e32 v97, 0
	s_waitcnt vmcnt(10)
	s_barrier
	ds_read_b128 v[240:243], v211 offset:0
	ds_read_b128 v[252:255], v215 offset:0
	ds_read_b128 v[236:239], v211 offset:4096
	ds_read_b128 v[248:251], v215 offset:4096
	ds_read_b128 v[244:247], v215 offset:8192
	s_mov_b32 s74, 0
.Lgm_ph20_loop:
	s_waitcnt lgkmcnt(1)
	v_mfma_f32_32x32x16_bf16 v[82:97], v[240:243], v[252:255], v[82:97]
	ds_read_b128 v[220:223], v210 offset:0
	v_mfma_f32_32x32x16_bf16 v[66:81], v[236:239], v[252:255], v[66:81]
	ds_read_b128 v[232:235], v214 offset:0
	v_mfma_f32_32x32x16_bf16 v[50:65], v[240:243], v[248:251], v[50:65]
	ds_read_b128 v[216:219], v210 offset:4096
	v_mfma_f32_32x32x16_bf16 v[34:49], v[236:239], v[248:251], v[34:49]
	ds_read_b128 v[228:231], v214 offset:4096
	s_waitcnt lgkmcnt(4)
	v_mfma_f32_32x32x16_bf16 v[18:33], v[240:243], v[244:247], v[18:33]
	ds_read_b128 v[224:227], v214 offset:8192
	v_mfma_f32_32x32x16_bf16 v[2:17], v[236:239], v[244:247], v[2:17]
	s_waitcnt lgkmcnt(1)
	v_mfma_f32_32x32x16_bf16 v[82:97], v[220:223], v[232:235], v[82:97]
	ds_read_b128 v[240:243], v209 offset:0
	v_mfma_f32_32x32x16_bf16 v[66:81], v[216:219], v[232:235], v[66:81]
	ds_read_b128 v[252:255], v213 offset:0
	v_mfma_f32_32x32x16_bf16 v[50:65], v[220:223], v[228:231], v[50:65]
	ds_read_b128 v[236:239], v209 offset:4096
	v_mfma_f32_32x32x16_bf16 v[34:49], v[216:219], v[228:231], v[34:49]
	ds_read_b128 v[248:251], v213 offset:4096
	s_waitcnt lgkmcnt(4)
	v_mfma_f32_32x32x16_bf16 v[18:33], v[220:223], v[224:227], v[18:33]
	ds_read_b128 v[244:247], v213 offset:8192
	v_mfma_f32_32x32x16_bf16 v[2:17], v[216:219], v[224:227], v[2:17]
	s_waitcnt lgkmcnt(1)
	v_mfma_f32_32x32x16_bf16 v[82:97], v[240:243], v[252:255], v[82:97]
	ds_read_b128 v[220:223], v208 offset:0
	s_add_u32 s79, s75, s74
	s_add_u32 s79, s79, 2
	s_and_b32 s79, s79, 15
	v_mfma_f32_32x32x16_bf16 v[66:81], v[236:239], v[252:255], v[66:81]
	ds_read_b128 v[232:235], v212 offset:0
	s_lshl_b32 s79, s79, 7
	s_add_u32 s70, s66, s79
	v_mfma_f32_32x32x16_bf16 v[50:65], v[240:243], v[248:251], v[50:65]
	ds_read_b128 v[216:219], v208 offset:4096
	s_addc_u32 s71, s67, 0
	s_add_u32 s72, s68, s79
	v_mfma_f32_32x32x16_bf16 v[34:49], v[236:239], v[248:251], v[34:49]
	ds_read_b128 v[228:231], v212 offset:4096
	s_addc_u32 s73, s69, 0
	s_add_u32 s77, s76, 0x0
	s_add_u32 s78, s76, 0xc000
	s_waitcnt lgkmcnt(4)
	v_mfma_f32_32x32x16_bf16 v[18:33], v[240:243], v[244:247], v[18:33]
	ds_read_b128 v[224:227], v212 offset:8192
	v_mfma_f32_32x32x16_bf16 v[2:17], v[236:239], v[244:247], v[2:17]
	s_waitcnt vmcnt(0) lgkmcnt(0)
	s_barrier
	v_mfma_f32_32x32x16_bf16 v[82:97], v[220:223], v[232:235], v[82:97]
	s_add_u32 m0, s77, 0x0
	ds_read_b128 v[240:243], v211 offset:16384
	global_load_lds_dwordx4 v207, s[70:71]
	s_add_u32 m0, s77, 0x1000
	s_nop 0
	global_load_lds_dwordx4 v206, s[70:71]
	v_mfma_f32_32x32x16_bf16 v[66:81], v[216:219], v[232:235], v[66:81]
	s_add_u32 m0, s77, 0x2000
	ds_read_b128 v[252:255], v215 offset:24576
	global_load_lds_dwordx4 v205, s[70:71]
	s_add_u32 m0, s77, 0x3000
	s_nop 0
	global_load_lds_dwordx4 v204, s[70:71]
	v_mfma_f32_32x32x16_bf16 v[50:65], v[220:223], v[228:231], v[50:65]
	s_add_u32 m0, s77, 0x4000
	ds_read_b128 v[236:239], v211 offset:20480
	global_load_lds_dwordx4 v203, s[70:71]
	s_add_u32 m0, s77, 0x5000
	s_nop 0
	global_load_lds_dwordx4 v202, s[70:71]
	v_mfma_f32_32x32x16_bf16 v[34:49], v[216:219], v[228:231], v[34:49]
	s_add_u32 m0, s78, 0x0
	ds_read_b128 v[248:251], v215 offset:28672
	global_load_lds_dwordx4 v207, s[72:73]
	s_add_u32 m0, s78, 0x1000
	s_nop 0
	global_load_lds_dwordx4 v206, s[72:73]
	v_mfma_f32_32x32x16_bf16 v[18:33], v[220:223], v[224:227], v[18:33]
	s_add_u32 m0, s78, 0x2000
	ds_read_b128 v[244:247], v215 offset:32768
	global_load_lds_dwordx4 v205, s[72:73]
	s_add_u32 m0, s78, 0x3000
	s_nop 0
	global_load_lds_dwordx4 v204, s[72:73]
	v_mfma_f32_32x32x16_bf16 v[2:17], v[216:219], v[224:227], v[2:17]
	s_waitcnt lgkmcnt(1)
	v_mfma_f32_32x32x16_bf16 v[82:97], v[240:243], v[252:255], v[82:97]
	ds_read_b128 v[220:223], v210 offset:16384
	v_mfma_f32_32x32x16_bf16 v[66:81], v[236:239], v[252:255], v[66:81]
	ds_read_b128 v[232:235], v214 offset:24576
	v_mfma_f32_32x32x16_bf16 v[50:65], v[240:243], v[248:251], v[50:65]
	ds_read_b128 v[216:219], v210 offset:20480
	v_mfma_f32_32x32x16_bf16 v[34:49], v[236:239], v[248:251], v[34:49]
	ds_read_b128 v[228:231], v214 offset:28672
	s_waitcnt lgkmcnt(4)
	v_mfma_f32_32x32x16_bf16 v[18:33], v[240:243], v[244:247], v[18:33]
	ds_read_b128 v[224:227], v214 offset:32768
	v_mfma_f32_32x32x16_bf16 v[2:17], v[236:239], v[244:247], v[2:17]
	s_waitcnt lgkmcnt(1)
	v_mfma_f32_32x32x16_bf16 v[82:97], v[220:223], v[232:235], v[82:97]
	ds_read_b128 v[240:243], v209 offset:16384
	v_mfma_f32_32x32x16_bf16 v[66:81], v[216:219], v[232:235], v[66:81]
	ds_read_b128 v[252:255], v213 offset:24576
	v_mfma_f32_32x32x16_bf16 v[50:65], v[220:223], v[228:231], v[50:65]
	ds_read_b128 v[236:239], v209 offset:20480
	v_mfma_f32_32x32x16_bf16 v[34:49], v[216:219], v[228:231], v[34:49]
	ds_read_b128 v[248:251], v213 offset:28672
	s_waitcnt lgkmcnt(4)
	v_mfma_f32_32x32x16_bf16 v[18:33], v[220:223], v[224:227], v[18:33]
	ds_read_b128 v[244:247], v213 offset:32768
	v_mfma_f32_32x32x16_bf16 v[2:17], v[216:219], v[224:227], v[2:17]
	s_waitcnt lgkmcnt(1)
	v_mfma_f32_32x32x16_bf16 v[82:97], v[240:243], v[252:255], v[82:97]
	ds_read_b128 v[220:223], v208 offset:16384
	s_add_u32 s79, s75, s74
	s_add_u32 s79, s79, 3
	s_and_b32 s79, s79, 15
	v_mfma_f32_32x32x16_bf16 v[66:81], v[236:239], v[252:255], v[66:81]
	ds_read_b128 v[232:235], v212 offset:24576
	s_lshl_b32 s79, s79, 7
	s_add_u32 s70, s66, s79
	v_mfma_f32_32x32x16_bf16 v[50:65], v[240:243], v[248:251], v[50:65]
	ds_read_b128 v[216:219], v208 offset:20480
	s_addc_u32 s71, s67, 0
	s_add_u32 s72, s68, s79
	v_mfma_f32_32x32x16_bf16 v[34:49], v[236:239], v[248:251], v[34:49]
	ds_read_b128 v[228:231], v212 offset:28672
	s_addc_u32 s73, s69, 0
	s_add_u32 s77, s76, 0x6000
	s_add_u32 s78, s76, 0x10000
	s_waitcnt lgkmcnt(4)
	v_mfma_f32_32x32x16_bf16 v[18:33], v[240:243], v[244:247], v[18:33]
	ds_read_b128 v[224:227], v212 offset:32768
	v_mfma_f32_32x32x16_bf16 v[2:17], v[236:239], v[244:247], v[2:17]
	s_waitcnt vmcnt(0) lgkmcnt(0)
	s_barrier
	v_mfma_f32_32x32x16_bf16 v[82:97], v[220:223], v[232:235], v[82:97]
	s_add_u32 m0, s77, 0x0
	ds_read_b128 v[240:243], v211 offset:0
	global_load_lds_dwordx4 v207, s[70:71]
	s_add_u32 m0, s77, 0x1000
	s_nop 0
	global_load_lds_dwordx4 v206, s[70:71]
	v_mfma_f32_32x32x16_bf16 v[66:81], v[216:219], v[232:235], v[66:81]
	s_add_u32 m0, s77, 0x2000
	ds_read_b128 v[252:255], v215 offset:0
	global_load_lds_dwordx4 v205, s[70:71]
	s_add_u32 m0, s77, 0x3000
	s_nop 0
	global_load_lds_dwordx4 v204, s[70:71]
	v_mfma_f32_32x32x16_bf16 v[50:65], v[220:223], v[228:231], v[50:65]
	s_add_u32 m0, s77, 0x4000
	ds_read_b128 v[236:239], v211 offset:4096
	global_load_lds_dwordx4 v203, s[70:71]
	s_add_u32 m0, s77, 0x5000
	s_nop 0
	global_load_lds_dwordx4 v202, s[70:71]
	v_mfma_f32_32x32x16_bf16 v[34:49], v[216:219], v[228:231], v[34:49]
	s_add_u32 m0, s78, 0x0
	ds_read_b128 v[248:251], v215 offset:4096
	global_load_lds_dwordx4 v207, s[72:73]
	s_add_u32 m0, s78, 0x1000
	s_nop 0
	global_load_lds_dwordx4 v206, s[72:73]
	v_mfma_f32_32x32x16_bf16 v[18:33], v[220:223], v[224:227], v[18:33]
	s_add_u32 m0, s78, 0x2000
	ds_read_b128 v[244:247], v215 offset:8192
	global_load_lds_dwordx4 v205, s[72:73]
	s_add_u32 m0, s78, 0x3000
	s_nop 0
	global_load_lds_dwordx4 v204, s[72:73]
	v_mfma_f32_32x32x16_bf16 v[2:17], v[216:219], v[224:227], v[2:17]
	s_add_u32 s74, s74, 2
	s_cmp_lt_u32 s74, 14
	s_cbranch_scc1 .Lgm_ph20_loop
	s_waitcnt lgkmcnt(1)
	v_mfma_f32_32x32x16_bf16 v[82:97], v[240:243], v[252:255], v[82:97]
	ds_read_b128 v[220:223], v210 offset:0
	v_mfma_f32_32x32x16_bf16 v[66:81], v[236:239], v[252:255], v[66:81]
	ds_read_b128 v[232:235], v214 offset:0
	v_mfma_f32_32x32x16_bf16 v[50:65], v[240:243], v[248:251], v[50:65]
	ds_read_b128 v[216:219], v210 offset:4096
	v_mfma_f32_32x32x16_bf16 v[34:49], v[236:239], v[248:251], v[34:49]
	ds_read_b128 v[228:231], v214 offset:4096
	s_waitcnt lgkmcnt(4)
	v_mfma_f32_32x32x16_bf16 v[18:33], v[240:243], v[244:247], v[18:33]
	ds_read_b128 v[224:227], v214 offset:8192
	v_mfma_f32_32x32x16_bf16 v[2:17], v[236:239], v[244:247], v[2:17]
	s_waitcnt lgkmcnt(1)
	v_mfma_f32_32x32x16_bf16 v[82:97], v[220:223], v[232:235], v[82:97]
	ds_read_b128 v[240:243], v209 offset:0
	v_mfma_f32_32x32x16_bf16 v[66:81], v[216:219], v[232:235], v[66:81]
	ds_read_b128 v[252:255], v213 offset:0
	v_mfma_f32_32x32x16_bf16 v[50:65], v[220:223], v[228:231], v[50:65]
	ds_read_b128 v[236:239], v209 offset:4096
	v_mfma_f32_32x32x16_bf16 v[34:49], v[216:219], v[228:231], v[34:49]
	ds_read_b128 v[248:251], v213 offset:4096
	s_waitcnt lgkmcnt(4)
	v_mfma_f32_32x32x16_bf16 v[18:33], v[220:223], v[224:227], v[18:33]
	ds_read_b128 v[244:247], v213 offset:8192
	v_mfma_f32_32x32x16_bf16 v[2:17], v[216:219], v[224:227], v[2:17]
	s_waitcnt lgkmcnt(1)
	v_mfma_f32_32x32x16_bf16 v[82:97], v[240:243], v[252:255], v[82:97]
	ds_read_b128 v[220:223], v208 offset:0
	v_mfma_f32_32x32x16_bf16 v[66:81], v[236:239], v[252:255], v[66:81]
	ds_read_b128 v[232:235], v212 offset:0
	v_mfma_f32_32x32x16_bf16 v[50:65], v[240:243], v[248:251], v[50:65]
	ds_read_b128 v[216:219], v208 offset:4096
	v_mfma_f32_32x32x16_bf16 v[34:49], v[236:239], v[248:251], v[34:49]
	ds_read_b128 v[228:231], v212 offset:4096
	s_waitcnt lgkmcnt(4)
	v_mfma_f32_32x32x16_bf16 v[18:33], v[240:243], v[244:247], v[18:33]
	ds_read_b128 v[224:227], v212 offset:8192
	v_mfma_f32_32x32x16_bf16 v[2:17], v[236:239], v[244:247], v[2:17]
	s_waitcnt vmcnt(0) lgkmcnt(0)
	s_barrier
	v_mfma_f32_32x32x16_bf16 v[82:97], v[220:223], v[232:235], v[82:97]
	ds_read_b128 v[240:243], v211 offset:16384
	v_mfma_f32_32x32x16_bf16 v[66:81], v[216:219], v[232:235], v[66:81]
	ds_read_b128 v[252:255], v215 offset:24576
	v_mfma_f32_32x32x16_bf16 v[50:65], v[220:223], v[228:231], v[50:65]
	ds_read_b128 v[236:239], v211 offset:20480
	v_mfma_f32_32x32x16_bf16 v[34:49], v[216:219], v[228:231], v[34:49]
	ds_read_b128 v[248:251], v215 offset:28672
	v_mfma_f32_32x32x16_bf16 v[18:33], v[220:223], v[224:227], v[18:33]
	ds_read_b128 v[244:247], v215 offset:32768
	v_mfma_f32_32x32x16_bf16 v[2:17], v[216:219], v[224:227], v[2:17]
	s_waitcnt lgkmcnt(1)
	v_mfma_f32_32x32x16_bf16 v[82:97], v[240:243], v[252:255], v[82:97]
	ds_read_b128 v[220:223], v210 offset:16384
	v_mfma_f32_32x32x16_bf16 v[66:81], v[236:239], v[252:255], v[66:81]
	ds_read_b128 v[232:235], v214 offset:24576
	v_mfma_f32_32x32x16_bf16 v[50:65], v[240:243], v[248:251], v[50:65]
	ds_read_b128 v[216:219], v210 offset:20480
	v_mfma_f32_32x32x16_bf16 v[34:49], v[236:239], v[248:251], v[34:49]
	ds_read_b128 v[228:231], v214 offset:28672
	s_waitcnt lgkmcnt(4)
	v_mfma_f32_32x32x16_bf16 v[18:33], v[240:243], v[244:247], v[18:33]
	ds_read_b128 v[224:227], v214 offset:32768
	v_mfma_f32_32x32x16_bf16 v[2:17], v[236:239], v[244:247], v[2:17]
	s_waitcnt lgkmcnt(1)
	v_mfma_f32_32x32x16_bf16 v[82:97], v[220:223], v[232:235], v[82:97]
	ds_read_b128 v[240:243], v209 offset:16384
	v_mfma_f32_32x32x16_bf16 v[66:81], v[216:219], v[232:235], v[66:81]
	ds_read_b128 v[252:255], v213 offset:24576
	v_mfma_f32_32x32x16_bf16 v[50:65], v[220:223], v[228:231], v[50:65]
	ds_read_b128 v[236:239], v209 offset:20480
	v_mfma_f32_32x32x16_bf16 v[34:49], v[216:219], v[228:231], v[34:49]
	ds_read_b128 v[248:251], v213 offset:28672
	s_waitcnt lgkmcnt(4)
	v_mfma_f32_32x32x16_bf16 v[18:33], v[220:223], v[224:227], v[18:33]
	ds_read_b128 v[244:247], v213 offset:32768
	v_mfma_f32_32x32x16_bf16 v[2:17], v[216:219], v[224:227], v[2:17]
	s_waitcnt lgkmcnt(1)
	v_mfma_f32_32x32x16_bf16 v[82:97], v[240:243], v[252:255], v[82:97]
	ds_read_b128 v[220:223], v208 offset:16384
	v_mfma_f32_32x32x16_bf16 v[66:81], v[236:239], v[252:255], v[66:81]
	ds_read_b128 v[232:235], v212 offset:24576
	v_mfma_f32_32x32x16_bf16 v[50:65], v[240:243], v[248:251], v[50:65]
	ds_read_b128 v[216:219], v208 offset:20480
	v_mfma_f32_32x32x16_bf16 v[34:49], v[236:239], v[248:251], v[34:49]
	ds_read_b128 v[228:231], v212 offset:28672
	s_waitcnt lgkmcnt(4)
	v_mfma_f32_32x32x16_bf16 v[18:33], v[240:243], v[244:247], v[18:33]
	ds_read_b128 v[224:227], v212 offset:32768
	v_mfma_f32_32x32x16_bf16 v[2:17], v[236:239], v[244:247], v[2:17]
	s_waitcnt vmcnt(0) lgkmcnt(0)
	s_barrier
	v_mfma_f32_32x32x16_bf16 v[82:97], v[220:223], v[232:235], v[82:97]
	v_mfma_f32_32x32x16_bf16 v[66:81], v[216:219], v[232:235], v[66:81]
	v_mfma_f32_32x32x16_bf16 v[50:65], v[220:223], v[228:231], v[50:65]
	v_mfma_f32_32x32x16_bf16 v[34:49], v[216:219], v[228:231], v[34:49]
	v_mfma_f32_32x32x16_bf16 v[18:33], v[220:223], v[224:227], v[18:33]
	v_mfma_f32_32x32x16_bf16 v[2:17], v[216:219], v[224:227], v[2:17]
	s_nop 7
	s_nop 7
	s_waitcnt lgkmcnt(0)
	s_nop 10
	ds_write_b128 v145, v[82:85]
	ds_write_b128 v145, v[86:89] offset:32
	ds_write_b128 v145, v[90:93] offset:64
	ds_write_b128 v145, v[94:97] offset:96
	ds_write_b128 v145, v[66:69] offset:128
	ds_write_b128 v145, v[70:73] offset:160
	ds_write_b128 v145, v[74:77] offset:192
	ds_write_b128 v145, v[78:81] offset:224
	s_waitcnt lgkmcnt(0)
	v_add_u32_e32 v104, s28, v111
	v_add_u32_e32 v67, 0xfffff000, v104
	v_or_b32_e32 v66, v104, v1
	v_lshrrev_b32_e32 v67, 11, v67
	v_or_b32_e32 v106, s29, v119
	v_mad_u32_u24 v80, v67, s26, s26
	v_cmp_lt_i32_e32 vcc, s27, v66
	v_ashrrev_i32_e32 v107, 31, v106
	v_lshlrev_b64 v[68:69], 2, v[106:107]
	v_cndmask_b32_e32 v98, 0, v80, vcc
	v_lshl_add_u64 v[70:71], v[98:99], 2, s[6:7]
	v_lshl_add_u64 v[74:75], v[70:71], 0, v[68:69]
	v_add_co_u32_e32 v74, vcc, s3, v74
	ds_read_b128 v[70:73], v147
	s_nop 0
	v_addc_co_u32_e32 v75, vcc, 0, v75, vcc
	global_load_dwordx4 v[74:77], v[74:75], off
	v_ashrrev_i32_e32 v67, 31, v66
	v_lshlrev_b64 v[66:67], 11, v[66:67]
	v_or_b32_e32 v78, v104, v120
	v_cmp_lt_i32_e32 vcc, s27, v78
	v_ashrrev_i32_e32 v79, 31, v78
	v_cndmask_b32_e32 v98, 0, v80, vcc
	s_waitcnt vmcnt(0) lgkmcnt(0)
	v_mul_f32_e64 v70, v70, v74
	v_mul_f32_e64 v71, v71, v75
	v_mul_f32_e64 v72, v72, v76
	v_mul_f32_e64 v73, v73, v77
	v_cvt_pk_bf16_f32 v70, v70, v71
	v_cvt_pk_bf16_f32 v71, v72, v73
	v_lshl_add_u64 v[72:73], s[4:5], 0, v[66:67]
	v_lshlrev_b64 v[66:67], 1, v[106:107]
	v_lshl_add_u64 v[72:73], v[72:73], 0, v[66:67]
	global_store_dwordx2 v[72:73], v[70:71], off
	v_lshl_add_u64 v[70:71], v[98:99], 2, s[6:7]
	v_lshl_add_u64 v[74:75], v[70:71], 0, v[68:69]
	v_add_co_u32_e32 v74, vcc, s3, v74
	ds_read_b128 v[70:73], v147 offset:1088
	s_nop 0
	v_addc_co_u32_e32 v75, vcc, 0, v75, vcc
	global_load_dwordx4 v[74:77], v[74:75], off
	s_waitcnt vmcnt(0) lgkmcnt(0)
	v_mul_f32_e64 v70, v70, v74
	v_mul_f32_e64 v71, v71, v75
	v_mul_f32_e64 v72, v72, v76
	v_mul_f32_e64 v73, v73, v77
	v_cvt_pk_bf16_f32 v70, v70, v71
	v_cvt_pk_bf16_f32 v71, v72, v73
	v_lshlrev_b64 v[72:73], 11, v[78:79]
	v_or_b32_e32 v78, v104, v121
	v_lshl_add_u64 v[72:73], s[4:5], 0, v[72:73]
	v_cmp_lt_i32_e32 vcc, s27, v78
	v_lshl_add_u64 v[72:73], v[72:73], 0, v[66:67]
	global_store_dwordx2 v[72:73], v[70:71], off
	v_cndmask_b32_e32 v98, 0, v80, vcc
	v_lshl_add_u64 v[70:71], v[98:99], 2, s[6:7]
	v_lshl_add_u64 v[74:75], v[70:71], 0, v[68:69]
	v_add_co_u32_e32 v74, vcc, s3, v74
	ds_read_b128 v[70:73], v147 offset:2176
	s_nop 0
	v_addc_co_u32_e32 v75, vcc, 0, v75, vcc
	global_load_dwordx4 v[74:77], v[74:75], off
	v_ashrrev_i32_e32 v79, 31, v78
	s_waitcnt vmcnt(0) lgkmcnt(0)
	v_mul_f32_e64 v70, v70, v74
	v_mul_f32_e64 v71, v71, v75
	v_mul_f32_e64 v72, v72, v76
	v_mul_f32_e64 v73, v73, v77
	v_cvt_pk_bf16_f32 v70, v70, v71
	v_cvt_pk_bf16_f32 v71, v72, v73
	v_lshlrev_b64 v[72:73], 11, v[78:79]
	v_or_b32_e32 v78, v104, v122
	v_lshl_add_u64 v[72:73], s[4:5], 0, v[72:73]
	v_cmp_lt_i32_e32 vcc, s27, v78
	v_lshl_add_u64 v[72:73], v[72:73], 0, v[66:67]
	global_store_dwordx2 v[72:73], v[70:71], off
	v_cndmask_b32_e32 v98, 0, v80, vcc
	v_lshl_add_u64 v[70:71], v[98:99], 2, s[6:7]
	v_lshl_add_u64 v[74:75], v[70:71], 0, v[68:69]
	v_add_co_u32_e32 v74, vcc, s3, v74
	ds_read_b128 v[70:73], v147 offset:3264
	s_nop 0
	v_addc_co_u32_e32 v75, vcc, 0, v75, vcc
	global_load_dwordx4 v[74:77], v[74:75], off
	v_ashrrev_i32_e32 v79, 31, v78
	s_waitcnt vmcnt(0) lgkmcnt(0)
	v_mul_f32_e64 v70, v70, v74
	v_mul_f32_e64 v71, v71, v75
	v_mul_f32_e64 v72, v72, v76
	v_mul_f32_e64 v73, v73, v77
	v_cvt_pk_bf16_f32 v70, v70, v71
	v_cvt_pk_bf16_f32 v71, v72, v73
	v_lshlrev_b64 v[72:73], 11, v[78:79]
	v_or_b32_e32 v78, v104, v123
	v_lshl_add_u64 v[72:73], s[4:5], 0, v[72:73]
	v_cmp_lt_i32_e32 vcc, s27, v78
	v_lshl_add_u64 v[72:73], v[72:73], 0, v[66:67]
	global_store_dwordx2 v[72:73], v[70:71], off
	v_cndmask_b32_e32 v98, 0, v80, vcc
	v_lshl_add_u64 v[70:71], v[98:99], 2, s[6:7]
	v_lshl_add_u64 v[74:75], v[70:71], 0, v[68:69]
	v_add_co_u32_e32 v74, vcc, s3, v74
	ds_read_b128 v[70:73], v147 offset:4352
	s_nop 0
	v_addc_co_u32_e32 v75, vcc, 0, v75, vcc
	global_load_dwordx4 v[74:77], v[74:75], off
	v_ashrrev_i32_e32 v79, 31, v78
	s_waitcnt vmcnt(0) lgkmcnt(0)
	v_mul_f32_e64 v70, v70, v74
	v_mul_f32_e64 v71, v71, v75
	v_mul_f32_e64 v72, v72, v76
	v_mul_f32_e64 v73, v73, v77
	v_cvt_pk_bf16_f32 v70, v70, v71
	v_cvt_pk_bf16_f32 v71, v72, v73
	v_lshlrev_b64 v[72:73], 11, v[78:79]
	v_or_b32_e32 v78, v104, v124
	v_lshl_add_u64 v[72:73], s[4:5], 0, v[72:73]
	v_cmp_lt_i32_e32 vcc, s27, v78
	v_lshl_add_u64 v[72:73], v[72:73], 0, v[66:67]
	global_store_dwordx2 v[72:73], v[70:71], off
	v_cndmask_b32_e32 v98, 0, v80, vcc
	v_lshl_add_u64 v[70:71], v[98:99], 2, s[6:7]
	v_lshl_add_u64 v[74:75], v[70:71], 0, v[68:69]
	v_add_co_u32_e32 v74, vcc, s3, v74
	ds_read_b128 v[70:73], v147 offset:5440
	s_nop 0
	v_addc_co_u32_e32 v75, vcc, 0, v75, vcc
	global_load_dwordx4 v[74:77], v[74:75], off
	v_ashrrev_i32_e32 v79, 31, v78
	s_waitcnt vmcnt(0) lgkmcnt(0)
	v_mul_f32_e64 v70, v70, v74
	v_mul_f32_e64 v71, v71, v75
	v_mul_f32_e64 v72, v72, v76
	v_mul_f32_e64 v73, v73, v77
	v_cvt_pk_bf16_f32 v70, v70, v71
	v_cvt_pk_bf16_f32 v71, v72, v73
	v_lshlrev_b64 v[72:73], 11, v[78:79]
	v_or_b32_e32 v78, v104, v125
	v_lshl_add_u64 v[72:73], s[4:5], 0, v[72:73]
	v_cmp_lt_i32_e32 vcc, s27, v78
	v_lshl_add_u64 v[72:73], v[72:73], 0, v[66:67]
	global_store_dwordx2 v[72:73], v[70:71], off
	v_cndmask_b32_e32 v98, 0, v80, vcc
	v_lshl_add_u64 v[70:71], v[98:99], 2, s[6:7]
	v_lshl_add_u64 v[74:75], v[70:71], 0, v[68:69]
	v_add_co_u32_e32 v74, vcc, s3, v74
	ds_read_b128 v[70:73], v147 offset:6528
	s_nop 0
	v_addc_co_u32_e32 v75, vcc, 0, v75, vcc
	global_load_dwordx4 v[74:77], v[74:75], off
	v_ashrrev_i32_e32 v79, 31, v78
	s_waitcnt vmcnt(0) lgkmcnt(0)
	v_mul_f32_e64 v70, v70, v74
	v_mul_f32_e64 v71, v71, v75
	v_mul_f32_e64 v72, v72, v76
	v_mul_f32_e64 v73, v73, v77
	v_cvt_pk_bf16_f32 v70, v70, v71
	v_cvt_pk_bf16_f32 v71, v72, v73
	v_lshlrev_b64 v[72:73], 11, v[78:79]
	v_or_b32_e32 v78, v104, v126
	v_lshl_add_u64 v[72:73], s[4:5], 0, v[72:73]
	v_cmp_lt_i32_e32 vcc, s27, v78
	v_lshl_add_u64 v[72:73], v[72:73], 0, v[66:67]
	global_store_dwordx2 v[72:73], v[70:71], off
	v_cndmask_b32_e32 v98, 0, v80, vcc
	v_lshl_add_u64 v[70:71], v[98:99], 2, s[6:7]
	v_lshl_add_u64 v[74:75], v[70:71], 0, v[68:69]
	v_add_co_u32_e32 v74, vcc, s3, v74
	ds_read_b128 v[70:73], v147 offset:7616
	s_nop 0
	v_addc_co_u32_e32 v75, vcc, 0, v75, vcc
	global_load_dwordx4 v[74:77], v[74:75], off
	v_ashrrev_i32_e32 v79, 31, v78
	s_waitcnt vmcnt(0) lgkmcnt(0)
	v_mul_f32_e64 v70, v70, v74
	v_mul_f32_e64 v71, v71, v75
	v_mul_f32_e64 v72, v72, v76
	v_mul_f32_e64 v73, v73, v77
	v_cvt_pk_bf16_f32 v70, v70, v71
	v_cvt_pk_bf16_f32 v71, v72, v73
	v_lshlrev_b64 v[72:73], 11, v[78:79]
	v_lshl_add_u64 v[72:73], s[4:5], 0, v[72:73]
	v_lshl_add_u64 v[72:73], v[72:73], 0, v[66:67]
	global_store_dwordx2 v[72:73], v[70:71], off
	s_waitcnt lgkmcnt(0)
	ds_write_b128 v145, v[50:53]
	ds_write_b128 v145, v[54:57] offset:32
	ds_write_b128 v145, v[58:61] offset:64
	ds_write_b128 v145, v[62:65] offset:96
	ds_write_b128 v145, v[34:37] offset:128
	ds_write_b128 v145, v[38:41] offset:160
	ds_write_b128 v145, v[42:45] offset:192
	ds_write_b128 v145, v[46:49] offset:224
	v_add_u32_e32 v34, 32, v104
	v_add_u32_e32 v35, 0xfffff020, v104
	v_or_b32_e32 v44, v34, v1
	v_lshrrev_b32_e32 v35, 11, v35
	v_mad_u32_u24 v35, v35, s26, s26
	v_cmp_lt_i32_e32 vcc, s27, v44
	s_waitcnt lgkmcnt(0)
	v_ashrrev_i32_e32 v45, 31, v44
	v_cndmask_b32_e32 v98, 0, v35, vcc
	v_lshl_add_u64 v[36:37], v[98:99], 2, s[6:7]
	v_lshl_add_u64 v[40:41], v[36:37], 0, v[68:69]
	v_add_co_u32_e32 v40, vcc, s3, v40
	ds_read_b128 v[36:39], v147
	s_nop 0
	v_addc_co_u32_e32 v41, vcc, 0, v41, vcc
	global_load_dwordx4 v[40:43], v[40:41], off
	s_waitcnt vmcnt(0) lgkmcnt(0)
	v_mul_f32_e64 v36, v36, v40
	v_mul_f32_e64 v37, v37, v41
	v_mul_f32_e64 v38, v38, v42
	v_mul_f32_e64 v39, v39, v43
	v_cvt_pk_bf16_f32 v36, v36, v37
	v_cvt_pk_bf16_f32 v37, v38, v39
	v_lshlrev_b64 v[38:39], 11, v[44:45]
	v_or_b32_e32 v44, v34, v120
	v_lshl_add_u64 v[38:39], s[4:5], 0, v[38:39]
	v_cmp_lt_i32_e32 vcc, s27, v44
	v_lshl_add_u64 v[38:39], v[38:39], 0, v[66:67]
	global_store_dwordx2 v[38:39], v[36:37], off
	v_cndmask_b32_e32 v98, 0, v35, vcc
	v_lshl_add_u64 v[36:37], v[98:99], 2, s[6:7]
	v_lshl_add_u64 v[40:41], v[36:37], 0, v[68:69]
	v_add_co_u32_e32 v40, vcc, s3, v40
	ds_read_b128 v[36:39], v147 offset:1088
	s_nop 0
	v_addc_co_u32_e32 v41, vcc, 0, v41, vcc
	global_load_dwordx4 v[40:43], v[40:41], off
	v_ashrrev_i32_e32 v45, 31, v44
	s_waitcnt vmcnt(0) lgkmcnt(0)
	v_mul_f32_e64 v36, v36, v40
	v_mul_f32_e64 v37, v37, v41
	v_mul_f32_e64 v38, v38, v42
	v_mul_f32_e64 v39, v39, v43
	v_cvt_pk_bf16_f32 v36, v36, v37
	v_cvt_pk_bf16_f32 v37, v38, v39
	v_lshlrev_b64 v[38:39], 11, v[44:45]
	v_or_b32_e32 v44, v34, v121
	v_lshl_add_u64 v[38:39], s[4:5], 0, v[38:39]
	v_cmp_lt_i32_e32 vcc, s27, v44
	v_lshl_add_u64 v[38:39], v[38:39], 0, v[66:67]
	global_store_dwordx2 v[38:39], v[36:37], off
	v_cndmask_b32_e32 v98, 0, v35, vcc
	v_lshl_add_u64 v[36:37], v[98:99], 2, s[6:7]
	v_lshl_add_u64 v[40:41], v[36:37], 0, v[68:69]
	v_add_co_u32_e32 v40, vcc, s3, v40
	ds_read_b128 v[36:39], v147 offset:2176
	s_nop 0
	v_addc_co_u32_e32 v41, vcc, 0, v41, vcc
	global_load_dwordx4 v[40:43], v[40:41], off
	v_ashrrev_i32_e32 v45, 31, v44
	s_waitcnt vmcnt(0) lgkmcnt(0)
	v_mul_f32_e64 v36, v36, v40
	v_mul_f32_e64 v37, v37, v41
	v_mul_f32_e64 v38, v38, v42
	v_mul_f32_e64 v39, v39, v43
	v_cvt_pk_bf16_f32 v36, v36, v37
	v_cvt_pk_bf16_f32 v37, v38, v39
	v_lshlrev_b64 v[38:39], 11, v[44:45]
	v_or_b32_e32 v44, v34, v122
	v_lshl_add_u64 v[38:39], s[4:5], 0, v[38:39]
	v_cmp_lt_i32_e32 vcc, s27, v44
	v_lshl_add_u64 v[38:39], v[38:39], 0, v[66:67]
	global_store_dwordx2 v[38:39], v[36:37], off
	v_cndmask_b32_e32 v98, 0, v35, vcc
	v_lshl_add_u64 v[36:37], v[98:99], 2, s[6:7]
	v_lshl_add_u64 v[40:41], v[36:37], 0, v[68:69]
	v_add_co_u32_e32 v40, vcc, s3, v40
	ds_read_b128 v[36:39], v147 offset:3264
	s_nop 0
	v_addc_co_u32_e32 v41, vcc, 0, v41, vcc
	global_load_dwordx4 v[40:43], v[40:41], off
	v_ashrrev_i32_e32 v45, 31, v44
	s_waitcnt vmcnt(0) lgkmcnt(0)
	v_mul_f32_e64 v36, v36, v40
	v_mul_f32_e64 v37, v37, v41
	v_mul_f32_e64 v38, v38, v42
	v_mul_f32_e64 v39, v39, v43
	v_cvt_pk_bf16_f32 v36, v36, v37
	v_cvt_pk_bf16_f32 v37, v38, v39
	v_lshlrev_b64 v[38:39], 11, v[44:45]
	v_or_b32_e32 v44, v34, v123
	v_lshl_add_u64 v[38:39], s[4:5], 0, v[38:39]
	v_cmp_lt_i32_e32 vcc, s27, v44
	v_lshl_add_u64 v[38:39], v[38:39], 0, v[66:67]
	global_store_dwordx2 v[38:39], v[36:37], off
	v_cndmask_b32_e32 v98, 0, v35, vcc
	v_lshl_add_u64 v[36:37], v[98:99], 2, s[6:7]
	v_lshl_add_u64 v[40:41], v[36:37], 0, v[68:69]
	v_add_co_u32_e32 v40, vcc, s3, v40
	ds_read_b128 v[36:39], v147 offset:4352
	s_nop 0
	v_addc_co_u32_e32 v41, vcc, 0, v41, vcc
	global_load_dwordx4 v[40:43], v[40:41], off
	v_ashrrev_i32_e32 v45, 31, v44
	s_waitcnt vmcnt(0) lgkmcnt(0)
	v_mul_f32_e64 v36, v36, v40
	v_mul_f32_e64 v37, v37, v41
	v_mul_f32_e64 v38, v38, v42
	v_mul_f32_e64 v39, v39, v43
	v_cvt_pk_bf16_f32 v36, v36, v37
	v_cvt_pk_bf16_f32 v37, v38, v39
	v_lshlrev_b64 v[38:39], 11, v[44:45]
	v_or_b32_e32 v44, v34, v124
	v_lshl_add_u64 v[38:39], s[4:5], 0, v[38:39]
	v_cmp_lt_i32_e32 vcc, s27, v44
	v_lshl_add_u64 v[38:39], v[38:39], 0, v[66:67]
	global_store_dwordx2 v[38:39], v[36:37], off
	v_cndmask_b32_e32 v98, 0, v35, vcc
	v_lshl_add_u64 v[36:37], v[98:99], 2, s[6:7]
	v_lshl_add_u64 v[40:41], v[36:37], 0, v[68:69]
	v_add_co_u32_e32 v40, vcc, s3, v40
	ds_read_b128 v[36:39], v147 offset:5440
	s_nop 0
	v_addc_co_u32_e32 v41, vcc, 0, v41, vcc
	global_load_dwordx4 v[40:43], v[40:41], off
	v_ashrrev_i32_e32 v45, 31, v44
	s_waitcnt vmcnt(0) lgkmcnt(0)
	v_pk_mul_f32 v[36:37], v[36:37], v[40:41]
	v_pk_mul_f32 v[38:39], v[38:39], v[42:43]
	v_cvt_pk_bf16_f32 v36, v36, v37
	v_cvt_pk_bf16_f32 v37, v38, v39
	v_lshlrev_b64 v[38:39], 11, v[44:45]
	v_or_b32_e32 v44, v34, v125
	v_lshl_add_u64 v[38:39], s[4:5], 0, v[38:39]
	v_cmp_lt_i32_e32 vcc, s27, v44
	v_lshl_add_u64 v[38:39], v[38:39], 0, v[66:67]
	global_store_dwordx2 v[38:39], v[36:37], off
	v_cndmask_b32_e32 v98, 0, v35, vcc
	v_lshl_add_u64 v[36:37], v[98:99], 2, s[6:7]
	v_lshl_add_u64 v[40:41], v[36:37], 0, v[68:69]
	v_add_co_u32_e32 v40, vcc, s3, v40
	ds_read_b128 v[36:39], v147 offset:6528
	s_nop 0
	v_addc_co_u32_e32 v41, vcc, 0, v41, vcc
	global_load_dwordx4 v[40:43], v[40:41], off
	v_ashrrev_i32_e32 v45, 31, v44
	s_waitcnt vmcnt(0) lgkmcnt(0)
	v_pk_mul_f32 v[36:37], v[36:37], v[40:41]
	v_pk_mul_f32 v[38:39], v[38:39], v[42:43]
	v_or_b32_e32 v42, v34, v126
	v_cvt_pk_bf16_f32 v36, v36, v37
	v_cvt_pk_bf16_f32 v37, v38, v39
	v_lshlrev_b64 v[38:39], 11, v[44:45]
	v_cmp_lt_i32_e32 vcc, s27, v42
	v_lshl_add_u64 v[38:39], s[4:5], 0, v[38:39]
	v_lshl_add_u64 v[38:39], v[38:39], 0, v[66:67]
	v_cndmask_b32_e32 v98, 0, v35, vcc
	v_lshl_add_u64 v[34:35], v[98:99], 2, s[6:7]
	global_store_dwordx2 v[38:39], v[36:37], off
	v_lshl_add_u64 v[38:39], v[34:35], 0, v[68:69]
	v_add_co_u32_e32 v38, vcc, s3, v38
	ds_read_b128 v[34:37], v147 offset:7616
	s_nop 0
	v_addc_co_u32_e32 v39, vcc, 0, v39, vcc
	global_load_dwordx4 v[38:41], v[38:39], off
	v_ashrrev_i32_e32 v43, 31, v42
	s_waitcnt vmcnt(0) lgkmcnt(0)
	v_pk_mul_f32 v[34:35], v[34:35], v[38:39]
	v_pk_mul_f32 v[36:37], v[36:37], v[40:41]
	v_cvt_pk_bf16_f32 v34, v34, v35
	v_cvt_pk_bf16_f32 v35, v36, v37
	v_lshlrev_b64 v[36:37], 11, v[42:43]
	v_lshl_add_u64 v[36:37], s[4:5], 0, v[36:37]
	v_lshl_add_u64 v[36:37], v[36:37], 0, v[66:67]
	global_store_dwordx2 v[36:37], v[34:35], off
	s_waitcnt lgkmcnt(0)
	ds_write_b128 v145, v[18:21]
	ds_write_b128 v145, v[22:25] offset:32
	ds_write_b128 v145, v[26:29] offset:64
	ds_write_b128 v145, v[30:33] offset:96
	ds_write_b128 v145, v[2:5] offset:128
	ds_write_b128 v145, v[6:9] offset:160
	ds_write_b128 v145, v[10:13] offset:192
	ds_write_b128 v145, v[14:17] offset:224
	v_add_u32_e32 v2, 64, v104
	v_add_u32_e32 v3, 0xfffff040, v104
	v_or_b32_e32 v12, v2, v1
	v_lshrrev_b32_e32 v3, 11, v3
	v_mad_u32_u24 v3, v3, s26, s26
	v_cmp_lt_i32_e32 vcc, s27, v12
	s_waitcnt lgkmcnt(0)
	v_ashrrev_i32_e32 v13, 31, v12
	s_nop 0
	v_cndmask_b32_e32 v98, 0, v3, vcc
	v_lshl_add_u64 v[4:5], v[98:99], 2, s[6:7]
	v_lshl_add_u64 v[8:9], v[4:5], 0, v[68:69]
	v_add_co_u32_e32 v8, vcc, s3, v8
	ds_read_b128 v[4:7], v147
	s_nop 0
	v_addc_co_u32_e32 v9, vcc, 0, v9, vcc
	global_load_dwordx4 v[8:11], v[8:9], off
	s_waitcnt vmcnt(0) lgkmcnt(0)
	v_pk_mul_f32 v[4:5], v[4:5], v[8:9]
	v_pk_mul_f32 v[6:7], v[6:7], v[10:11]
	v_cvt_pk_bf16_f32 v4, v4, v5
	v_cvt_pk_bf16_f32 v5, v6, v7
	v_lshlrev_b64 v[6:7], 11, v[12:13]
	v_or_b32_e32 v12, v2, v120
	v_lshl_add_u64 v[6:7], s[4:5], 0, v[6:7]
	v_cmp_lt_i32_e32 vcc, s27, v12
	v_lshl_add_u64 v[6:7], v[6:7], 0, v[66:67]
	global_store_dwordx2 v[6:7], v[4:5], off
	v_cndmask_b32_e32 v98, 0, v3, vcc
	v_lshl_add_u64 v[4:5], v[98:99], 2, s[6:7]
	v_lshl_add_u64 v[8:9], v[4:5], 0, v[68:69]
	v_add_co_u32_e32 v8, vcc, s3, v8
	ds_read_b128 v[4:7], v147 offset:1088
	s_nop 0
	v_addc_co_u32_e32 v9, vcc, 0, v9, vcc
	global_load_dwordx4 v[8:11], v[8:9], off
	v_ashrrev_i32_e32 v13, 31, v12
	s_waitcnt vmcnt(0) lgkmcnt(0)
	v_pk_mul_f32 v[4:5], v[4:5], v[8:9]
	v_pk_mul_f32 v[6:7], v[6:7], v[10:11]
	v_cvt_pk_bf16_f32 v4, v4, v5
	v_cvt_pk_bf16_f32 v5, v6, v7
	v_lshlrev_b64 v[6:7], 11, v[12:13]
	v_or_b32_e32 v12, v2, v121
	v_lshl_add_u64 v[6:7], s[4:5], 0, v[6:7]
	v_cmp_lt_i32_e32 vcc, s27, v12
	v_lshl_add_u64 v[6:7], v[6:7], 0, v[66:67]
	global_store_dwordx2 v[6:7], v[4:5], off
	v_cndmask_b32_e32 v98, 0, v3, vcc
	v_lshl_add_u64 v[4:5], v[98:99], 2, s[6:7]
	v_lshl_add_u64 v[8:9], v[4:5], 0, v[68:69]
	v_add_co_u32_e32 v8, vcc, s3, v8
	ds_read_b128 v[4:7], v147 offset:2176
	s_nop 0
	v_addc_co_u32_e32 v9, vcc, 0, v9, vcc
	global_load_dwordx4 v[8:11], v[8:9], off
	v_ashrrev_i32_e32 v13, 31, v12
	s_waitcnt vmcnt(0) lgkmcnt(0)
	v_pk_mul_f32 v[4:5], v[4:5], v[8:9]
	v_pk_mul_f32 v[6:7], v[6:7], v[10:11]
	v_cvt_pk_bf16_f32 v4, v4, v5
	v_cvt_pk_bf16_f32 v5, v6, v7
	v_lshlrev_b64 v[6:7], 11, v[12:13]
	v_or_b32_e32 v12, v2, v122
	v_lshl_add_u64 v[6:7], s[4:5], 0, v[6:7]
	v_cmp_lt_i32_e32 vcc, s27, v12
	v_lshl_add_u64 v[6:7], v[6:7], 0, v[66:67]
	global_store_dwordx2 v[6:7], v[4:5], off
	v_cndmask_b32_e32 v98, 0, v3, vcc
	v_lshl_add_u64 v[4:5], v[98:99], 2, s[6:7]
	v_lshl_add_u64 v[8:9], v[4:5], 0, v[68:69]
	v_add_co_u32_e32 v8, vcc, s3, v8
	ds_read_b128 v[4:7], v147 offset:3264
	s_nop 0
	v_addc_co_u32_e32 v9, vcc, 0, v9, vcc
	global_load_dwordx4 v[8:11], v[8:9], off
	v_ashrrev_i32_e32 v13, 31, v12
	s_waitcnt vmcnt(0) lgkmcnt(0)
	v_pk_mul_f32 v[4:5], v[4:5], v[8:9]
	v_pk_mul_f32 v[6:7], v[6:7], v[10:11]
	v_cvt_pk_bf16_f32 v4, v4, v5
	v_cvt_pk_bf16_f32 v5, v6, v7
	v_lshlrev_b64 v[6:7], 11, v[12:13]
	v_or_b32_e32 v12, v2, v123
	v_lshl_add_u64 v[6:7], s[4:5], 0, v[6:7]
	v_cmp_lt_i32_e32 vcc, s27, v12
	v_lshl_add_u64 v[6:7], v[6:7], 0, v[66:67]
	global_store_dwordx2 v[6:7], v[4:5], off
	v_cndmask_b32_e32 v98, 0, v3, vcc
	v_lshl_add_u64 v[4:5], v[98:99], 2, s[6:7]
	v_lshl_add_u64 v[8:9], v[4:5], 0, v[68:69]
	v_add_co_u32_e32 v8, vcc, s3, v8
	ds_read_b128 v[4:7], v147 offset:4352
	s_nop 0
	v_addc_co_u32_e32 v9, vcc, 0, v9, vcc
	global_load_dwordx4 v[8:11], v[8:9], off
	v_ashrrev_i32_e32 v13, 31, v12
	s_waitcnt vmcnt(0) lgkmcnt(0)
	v_pk_mul_f32 v[4:5], v[4:5], v[8:9]
	v_pk_mul_f32 v[6:7], v[6:7], v[10:11]
	v_cvt_pk_bf16_f32 v4, v4, v5
	v_cvt_pk_bf16_f32 v5, v6, v7
	v_lshlrev_b64 v[6:7], 11, v[12:13]
	v_or_b32_e32 v12, v2, v124
	v_lshl_add_u64 v[6:7], s[4:5], 0, v[6:7]
	v_cmp_lt_i32_e32 vcc, s27, v12
	v_lshl_add_u64 v[6:7], v[6:7], 0, v[66:67]
	global_store_dwordx2 v[6:7], v[4:5], off
	v_cndmask_b32_e32 v98, 0, v3, vcc
	v_lshl_add_u64 v[4:5], v[98:99], 2, s[6:7]
	v_lshl_add_u64 v[8:9], v[4:5], 0, v[68:69]
	v_add_co_u32_e32 v8, vcc, s3, v8
	ds_read_b128 v[4:7], v147 offset:5440
	s_nop 0
	v_addc_co_u32_e32 v9, vcc, 0, v9, vcc
	global_load_dwordx4 v[8:11], v[8:9], off
	v_ashrrev_i32_e32 v13, 31, v12
	s_waitcnt vmcnt(0) lgkmcnt(0)
	v_pk_mul_f32 v[4:5], v[4:5], v[8:9]
	v_pk_mul_f32 v[6:7], v[6:7], v[10:11]
	v_cvt_pk_bf16_f32 v4, v4, v5
	v_cvt_pk_bf16_f32 v5, v6, v7
	v_lshlrev_b64 v[6:7], 11, v[12:13]
	v_or_b32_e32 v12, v2, v125
	v_lshl_add_u64 v[6:7], s[4:5], 0, v[6:7]
	v_cmp_lt_i32_e32 vcc, s27, v12
	v_lshl_add_u64 v[6:7], v[6:7], 0, v[66:67]
	global_store_dwordx2 v[6:7], v[4:5], off
	v_cndmask_b32_e32 v98, 0, v3, vcc
	v_lshl_add_u64 v[4:5], v[98:99], 2, s[6:7]
	v_lshl_add_u64 v[8:9], v[4:5], 0, v[68:69]
	v_add_co_u32_e32 v8, vcc, s3, v8
	ds_read_b128 v[4:7], v147 offset:6528
	s_nop 0
	v_addc_co_u32_e32 v9, vcc, 0, v9, vcc
	global_load_dwordx4 v[8:11], v[8:9], off
	v_ashrrev_i32_e32 v13, 31, v12
	s_waitcnt vmcnt(0) lgkmcnt(0)
	v_pk_mul_f32 v[4:5], v[4:5], v[8:9]
	v_pk_mul_f32 v[6:7], v[6:7], v[10:11]
	v_or_b32_e32 v10, v2, v126
	v_cvt_pk_bf16_f32 v4, v4, v5
	v_cvt_pk_bf16_f32 v5, v6, v7
	v_lshlrev_b64 v[6:7], 11, v[12:13]
	v_cmp_lt_i32_e32 vcc, s27, v10
	v_lshl_add_u64 v[6:7], s[4:5], 0, v[6:7]
	v_lshl_add_u64 v[6:7], v[6:7], 0, v[66:67]
	v_cndmask_b32_e32 v98, 0, v3, vcc
	v_lshl_add_u64 v[2:3], v[98:99], 2, s[6:7]
	global_store_dwordx2 v[6:7], v[4:5], off
	v_lshl_add_u64 v[6:7], v[2:3], 0, v[68:69]
	v_add_co_u32_e32 v6, vcc, s3, v6
	ds_read_b128 v[2:5], v147 offset:7616
	s_nop 0
	v_addc_co_u32_e32 v7, vcc, 0, v7, vcc
	global_load_dwordx4 v[6:9], v[6:7], off
	v_ashrrev_i32_e32 v11, 31, v10
	s_waitcnt vmcnt(0) lgkmcnt(0)
	v_pk_mul_f32 v[2:3], v[2:3], v[6:7]
	v_pk_mul_f32 v[4:5], v[4:5], v[8:9]
	v_cvt_pk_bf16_f32 v2, v2, v3
	v_cvt_pk_bf16_f32 v3, v4, v5
	v_lshlrev_b64 v[4:5], 11, v[10:11]
	v_lshl_add_u64 v[4:5], s[4:5], 0, v[4:5]
	v_lshl_add_u64 v[4:5], v[4:5], 0, v[66:67]
	global_store_dwordx2 v[4:5], v[2:3], off
	s_waitcnt lgkmcnt(0)
	s_load_dword s10, s[8:9], 0x0
	s_waitcnt lgkmcnt(0)
	s_add_i32 s2, s10, s2
	s_cmpk_lt_i32 s2, 0x200
	s_cbranch_scc1 .LBB0_2331

	.amdhsa_kernel _Z4mega6Paramsii
		.amdhsa_group_segment_fixed_size 81920
		.amdhsa_private_segment_fixed_size 0
		.amdhsa_kernarg_size 1384
		.amdhsa_user_sgpr_count 2
		.amdhsa_user_sgpr_dispatch_ptr 0
		.amdhsa_user_sgpr_queue_ptr 0
		.amdhsa_user_sgpr_kernarg_segment_ptr 1
		.amdhsa_user_sgpr_dispatch_id 0
		.amdhsa_user_sgpr_kernarg_preload_length 0
		.amdhsa_user_sgpr_kernarg_preload_offset 0
		.amdhsa_user_sgpr_private_segment_size 0
		.amdhsa_uses_dynamic_stack 0
		.amdhsa_enable_private_segment 0
		.amdhsa_system_sgpr_workgroup_id_x 1
		.amdhsa_system_sgpr_workgroup_id_y 0
		.amdhsa_system_sgpr_workgroup_id_z 0
		.amdhsa_system_sgpr_workgroup_info 0
		.amdhsa_system_vgpr_workitem_id 2
		.amdhsa_next_free_vgpr 256
		.amdhsa_next_free_sgpr 98
		.amdhsa_accum_offset 256
		.amdhsa_reserve_vcc 1
		.amdhsa_float_round_mode_32 0
		.amdhsa_float_round_mode_16_64 0
		.amdhsa_float_denorm_mode_32 3
		.amdhsa_float_denorm_mode_16_64 3
		.amdhsa_dx10_clamp 1
		.amdhsa_ieee_mode 1
		.amdhsa_fp16_overflow 0
		.amdhsa_tg_split 0
		.amdhsa_exception_fp_ieee_invalid_op 0
		.amdhsa_exception_fp_denorm_src 0
		.amdhsa_exception_fp_ieee_div_zero 0
		.amdhsa_exception_fp_ieee_overflow 0
		.amdhsa_exception_fp_ieee_underflow 0
		.amdhsa_exception_fp_ieee_inexact 0
		.amdhsa_exception_int_div_zero 0
	.end_amdhsa_kernel

amdhsa.kernels:
  - .agpr_count:     0
    .args:
      - .offset:         0
        .size:           1120
        .value_kind:     by_value
      - .offset:         1120
        .size:           4
        .value_kind:     by_value
      - .offset:         1124
        .size:           4
        .value_kind:     by_value
      - .offset:         1128
        .size:           4
        .value_kind:     hidden_block_count_x
      - .offset:         1132
        .size:           4
        .value_kind:     hidden_block_count_y
      - .offset:         1136
        .size:           4
        .value_kind:     hidden_block_count_z
      - .offset:         1140
        .size:           2
        .value_kind:     hidden_group_size_x
      - .offset:         1142
        .size:           2
        .value_kind:     hidden_group_size_y
      - .offset:         1144
        .size:           2
        .value_kind:     hidden_group_size_z
      - .offset:         1146
        .size:           2
        .value_kind:     hidden_remainder_x
      - .offset:         1148
        .size:           2
        .value_kind:     hidden_remainder_y
      - .offset:         1150
        .size:           2
        .value_kind:     hidden_remainder_z
      - .offset:         1168
        .size:           8
        .value_kind:     hidden_global_offset_x
      - .offset:         1176
        .size:           8
        .value_kind:     hidden_global_offset_y
      - .offset:         1184
        .size:           8
        .value_kind:     hidden_global_offset_z
      - .offset:         1192
        .size:           2
        .value_kind:     hidden_grid_dims
      - .offset:         1216
        .size:           8
        .value_kind:     hidden_multigrid_sync_arg
    .group_segment_fixed_size: 81920
    .kernarg_segment_align: 8
    .kernarg_segment_size: 1384
    .language:       OpenCL C
    .language_version:
      - 2
      - 0
    .max_flat_workgroup_size: 256
    .name:           _Z4mega6Paramsii
    .private_segment_fixed_size: 0
    .sgpr_count:     104
    .sgpr_spill_count: 0
    .symbol:         _Z4mega6Paramsii.kd
    .uniform_work_group_size: 1
    .uses_dynamic_stack: false
    .vgpr_count:     256
    .vgpr_spill_count: 0
    .wavefront_size: 64
